# v12 + 24 wait states at the head of every L1 load segment (de-phase the loader's LDS read burst from the partner's MFMA segment head)
# baseline (speedup 1.0000x reference)
.LBB0_642:
	ds_read_b128 v[148:151], v139
	ds_read_b128 v[152:155], v139 offset:1024
	ds_read_b128 v[156:159], v139 offset:2048
	ds_read_b128 v[160:163], v139 offset:3072
	ds_read_b128 v[164:167], v140
	ds_read_b128 v[168:171], v140 offset:1024
	ds_read_b128 v[172:175], v140 offset:2048
	ds_read_b128 v[176:179], v140 offset:3072
	s_add_i32 s18, s71, 0xffe80080
	s_cmp_eq_u32 s58, s73
	s_cselect_b32 s74, s69, s18
	s_cselect_b32 s76, s70, s72
	s_or_b32 s75, s74, 0x80
	s_add_i32 s18, s71, 0xfff80000
	s_mov_b32 m0, s59
	ds_read_b128 v[180:183], v141
	ds_read_b128 v[184:187], v141 offset:1024
	ds_read_b128 v[188:191], v141 offset:2048
	ds_read_b128 v[192:195], v141 offset:3072
	ds_read_b128 v[196:199], v141 offset:4096
	ds_read_b128 v[200:203], v141 offset:5120
	ds_read_b128 v[204:207], v141 offset:6144
	ds_read_b128 v[208:211], v141 offset:7168
	buffer_load_dwordx4 v137, s[12:15], s18 offen lds
	s_mov_b32 m0, s60
	s_nop 0
	buffer_load_dwordx4 v137, s[12:15], s71 offen lds
	s_waitcnt vmcnt(8)
	s_waitcnt lgkmcnt(0)
	s_setprio 1
	v_mfma_f32_16x16x32_bf16 v[118:121], v[148:151], v[180:183], v[118:121]
	s_barrier
	v_mfma_f32_16x16x32_bf16 v[118:121], v[152:155], v[184:187], v[118:121]
	v_mfma_f32_16x16x32_bf16 v[114:117], v[156:159], v[180:183], v[114:117]
	v_mfma_f32_16x16x32_bf16 v[114:117], v[160:163], v[184:187], v[114:117]
	v_mfma_f32_16x16x32_bf16 v[126:129], v[164:167], v[180:183], v[126:129]
	v_mfma_f32_16x16x32_bf16 v[126:129], v[168:171], v[184:187], v[126:129]
	v_mfma_f32_16x16x32_bf16 v[122:125], v[172:175], v[180:183], v[122:125]
	v_mfma_f32_16x16x32_bf16 v[122:125], v[176:179], v[184:187], v[122:125]
	v_mfma_f32_16x16x32_bf16 v[98:101], v[172:175], v[188:191], v[98:101]
	v_mfma_f32_16x16x32_bf16 v[98:101], v[176:179], v[192:195], v[98:101]
	v_mfma_f32_16x16x32_bf16 v[106:109], v[164:167], v[188:191], v[106:109]
	v_mfma_f32_16x16x32_bf16 v[106:109], v[168:171], v[192:195], v[106:109]
	v_mfma_f32_16x16x32_bf16 v[102:105], v[156:159], v[188:191], v[102:105]
	v_mfma_f32_16x16x32_bf16 v[102:105], v[160:163], v[192:195], v[102:105]
	v_mfma_f32_16x16x32_bf16 v[110:113], v[148:151], v[188:191], v[110:113]
	v_mfma_f32_16x16x32_bf16 v[110:113], v[152:155], v[192:195], v[110:113]
	v_mfma_f32_16x16x32_bf16 v[94:97], v[148:151], v[196:199], v[94:97]
	v_mfma_f32_16x16x32_bf16 v[94:97], v[152:155], v[200:203], v[94:97]
	v_mfma_f32_16x16x32_bf16 v[86:89], v[156:159], v[196:199], v[86:89]
	v_mfma_f32_16x16x32_bf16 v[86:89], v[160:163], v[200:203], v[86:89]
	v_mfma_f32_16x16x32_bf16 v[90:93], v[164:167], v[196:199], v[90:93]
	v_mfma_f32_16x16x32_bf16 v[90:93], v[168:171], v[200:203], v[90:93]
	v_mfma_f32_16x16x32_bf16 v[82:85], v[172:175], v[196:199], v[82:85]
	v_mfma_f32_16x16x32_bf16 v[82:85], v[176:179], v[200:203], v[82:85]
	v_mfma_f32_16x16x32_bf16 v[70:73], v[172:175], v[204:207], v[70:73]
	v_mfma_f32_16x16x32_bf16 v[70:73], v[176:179], v[208:211], v[70:73]
	v_mfma_f32_16x16x32_bf16 v[74:77], v[164:167], v[204:207], v[74:77]
	v_mfma_f32_16x16x32_bf16 v[74:77], v[168:171], v[208:211], v[74:77]
	v_mfma_f32_16x16x32_bf16 v[66:69], v[156:159], v[204:207], v[66:69]
	v_mfma_f32_16x16x32_bf16 v[66:69], v[160:163], v[208:211], v[66:69]
	v_mfma_f32_16x16x32_bf16 v[78:81], v[148:151], v[204:207], v[78:81]
	v_mfma_f32_16x16x32_bf16 v[78:81], v[152:155], v[208:211], v[78:81]
	s_setprio 0
	s_barrier
	s_mov_b32 m0, s30
	s_mov_b32 s18, s14
	s_mov_b32 s19, s15
	ds_read_b128 v[180:183], v141 offset:16384
	ds_read_b128 v[184:187], v141 offset:17408
	ds_read_b128 v[188:191], v141 offset:18432
	ds_read_b128 v[192:195], v141 offset:19456
	ds_read_b128 v[196:199], v141 offset:20480
	ds_read_b128 v[200:203], v141 offset:21504
	ds_read_b128 v[204:207], v141 offset:22528
	ds_read_b128 v[208:211], v141 offset:23552
	buffer_load_dwordx4 v138, s[16:19], s76 offen lds
	s_add_i32 s77, s76, 0x80000
	s_mov_b32 m0, s31
	s_nop 0
	buffer_load_dwordx4 v138, s[16:19], s77 offen lds
	s_add_i32 s77, s76, 0x100000
	s_mov_b32 m0, s44
	s_nop 0
	buffer_load_dwordx4 v138, s[16:19], s77 offen lds
	s_add_i32 s77, s76, 0x180000
	s_mov_b32 m0, s45
	s_nop 0
	buffer_load_dwordx4 v138, s[16:19], s77 offen lds
	s_mov_b32 m0, s27
	s_add_i32 s77, s74, 0x80000
	buffer_load_dwordx4 v137, s[12:15], s74 offen lds
	s_mov_b32 m0, s46
	s_nop 0
	buffer_load_dwordx4 v137, s[12:15], s77 offen lds
	s_waitcnt vmcnt(8)
	s_waitcnt lgkmcnt(0)
	s_setprio 1
	v_mfma_f32_16x16x32_bf16 v[62:65], v[148:151], v[180:183], v[62:65]
	s_barrier
	v_mfma_f32_16x16x32_bf16 v[62:65], v[152:155], v[184:187], v[62:65]
	v_mfma_f32_16x16x32_bf16 v[54:57], v[156:159], v[180:183], v[54:57]
	v_mfma_f32_16x16x32_bf16 v[54:57], v[160:163], v[184:187], v[54:57]
	v_mfma_f32_16x16x32_bf16 v[58:61], v[164:167], v[180:183], v[58:61]
	v_mfma_f32_16x16x32_bf16 v[58:61], v[168:171], v[184:187], v[58:61]
	v_mfma_f32_16x16x32_bf16 v[50:53], v[172:175], v[180:183], v[50:53]
	v_mfma_f32_16x16x32_bf16 v[50:53], v[176:179], v[184:187], v[50:53]
	v_mfma_f32_16x16x32_bf16 v[34:37], v[172:175], v[188:191], v[34:37]
	v_mfma_f32_16x16x32_bf16 v[34:37], v[176:179], v[192:195], v[34:37]
	v_mfma_f32_16x16x32_bf16 v[42:45], v[164:167], v[188:191], v[42:45]
	v_mfma_f32_16x16x32_bf16 v[42:45], v[168:171], v[192:195], v[42:45]
	v_mfma_f32_16x16x32_bf16 v[38:41], v[156:159], v[188:191], v[38:41]
	v_mfma_f32_16x16x32_bf16 v[38:41], v[160:163], v[192:195], v[38:41]
	v_mfma_f32_16x16x32_bf16 v[46:49], v[148:151], v[188:191], v[46:49]
	v_mfma_f32_16x16x32_bf16 v[46:49], v[152:155], v[192:195], v[46:49]
	v_mfma_f32_16x16x32_bf16 v[30:33], v[148:151], v[196:199], v[30:33]
	v_mfma_f32_16x16x32_bf16 v[30:33], v[152:155], v[200:203], v[30:33]
	v_mfma_f32_16x16x32_bf16 v[22:25], v[156:159], v[196:199], v[22:25]
	v_mfma_f32_16x16x32_bf16 v[22:25], v[160:163], v[200:203], v[22:25]
	v_mfma_f32_16x16x32_bf16 v[26:29], v[164:167], v[196:199], v[26:29]
	v_mfma_f32_16x16x32_bf16 v[26:29], v[168:171], v[200:203], v[26:29]
	v_mfma_f32_16x16x32_bf16 v[18:21], v[172:175], v[196:199], v[18:21]
	v_mfma_f32_16x16x32_bf16 v[18:21], v[176:179], v[200:203], v[18:21]
	v_mfma_f32_16x16x32_bf16 v[2:5], v[172:175], v[204:207], v[2:5]
	v_mfma_f32_16x16x32_bf16 v[2:5], v[176:179], v[208:211], v[2:5]
	v_mfma_f32_16x16x32_bf16 v[10:13], v[164:167], v[204:207], v[10:13]
	v_mfma_f32_16x16x32_bf16 v[10:13], v[168:171], v[208:211], v[10:13]
	v_mfma_f32_16x16x32_bf16 v[6:9], v[156:159], v[204:207], v[6:9]
	v_mfma_f32_16x16x32_bf16 v[6:9], v[160:163], v[208:211], v[6:9]
	v_mfma_f32_16x16x32_bf16 v[14:17], v[148:151], v[204:207], v[14:17]
	v_mfma_f32_16x16x32_bf16 v[14:17], v[152:155], v[208:211], v[14:17]
	s_setprio 0
	s_barrier
	s_nop 7
	s_nop 7
	s_nop 7
	ds_read_b128 v[148:151], v142
	ds_read_b128 v[152:155], v142 offset:1024
	ds_read_b128 v[156:159], v142 offset:2048
	ds_read_b128 v[160:163], v142 offset:3072
	ds_read_b128 v[164:167], v143
	ds_read_b128 v[168:171], v143 offset:1024
	ds_read_b128 v[172:175], v143 offset:2048
	ds_read_b128 v[176:179], v143 offset:3072
	s_mov_b32 m0, s47
	s_add_i32 s77, s74, 0x100000
	ds_read_b128 v[180:183], v141 offset:32768
	ds_read_b128 v[184:187], v141 offset:33792
	ds_read_b128 v[188:191], v141 offset:34816
	ds_read_b128 v[192:195], v141 offset:35840
	ds_read_b128 v[196:199], v141 offset:36864
	ds_read_b128 v[200:203], v141 offset:37888
	ds_read_b128 v[204:207], v141 offset:38912
	ds_read_b128 v[208:211], v141 offset:39936
	buffer_load_dwordx4 v137, s[12:15], s77 offen lds
	s_add_i32 s77, s74, 0x180000
	s_mov_b32 m0, s48
	s_nop 0
	buffer_load_dwordx4 v137, s[12:15], s77 offen lds
	s_waitcnt vmcnt(8)
	s_waitcnt lgkmcnt(0)
	s_setprio 1
	v_mfma_f32_16x16x32_bf16 v[118:121], v[148:151], v[180:183], v[118:121]
	s_barrier
	v_mfma_f32_16x16x32_bf16 v[118:121], v[152:155], v[184:187], v[118:121]
	v_mfma_f32_16x16x32_bf16 v[114:117], v[156:159], v[180:183], v[114:117]
	v_mfma_f32_16x16x32_bf16 v[114:117], v[160:163], v[184:187], v[114:117]
	v_mfma_f32_16x16x32_bf16 v[126:129], v[164:167], v[180:183], v[126:129]
	v_mfma_f32_16x16x32_bf16 v[126:129], v[168:171], v[184:187], v[126:129]
	v_mfma_f32_16x16x32_bf16 v[122:125], v[172:175], v[180:183], v[122:125]
	v_mfma_f32_16x16x32_bf16 v[122:125], v[176:179], v[184:187], v[122:125]
	v_mfma_f32_16x16x32_bf16 v[98:101], v[172:175], v[188:191], v[98:101]
	v_mfma_f32_16x16x32_bf16 v[98:101], v[176:179], v[192:195], v[98:101]
	v_mfma_f32_16x16x32_bf16 v[106:109], v[164:167], v[188:191], v[106:109]
	v_mfma_f32_16x16x32_bf16 v[106:109], v[168:171], v[192:195], v[106:109]
	v_mfma_f32_16x16x32_bf16 v[102:105], v[156:159], v[188:191], v[102:105]
	v_mfma_f32_16x16x32_bf16 v[102:105], v[160:163], v[192:195], v[102:105]
	v_mfma_f32_16x16x32_bf16 v[110:113], v[148:151], v[188:191], v[110:113]
	v_mfma_f32_16x16x32_bf16 v[110:113], v[152:155], v[192:195], v[110:113]
	v_mfma_f32_16x16x32_bf16 v[94:97], v[148:151], v[196:199], v[94:97]
	v_mfma_f32_16x16x32_bf16 v[94:97], v[152:155], v[200:203], v[94:97]
	v_mfma_f32_16x16x32_bf16 v[86:89], v[156:159], v[196:199], v[86:89]
	v_mfma_f32_16x16x32_bf16 v[86:89], v[160:163], v[200:203], v[86:89]
	v_mfma_f32_16x16x32_bf16 v[90:93], v[164:167], v[196:199], v[90:93]
	v_mfma_f32_16x16x32_bf16 v[90:93], v[168:171], v[200:203], v[90:93]
	v_mfma_f32_16x16x32_bf16 v[82:85], v[172:175], v[196:199], v[82:85]
	v_mfma_f32_16x16x32_bf16 v[82:85], v[176:179], v[200:203], v[82:85]
	v_mfma_f32_16x16x32_bf16 v[70:73], v[172:175], v[204:207], v[70:73]
	v_mfma_f32_16x16x32_bf16 v[70:73], v[176:179], v[208:211], v[70:73]
	v_mfma_f32_16x16x32_bf16 v[74:77], v[164:167], v[204:207], v[74:77]
	v_mfma_f32_16x16x32_bf16 v[74:77], v[168:171], v[208:211], v[74:77]
	v_mfma_f32_16x16x32_bf16 v[66:69], v[156:159], v[204:207], v[66:69]
	v_mfma_f32_16x16x32_bf16 v[66:69], v[160:163], v[208:211], v[66:69]
	v_mfma_f32_16x16x32_bf16 v[78:81], v[148:151], v[204:207], v[78:81]
	v_mfma_f32_16x16x32_bf16 v[78:81], v[152:155], v[208:211], v[78:81]
	s_setprio 0
	s_barrier
	s_mov_b32 m0, s50
	s_or_b32 s77, s76, 0x80
	ds_read_b128 v[180:183], v141 offset:49152
	ds_read_b128 v[184:187], v141 offset:50176
	ds_read_b128 v[188:191], v141 offset:51200
	ds_read_b128 v[192:195], v141 offset:52224
	ds_read_b128 v[196:199], v141 offset:53248
	ds_read_b128 v[200:203], v141 offset:54272
	ds_read_b128 v[204:207], v141 offset:55296
	ds_read_b128 v[208:211], v141 offset:56320
	buffer_load_dwordx4 v138, s[16:19], s77 offen lds
	s_add_i32 s77, s76, 0x80080
	s_mov_b32 m0, s51
	s_add_i32 s74, s74, 0x80080
	buffer_load_dwordx4 v138, s[16:19], s77 offen lds
	s_add_i32 s77, s76, 0x100080
	s_mov_b32 m0, s54
	s_add_i32 s76, s76, 0x180080
	buffer_load_dwordx4 v138, s[16:19], s77 offen lds
	s_mov_b32 m0, s55
	s_nop 0
	buffer_load_dwordx4 v138, s[16:19], s76 offen lds
	s_mov_b32 m0, s52
	s_nop 0
	buffer_load_dwordx4 v137, s[12:15], s75 offen lds
	s_mov_b32 m0, s53
	s_nop 0
	buffer_load_dwordx4 v137, s[12:15], s74 offen lds
	s_waitcnt vmcnt(8)
	s_waitcnt lgkmcnt(0)
	s_setprio 1
	v_mfma_f32_16x16x32_bf16 v[62:65], v[148:151], v[180:183], v[62:65]
	s_barrier
	v_mfma_f32_16x16x32_bf16 v[62:65], v[152:155], v[184:187], v[62:65]
	v_mfma_f32_16x16x32_bf16 v[54:57], v[156:159], v[180:183], v[54:57]
	v_mfma_f32_16x16x32_bf16 v[54:57], v[160:163], v[184:187], v[54:57]
	v_mfma_f32_16x16x32_bf16 v[58:61], v[164:167], v[180:183], v[58:61]
	v_mfma_f32_16x16x32_bf16 v[58:61], v[168:171], v[184:187], v[58:61]
	v_mfma_f32_16x16x32_bf16 v[50:53], v[172:175], v[180:183], v[50:53]
	v_mfma_f32_16x16x32_bf16 v[50:53], v[176:179], v[184:187], v[50:53]
	v_mfma_f32_16x16x32_bf16 v[34:37], v[172:175], v[188:191], v[34:37]
	v_mfma_f32_16x16x32_bf16 v[34:37], v[176:179], v[192:195], v[34:37]
	v_mfma_f32_16x16x32_bf16 v[42:45], v[164:167], v[188:191], v[42:45]
	v_mfma_f32_16x16x32_bf16 v[42:45], v[168:171], v[192:195], v[42:45]
	v_mfma_f32_16x16x32_bf16 v[38:41], v[156:159], v[188:191], v[38:41]
	v_mfma_f32_16x16x32_bf16 v[38:41], v[160:163], v[192:195], v[38:41]
	v_mfma_f32_16x16x32_bf16 v[46:49], v[148:151], v[188:191], v[46:49]
	v_mfma_f32_16x16x32_bf16 v[46:49], v[152:155], v[192:195], v[46:49]
	v_mfma_f32_16x16x32_bf16 v[30:33], v[148:151], v[196:199], v[30:33]
	v_mfma_f32_16x16x32_bf16 v[30:33], v[152:155], v[200:203], v[30:33]
	v_mfma_f32_16x16x32_bf16 v[22:25], v[156:159], v[196:199], v[22:25]
	v_mfma_f32_16x16x32_bf16 v[22:25], v[160:163], v[200:203], v[22:25]
	v_mfma_f32_16x16x32_bf16 v[26:29], v[164:167], v[196:199], v[26:29]
	v_mfma_f32_16x16x32_bf16 v[26:29], v[168:171], v[200:203], v[26:29]
	v_mfma_f32_16x16x32_bf16 v[18:21], v[172:175], v[196:199], v[18:21]
	v_mfma_f32_16x16x32_bf16 v[18:21], v[176:179], v[200:203], v[18:21]
	v_mfma_f32_16x16x32_bf16 v[2:5], v[172:175], v[204:207], v[2:5]
	v_mfma_f32_16x16x32_bf16 v[2:5], v[176:179], v[208:211], v[2:5]
	v_mfma_f32_16x16x32_bf16 v[10:13], v[164:167], v[204:207], v[10:13]
	v_mfma_f32_16x16x32_bf16 v[10:13], v[168:171], v[208:211], v[10:13]
	v_mfma_f32_16x16x32_bf16 v[6:9], v[156:159], v[204:207], v[6:9]
	v_mfma_f32_16x16x32_bf16 v[6:9], v[160:163], v[208:211], v[6:9]
	v_mfma_f32_16x16x32_bf16 v[14:17], v[148:151], v[204:207], v[14:17]
	v_mfma_f32_16x16x32_bf16 v[14:17], v[152:155], v[208:211], v[14:17]
	s_setprio 0
	s_barrier
	s_nop 7
	s_nop 7
	s_nop 7
	s_add_i32 s73, s73, 2
	s_addk_i32 s71, 0x100
	s_addk_i32 s72, 0x100
	s_cmp_ge_i32 s73, s3
	s_cbranch_scc0 .LBB0_642
	s_and_b64 vcc, exec, s[42:43]
	s_cbranch_vccz .LBB0_645

.LBB0_799:
	ds_read_b128 v[134:137], v210
	ds_read_b128 v[138:141], v210 offset:1024
	ds_read_b128 v[142:145], v210 offset:2048
	ds_read_b128 v[148:151], v210 offset:3072
	ds_read_b128 v[152:155], v211
	ds_read_b128 v[156:159], v211 offset:1024
	ds_read_b128 v[160:163], v211 offset:2048
	ds_read_b128 v[164:167], v211 offset:3072
	s_add_i32 s18, s77, 0xffbf8080
	s_cmp_eq_u32 s62, s79
	s_cselect_b32 s80, s6, s18
	s_cselect_b32 s82, s7, s78
	s_or_b32 s81, s80, 0x80
	s_add_i32 s18, s77, 0xffea8000
	s_mov_b32 m0, s63
	ds_read_b128 v[168:171], v212
	ds_read_b128 v[172:175], v212 offset:1024
	ds_read_b128 v[176:179], v212 offset:2048
	ds_read_b128 v[180:183], v212 offset:3072
	ds_read_b128 v[184:187], v212 offset:4096
	ds_read_b128 v[188:191], v212 offset:5120
	ds_read_b128 v[192:195], v212 offset:6144
	ds_read_b128 v[196:199], v212 offset:7168
	buffer_load_dwordx4 v208, s[12:15], s18 offen lds
	s_mov_b32 m0, s66
	s_nop 0
	buffer_load_dwordx4 v208, s[12:15], s77 offen lds
	s_waitcnt vmcnt(8)
	s_waitcnt lgkmcnt(0)
	s_setprio 1
	v_mfma_f32_16x16x32_bf16 v[126:129], v[134:137], v[168:171], v[126:129]
	s_barrier
	v_mfma_f32_16x16x32_bf16 v[126:129], v[138:141], v[172:175], v[126:129]
	v_mfma_f32_16x16x32_bf16 v[122:125], v[142:145], v[168:171], v[122:125]
	v_mfma_f32_16x16x32_bf16 v[122:125], v[148:151], v[172:175], v[122:125]
	v_mfma_f32_16x16x32_bf16 v[110:113], v[152:155], v[168:171], v[110:113]
	v_mfma_f32_16x16x32_bf16 v[110:113], v[156:159], v[172:175], v[110:113]
	v_mfma_f32_16x16x32_bf16 v[102:105], v[160:163], v[168:171], v[102:105]
	v_mfma_f32_16x16x32_bf16 v[102:105], v[164:167], v[172:175], v[102:105]
	v_mfma_f32_16x16x32_bf16 v[86:89], v[160:163], v[176:179], v[86:89]
	v_mfma_f32_16x16x32_bf16 v[86:89], v[164:167], v[180:183], v[86:89]
	v_mfma_f32_16x16x32_bf16 v[94:97], v[152:155], v[176:179], v[94:97]
	v_mfma_f32_16x16x32_bf16 v[94:97], v[156:159], v[180:183], v[94:97]
	v_mfma_f32_16x16x32_bf16 v[114:117], v[142:145], v[176:179], v[114:117]
	v_mfma_f32_16x16x32_bf16 v[114:117], v[148:151], v[180:183], v[114:117]
	v_mfma_f32_16x16x32_bf16 v[118:121], v[134:137], v[176:179], v[118:121]
	v_mfma_f32_16x16x32_bf16 v[118:121], v[138:141], v[180:183], v[118:121]
	v_mfma_f32_16x16x32_bf16 v[106:109], v[134:137], v[184:187], v[106:109]
	v_mfma_f32_16x16x32_bf16 v[106:109], v[138:141], v[188:191], v[106:109]
	v_mfma_f32_16x16x32_bf16 v[98:101], v[142:145], v[184:187], v[98:101]
	v_mfma_f32_16x16x32_bf16 v[98:101], v[148:151], v[188:191], v[98:101]
	v_mfma_f32_16x16x32_bf16 v[78:81], v[152:155], v[184:187], v[78:81]
	v_mfma_f32_16x16x32_bf16 v[78:81], v[156:159], v[188:191], v[78:81]
	v_mfma_f32_16x16x32_bf16 v[74:77], v[160:163], v[184:187], v[74:77]
	v_mfma_f32_16x16x32_bf16 v[74:77], v[164:167], v[188:191], v[74:77]
	v_mfma_f32_16x16x32_bf16 v[66:69], v[160:163], v[192:195], v[66:69]
	v_mfma_f32_16x16x32_bf16 v[66:69], v[164:167], v[196:199], v[66:69]
	v_mfma_f32_16x16x32_bf16 v[70:73], v[152:155], v[192:195], v[70:73]
	v_mfma_f32_16x16x32_bf16 v[70:73], v[156:159], v[196:199], v[70:73]
	v_mfma_f32_16x16x32_bf16 v[82:85], v[142:145], v[192:195], v[82:85]
	v_mfma_f32_16x16x32_bf16 v[82:85], v[148:151], v[196:199], v[82:85]
	v_mfma_f32_16x16x32_bf16 v[90:93], v[134:137], v[192:195], v[90:93]
	v_mfma_f32_16x16x32_bf16 v[90:93], v[138:141], v[196:199], v[90:93]
	s_setprio 0
	s_barrier
	s_mov_b32 m0, s25
	s_mov_b32 s18, s14
	s_mov_b32 s19, s15
	ds_read_b128 v[168:171], v212 offset:16384
	ds_read_b128 v[172:175], v212 offset:17408
	ds_read_b128 v[176:179], v212 offset:18432
	ds_read_b128 v[180:183], v212 offset:19456
	ds_read_b128 v[184:187], v212 offset:20480
	ds_read_b128 v[188:191], v212 offset:21504
	ds_read_b128 v[192:195], v212 offset:22528
	ds_read_b128 v[196:199], v212 offset:23552
	buffer_load_dwordx4 v209, s[16:19], s82 offen lds
	s_add_i32 s83, s82, 0x158000
	s_mov_b32 m0, s27
	s_nop 0
	buffer_load_dwordx4 v209, s[16:19], s83 offen lds
	s_add_i32 s83, s82, 0x2b0000
	s_mov_b32 m0, s30
	s_nop 0
	buffer_load_dwordx4 v209, s[16:19], s83 offen lds
	s_add_i32 s83, s82, 0x408000
	s_mov_b32 m0, s31
	s_nop 0
	buffer_load_dwordx4 v209, s[16:19], s83 offen lds
	s_mov_b32 m0, s21
	s_add_i32 s83, s80, 0x158000
	buffer_load_dwordx4 v208, s[12:15], s80 offen lds
	s_mov_b32 m0, s48
	s_nop 0
	buffer_load_dwordx4 v208, s[12:15], s83 offen lds
	s_waitcnt vmcnt(8)
	s_waitcnt lgkmcnt(0)
	s_setprio 1
	v_mfma_f32_16x16x32_bf16 v[62:65], v[134:137], v[168:171], v[62:65]
	s_barrier
	v_mfma_f32_16x16x32_bf16 v[62:65], v[138:141], v[172:175], v[62:65]
	v_mfma_f32_16x16x32_bf16 v[58:61], v[142:145], v[168:171], v[58:61]
	v_mfma_f32_16x16x32_bf16 v[58:61], v[148:151], v[172:175], v[58:61]
	v_mfma_f32_16x16x32_bf16 v[46:49], v[152:155], v[168:171], v[46:49]
	v_mfma_f32_16x16x32_bf16 v[46:49], v[156:159], v[172:175], v[46:49]
	v_mfma_f32_16x16x32_bf16 v[38:41], v[160:163], v[168:171], v[38:41]
	v_mfma_f32_16x16x32_bf16 v[38:41], v[164:167], v[172:175], v[38:41]
	v_mfma_f32_16x16x32_bf16 v[22:25], v[160:163], v[176:179], v[22:25]
	v_mfma_f32_16x16x32_bf16 v[22:25], v[164:167], v[180:183], v[22:25]
	v_mfma_f32_16x16x32_bf16 v[30:33], v[152:155], v[176:179], v[30:33]
	v_mfma_f32_16x16x32_bf16 v[30:33], v[156:159], v[180:183], v[30:33]
	v_mfma_f32_16x16x32_bf16 v[50:53], v[142:145], v[176:179], v[50:53]
	v_mfma_f32_16x16x32_bf16 v[50:53], v[148:151], v[180:183], v[50:53]
	v_mfma_f32_16x16x32_bf16 v[54:57], v[134:137], v[176:179], v[54:57]
	v_mfma_f32_16x16x32_bf16 v[54:57], v[138:141], v[180:183], v[54:57]
	v_mfma_f32_16x16x32_bf16 v[42:45], v[134:137], v[184:187], v[42:45]
	v_mfma_f32_16x16x32_bf16 v[42:45], v[138:141], v[188:191], v[42:45]
	v_mfma_f32_16x16x32_bf16 v[34:37], v[142:145], v[184:187], v[34:37]
	v_mfma_f32_16x16x32_bf16 v[34:37], v[148:151], v[188:191], v[34:37]
	v_mfma_f32_16x16x32_bf16 v[14:17], v[152:155], v[184:187], v[14:17]
	v_mfma_f32_16x16x32_bf16 v[14:17], v[156:159], v[188:191], v[14:17]
	v_mfma_f32_16x16x32_bf16 v[10:13], v[160:163], v[184:187], v[10:13]
	v_mfma_f32_16x16x32_bf16 v[10:13], v[164:167], v[188:191], v[10:13]
	v_mfma_f32_16x16x32_bf16 v[2:5], v[160:163], v[192:195], v[2:5]
	v_mfma_f32_16x16x32_bf16 v[2:5], v[164:167], v[196:199], v[2:5]
	v_mfma_f32_16x16x32_bf16 v[6:9], v[152:155], v[192:195], v[6:9]
	v_mfma_f32_16x16x32_bf16 v[6:9], v[156:159], v[196:199], v[6:9]
	v_mfma_f32_16x16x32_bf16 v[18:21], v[142:145], v[192:195], v[18:21]
	v_mfma_f32_16x16x32_bf16 v[18:21], v[148:151], v[196:199], v[18:21]
	v_mfma_f32_16x16x32_bf16 v[26:29], v[134:137], v[192:195], v[26:29]
	v_mfma_f32_16x16x32_bf16 v[26:29], v[138:141], v[196:199], v[26:29]
	s_setprio 0
	s_barrier
	s_nop 7
	s_nop 7
	s_nop 7
	ds_read_b128 v[134:137], v213
	ds_read_b128 v[138:141], v213 offset:1024
	ds_read_b128 v[142:145], v213 offset:2048
	ds_read_b128 v[148:151], v213 offset:3072
	ds_read_b128 v[152:155], v214
	ds_read_b128 v[156:159], v214 offset:1024
	ds_read_b128 v[160:163], v214 offset:2048
	ds_read_b128 v[164:167], v214 offset:3072
	s_mov_b32 m0, s49
	s_add_i32 s83, s80, 0x2b0000
	ds_read_b128 v[168:171], v212 offset:32768
	ds_read_b128 v[172:175], v212 offset:33792
	ds_read_b128 v[176:179], v212 offset:34816
	ds_read_b128 v[180:183], v212 offset:35840
	ds_read_b128 v[184:187], v212 offset:36864
	ds_read_b128 v[188:191], v212 offset:37888
	ds_read_b128 v[192:195], v212 offset:38912
	ds_read_b128 v[196:199], v212 offset:39936
	buffer_load_dwordx4 v208, s[12:15], s83 offen lds
	s_add_i32 s83, s80, 0x408000
	s_mov_b32 m0, s50
	s_nop 0
	buffer_load_dwordx4 v208, s[12:15], s83 offen lds
	s_waitcnt vmcnt(8)
	s_waitcnt lgkmcnt(0)
	s_setprio 1
	v_mfma_f32_16x16x32_bf16 v[126:129], v[134:137], v[168:171], v[126:129]
	s_barrier
	v_mfma_f32_16x16x32_bf16 v[126:129], v[138:141], v[172:175], v[126:129]
	v_mfma_f32_16x16x32_bf16 v[122:125], v[142:145], v[168:171], v[122:125]
	v_mfma_f32_16x16x32_bf16 v[122:125], v[148:151], v[172:175], v[122:125]
	v_mfma_f32_16x16x32_bf16 v[110:113], v[152:155], v[168:171], v[110:113]
	v_mfma_f32_16x16x32_bf16 v[110:113], v[156:159], v[172:175], v[110:113]
	v_mfma_f32_16x16x32_bf16 v[102:105], v[160:163], v[168:171], v[102:105]
	v_mfma_f32_16x16x32_bf16 v[102:105], v[164:167], v[172:175], v[102:105]
	v_mfma_f32_16x16x32_bf16 v[86:89], v[160:163], v[176:179], v[86:89]
	v_mfma_f32_16x16x32_bf16 v[86:89], v[164:167], v[180:183], v[86:89]
	v_mfma_f32_16x16x32_bf16 v[94:97], v[152:155], v[176:179], v[94:97]
	v_mfma_f32_16x16x32_bf16 v[94:97], v[156:159], v[180:183], v[94:97]
	v_mfma_f32_16x16x32_bf16 v[114:117], v[142:145], v[176:179], v[114:117]
	v_mfma_f32_16x16x32_bf16 v[114:117], v[148:151], v[180:183], v[114:117]
	v_mfma_f32_16x16x32_bf16 v[118:121], v[134:137], v[176:179], v[118:121]
	v_mfma_f32_16x16x32_bf16 v[118:121], v[138:141], v[180:183], v[118:121]
	v_mfma_f32_16x16x32_bf16 v[106:109], v[134:137], v[184:187], v[106:109]
	v_mfma_f32_16x16x32_bf16 v[106:109], v[138:141], v[188:191], v[106:109]
	v_mfma_f32_16x16x32_bf16 v[98:101], v[142:145], v[184:187], v[98:101]
	v_mfma_f32_16x16x32_bf16 v[98:101], v[148:151], v[188:191], v[98:101]
	v_mfma_f32_16x16x32_bf16 v[78:81], v[152:155], v[184:187], v[78:81]
	v_mfma_f32_16x16x32_bf16 v[78:81], v[156:159], v[188:191], v[78:81]
	v_mfma_f32_16x16x32_bf16 v[74:77], v[160:163], v[184:187], v[74:77]
	v_mfma_f32_16x16x32_bf16 v[74:77], v[164:167], v[188:191], v[74:77]
	v_mfma_f32_16x16x32_bf16 v[66:69], v[160:163], v[192:195], v[66:69]
	v_mfma_f32_16x16x32_bf16 v[66:69], v[164:167], v[196:199], v[66:69]
	v_mfma_f32_16x16x32_bf16 v[70:73], v[152:155], v[192:195], v[70:73]
	v_mfma_f32_16x16x32_bf16 v[70:73], v[156:159], v[196:199], v[70:73]
	v_mfma_f32_16x16x32_bf16 v[82:85], v[142:145], v[192:195], v[82:85]
	v_mfma_f32_16x16x32_bf16 v[82:85], v[148:151], v[196:199], v[82:85]
	v_mfma_f32_16x16x32_bf16 v[90:93], v[134:137], v[192:195], v[90:93]
	v_mfma_f32_16x16x32_bf16 v[90:93], v[138:141], v[196:199], v[90:93]
	s_setprio 0
	s_barrier
	s_mov_b32 m0, s54
	s_or_b32 s83, s82, 0x80
	ds_read_b128 v[168:171], v212 offset:49152
	ds_read_b128 v[172:175], v212 offset:50176
	ds_read_b128 v[176:179], v212 offset:51200
	ds_read_b128 v[180:183], v212 offset:52224
	ds_read_b128 v[184:187], v212 offset:53248
	ds_read_b128 v[188:191], v212 offset:54272
	ds_read_b128 v[192:195], v212 offset:55296
	ds_read_b128 v[196:199], v212 offset:56320
	buffer_load_dwordx4 v209, s[16:19], s83 offen lds
	s_add_i32 s83, s82, 0x158080
	s_mov_b32 m0, s55
	s_add_i32 s80, s80, 0x158080
	buffer_load_dwordx4 v209, s[16:19], s83 offen lds
	s_add_i32 s83, s82, 0x2b0080
	s_mov_b32 m0, s58
	s_add_i32 s82, s82, 0x408080
	buffer_load_dwordx4 v209, s[16:19], s83 offen lds
	s_mov_b32 m0, s59
	s_nop 0
	buffer_load_dwordx4 v209, s[16:19], s82 offen lds
	s_mov_b32 m0, s56
	s_nop 0
	buffer_load_dwordx4 v208, s[12:15], s81 offen lds
	s_mov_b32 m0, s57
	s_nop 0
	buffer_load_dwordx4 v208, s[12:15], s80 offen lds
	s_waitcnt vmcnt(8)
	s_waitcnt lgkmcnt(0)
	s_setprio 1
	v_mfma_f32_16x16x32_bf16 v[62:65], v[134:137], v[168:171], v[62:65]
	s_barrier
	v_mfma_f32_16x16x32_bf16 v[62:65], v[138:141], v[172:175], v[62:65]
	v_mfma_f32_16x16x32_bf16 v[58:61], v[142:145], v[168:171], v[58:61]
	v_mfma_f32_16x16x32_bf16 v[58:61], v[148:151], v[172:175], v[58:61]
	v_mfma_f32_16x16x32_bf16 v[46:49], v[152:155], v[168:171], v[46:49]
	v_mfma_f32_16x16x32_bf16 v[46:49], v[156:159], v[172:175], v[46:49]
	v_mfma_f32_16x16x32_bf16 v[38:41], v[160:163], v[168:171], v[38:41]
	v_mfma_f32_16x16x32_bf16 v[38:41], v[164:167], v[172:175], v[38:41]
	v_mfma_f32_16x16x32_bf16 v[22:25], v[160:163], v[176:179], v[22:25]
	v_mfma_f32_16x16x32_bf16 v[22:25], v[164:167], v[180:183], v[22:25]
	v_mfma_f32_16x16x32_bf16 v[30:33], v[152:155], v[176:179], v[30:33]
	v_mfma_f32_16x16x32_bf16 v[30:33], v[156:159], v[180:183], v[30:33]
	v_mfma_f32_16x16x32_bf16 v[50:53], v[142:145], v[176:179], v[50:53]
	v_mfma_f32_16x16x32_bf16 v[50:53], v[148:151], v[180:183], v[50:53]
	v_mfma_f32_16x16x32_bf16 v[54:57], v[134:137], v[176:179], v[54:57]
	v_mfma_f32_16x16x32_bf16 v[54:57], v[138:141], v[180:183], v[54:57]
	v_mfma_f32_16x16x32_bf16 v[42:45], v[134:137], v[184:187], v[42:45]
	v_mfma_f32_16x16x32_bf16 v[42:45], v[138:141], v[188:191], v[42:45]
	v_mfma_f32_16x16x32_bf16 v[34:37], v[142:145], v[184:187], v[34:37]
	v_mfma_f32_16x16x32_bf16 v[34:37], v[148:151], v[188:191], v[34:37]
	v_mfma_f32_16x16x32_bf16 v[14:17], v[152:155], v[184:187], v[14:17]
	v_mfma_f32_16x16x32_bf16 v[14:17], v[156:159], v[188:191], v[14:17]
	v_mfma_f32_16x16x32_bf16 v[10:13], v[160:163], v[184:187], v[10:13]
	v_mfma_f32_16x16x32_bf16 v[10:13], v[164:167], v[188:191], v[10:13]
	v_mfma_f32_16x16x32_bf16 v[2:5], v[160:163], v[192:195], v[2:5]
	v_mfma_f32_16x16x32_bf16 v[2:5], v[164:167], v[196:199], v[2:5]
	v_mfma_f32_16x16x32_bf16 v[6:9], v[152:155], v[192:195], v[6:9]
	v_mfma_f32_16x16x32_bf16 v[6:9], v[156:159], v[196:199], v[6:9]
	v_mfma_f32_16x16x32_bf16 v[18:21], v[142:145], v[192:195], v[18:21]
	v_mfma_f32_16x16x32_bf16 v[18:21], v[148:151], v[196:199], v[18:21]
	v_mfma_f32_16x16x32_bf16 v[26:29], v[134:137], v[192:195], v[26:29]
	v_mfma_f32_16x16x32_bf16 v[26:29], v[138:141], v[196:199], v[26:29]
	s_setprio 0
	s_barrier
	s_nop 7
	s_nop 7
	s_nop 7
	s_add_i32 s79, s79, 2
	s_addk_i32 s77, 0x100
	s_addk_i32 s78, 0x100
	s_cmp_ge_i32 s79, s3
	s_cbranch_scc0 .LBB0_799
	v_pk_mul_f32 v[184:185], v[128:129], 0.5 op_sel_hi:[1,0]
	v_pk_mul_f32 v[186:187], v[126:127], 0.5 op_sel_hi:[1,0]
	v_pk_mul_f32 v[188:189], v[124:125], 0.5 op_sel_hi:[1,0]
	v_pk_mul_f32 v[190:191], v[122:123], 0.5 op_sel_hi:[1,0]
	v_pk_mul_f32 v[198:199], v[112:113], 0.5 op_sel_hi:[1,0]
	v_pk_mul_f32 v[196:197], v[110:111], 0.5 op_sel_hi:[1,0]
	v_pk_mul_f32 v[194:195], v[104:105], 0.5 op_sel_hi:[1,0]
	v_pk_mul_f32 v[192:193], v[102:103], 0.5 op_sel_hi:[1,0]
	v_pk_mul_f32 v[182:183], v[120:121], 0.5 op_sel_hi:[1,0]
	v_pk_mul_f32 v[180:181], v[118:119], 0.5 op_sel_hi:[1,0]
	v_pk_mul_f32 v[178:179], v[116:117], 0.5 op_sel_hi:[1,0]
	v_pk_mul_f32 v[176:177], v[114:115], 0.5 op_sel_hi:[1,0]
	v_pk_mul_f32 v[172:173], v[96:97], 0.5 op_sel_hi:[1,0]
	v_pk_mul_f32 v[170:171], v[94:95], 0.5 op_sel_hi:[1,0]
	v_pk_mul_f32 v[168:169], v[88:89], 0.5 op_sel_hi:[1,0]
	v_pk_mul_f32 v[166:167], v[86:87], 0.5 op_sel_hi:[1,0]
	v_pk_mul_f32 v[164:165], v[108:109], 0.5 op_sel_hi:[1,0]
	v_pk_mul_f32 v[162:163], v[106:107], 0.5 op_sel_hi:[1,0]
	v_pk_mul_f32 v[160:161], v[100:101], 0.5 op_sel_hi:[1,0]
	v_pk_mul_f32 v[158:159], v[98:99], 0.5 op_sel_hi:[1,0]
	v_pk_mul_f32 v[156:157], v[80:81], 0.5 op_sel_hi:[1,0]
	v_pk_mul_f32 v[154:155], v[78:79], 0.5 op_sel_hi:[1,0]
	v_pk_mul_f32 v[152:153], v[76:77], 0.5 op_sel_hi:[1,0]
	v_pk_mul_f32 v[150:151], v[74:75], 0.5 op_sel_hi:[1,0]
	v_pk_mul_f32 v[144:145], v[92:93], 0.5 op_sel_hi:[1,0]
	v_pk_mul_f32 v[142:143], v[90:91], 0.5 op_sel_hi:[1,0]
	v_pk_mul_f32 v[140:141], v[84:85], 0.5 op_sel_hi:[1,0]
	v_pk_mul_f32 v[138:139], v[82:83], 0.5 op_sel_hi:[1,0]
	v_pk_mul_f32 v[136:137], v[72:73], 0.5 op_sel_hi:[1,0]
	v_pk_mul_f32 v[134:135], v[70:71], 0.5 op_sel_hi:[1,0]
	v_pk_mul_f32 v[128:129], v[68:69], 0.5 op_sel_hi:[1,0]
	v_pk_mul_f32 v[126:127], v[66:67], 0.5 op_sel_hi:[1,0]
	v_pk_mul_f32 v[122:123], v[64:65], 0.5 op_sel_hi:[1,0]
	v_pk_mul_f32 v[120:121], v[62:63], 0.5 op_sel_hi:[1,0]
	v_pk_mul_f32 v[118:119], v[60:61], 0.5 op_sel_hi:[1,0]
	v_pk_mul_f32 v[116:117], v[58:59], 0.5 op_sel_hi:[1,0]
	v_pk_mul_f32 v[112:113], v[48:49], 0.5 op_sel_hi:[1,0]
	v_pk_mul_f32 v[110:111], v[46:47], 0.5 op_sel_hi:[1,0]
	v_pk_mul_f32 v[108:109], v[40:41], 0.5 op_sel_hi:[1,0]
	v_pk_mul_f32 v[106:107], v[38:39], 0.5 op_sel_hi:[1,0]
	v_pk_mul_f32 v[104:105], v[56:57], 0.5 op_sel_hi:[1,0]
	v_pk_mul_f32 v[102:103], v[54:55], 0.5 op_sel_hi:[1,0]
	v_pk_mul_f32 v[100:101], v[52:53], 0.5 op_sel_hi:[1,0]
	v_pk_mul_f32 v[98:99], v[50:51], 0.5 op_sel_hi:[1,0]
	v_pk_mul_f32 v[96:97], v[32:33], 0.5 op_sel_hi:[1,0]
	v_pk_mul_f32 v[94:95], v[30:31], 0.5 op_sel_hi:[1,0]
	v_pk_mul_f32 v[92:93], v[24:25], 0.5 op_sel_hi:[1,0]
	v_pk_mul_f32 v[90:91], v[22:23], 0.5 op_sel_hi:[1,0]
	v_pk_mul_f32 v[88:89], v[44:45], 0.5 op_sel_hi:[1,0]
	v_pk_mul_f32 v[86:87], v[42:43], 0.5 op_sel_hi:[1,0]
	v_pk_mul_f32 v[84:85], v[36:37], 0.5 op_sel_hi:[1,0]
	v_pk_mul_f32 v[82:83], v[34:35], 0.5 op_sel_hi:[1,0]
	v_pk_mul_f32 v[80:81], v[16:17], 0.5 op_sel_hi:[1,0]
	v_pk_mul_f32 v[78:79], v[14:15], 0.5 op_sel_hi:[1,0]
	v_pk_mul_f32 v[76:77], v[12:13], 0.5 op_sel_hi:[1,0]
	v_pk_mul_f32 v[74:75], v[10:11], 0.5 op_sel_hi:[1,0]
	v_pk_mul_f32 v[72:73], v[28:29], 0.5 op_sel_hi:[1,0]
	v_pk_mul_f32 v[70:71], v[26:27], 0.5 op_sel_hi:[1,0]
	v_pk_mul_f32 v[68:69], v[20:21], 0.5 op_sel_hi:[1,0]
	v_pk_mul_f32 v[66:67], v[18:19], 0.5 op_sel_hi:[1,0]
	v_pk_mul_f32 v[64:65], v[8:9], 0.5 op_sel_hi:[1,0]
	v_pk_mul_f32 v[62:63], v[6:7], 0.5 op_sel_hi:[1,0]
	v_pk_mul_f32 v[60:61], v[4:5], 0.5 op_sel_hi:[1,0]
	v_pk_mul_f32 v[58:59], v[2:3], 0.5 op_sel_hi:[1,0]
	s_and_b64 vcc, exec, s[38:39]
	s_cbranch_vccz .LBB0_802

.LBB0_892:
	ds_read_b128 v[130:133], v172
	ds_read_b128 v[134:137], v172 offset:1024
	ds_read_b128 v[148:151], v172 offset:2048
	ds_read_b128 v[152:155], v172 offset:3072
	ds_read_b128 v[156:159], v173
	ds_read_b128 v[160:163], v173 offset:1024
	ds_read_b128 v[164:167], v173 offset:2048
	ds_read_b128 v[180:183], v173 offset:3072
	s_add_i32 s18, s8, 0xffe80080
	s_cmp_eq_u32 s77, s52
	s_cselect_b32 s53, s6, s18
	s_cselect_b32 s58, s7, s9
	s_or_b32 s57, s53, 0x80
	s_add_i32 s18, s8, 0xfff80000
	s_mov_b32 m0, s78
	ds_read_b128 v[184:187], v174
	ds_read_b128 v[188:191], v174 offset:1024
	ds_read_b128 v[192:195], v174 offset:2048
	ds_read_b128 v[196:199], v174 offset:3072
	ds_read_b128 v[200:203], v174 offset:4096
	ds_read_b128 v[204:207], v174 offset:5120
	ds_read_b128 v[208:211], v174 offset:6144
	ds_read_b128 v[212:215], v174 offset:7168
	buffer_load_dwordx4 v170, s[12:15], s18 offen lds
	s_mov_b32 m0, s79
	s_nop 0
	buffer_load_dwordx4 v170, s[12:15], s8 offen lds
	s_waitcnt vmcnt(8)
	s_waitcnt lgkmcnt(0)
	s_setprio 1
	v_mfma_f32_16x16x32_bf16 v[126:129], v[130:133], v[184:187], v[126:129]
	s_barrier
	v_mfma_f32_16x16x32_bf16 v[126:129], v[134:137], v[188:191], v[126:129]
	v_mfma_f32_16x16x32_bf16 v[118:121], v[148:151], v[184:187], v[118:121]
	v_mfma_f32_16x16x32_bf16 v[118:121], v[152:155], v[188:191], v[118:121]
	v_mfma_f32_16x16x32_bf16 v[122:125], v[156:159], v[184:187], v[122:125]
	v_mfma_f32_16x16x32_bf16 v[122:125], v[160:163], v[188:191], v[122:125]
	v_mfma_f32_16x16x32_bf16 v[114:117], v[164:167], v[184:187], v[114:117]
	v_mfma_f32_16x16x32_bf16 v[114:117], v[180:183], v[188:191], v[114:117]
	v_mfma_f32_16x16x32_bf16 v[98:101], v[164:167], v[192:195], v[98:101]
	v_mfma_f32_16x16x32_bf16 v[98:101], v[180:183], v[196:199], v[98:101]
	v_mfma_f32_16x16x32_bf16 v[106:109], v[156:159], v[192:195], v[106:109]
	v_mfma_f32_16x16x32_bf16 v[106:109], v[160:163], v[196:199], v[106:109]
	v_mfma_f32_16x16x32_bf16 v[102:105], v[148:151], v[192:195], v[102:105]
	v_mfma_f32_16x16x32_bf16 v[102:105], v[152:155], v[196:199], v[102:105]
	v_mfma_f32_16x16x32_bf16 v[110:113], v[130:133], v[192:195], v[110:113]
	v_mfma_f32_16x16x32_bf16 v[110:113], v[134:137], v[196:199], v[110:113]
	v_mfma_f32_16x16x32_bf16 v[94:97], v[130:133], v[200:203], v[94:97]
	v_mfma_f32_16x16x32_bf16 v[94:97], v[134:137], v[204:207], v[94:97]
	v_mfma_f32_16x16x32_bf16 v[90:93], v[148:151], v[200:203], v[90:93]
	v_mfma_f32_16x16x32_bf16 v[90:93], v[152:155], v[204:207], v[90:93]
	v_mfma_f32_16x16x32_bf16 v[86:89], v[156:159], v[200:203], v[86:89]
	v_mfma_f32_16x16x32_bf16 v[86:89], v[160:163], v[204:207], v[86:89]
	v_mfma_f32_16x16x32_bf16 v[82:85], v[164:167], v[200:203], v[82:85]
	v_mfma_f32_16x16x32_bf16 v[82:85], v[180:183], v[204:207], v[82:85]
	v_mfma_f32_16x16x32_bf16 v[66:69], v[164:167], v[208:211], v[66:69]
	v_mfma_f32_16x16x32_bf16 v[66:69], v[180:183], v[212:215], v[66:69]
	v_mfma_f32_16x16x32_bf16 v[74:77], v[156:159], v[208:211], v[74:77]
	v_mfma_f32_16x16x32_bf16 v[74:77], v[160:163], v[212:215], v[74:77]
	v_mfma_f32_16x16x32_bf16 v[70:73], v[148:151], v[208:211], v[70:73]
	v_mfma_f32_16x16x32_bf16 v[70:73], v[152:155], v[212:215], v[70:73]
	v_mfma_f32_16x16x32_bf16 v[78:81], v[130:133], v[208:211], v[78:81]
	v_mfma_f32_16x16x32_bf16 v[78:81], v[134:137], v[212:215], v[78:81]
	s_setprio 0
	s_barrier
	s_mov_b32 m0, s27
	s_mov_b32 s18, s14
	s_mov_b32 s19, s15
	ds_read_b128 v[184:187], v174 offset:16384
	ds_read_b128 v[188:191], v174 offset:17408
	ds_read_b128 v[192:195], v174 offset:18432
	ds_read_b128 v[196:199], v174 offset:19456
	ds_read_b128 v[200:203], v174 offset:20480
	ds_read_b128 v[204:207], v174 offset:21504
	ds_read_b128 v[208:211], v174 offset:22528
	ds_read_b128 v[212:215], v174 offset:23552
	buffer_load_dwordx4 v171, s[16:19], s58 offen lds
	s_add_i32 s59, s58, 0x80000
	s_mov_b32 m0, s60
	s_nop 0
	buffer_load_dwordx4 v171, s[16:19], s59 offen lds
	s_add_i32 s59, s58, 0x100000
	s_mov_b32 m0, s61
	s_nop 0
	buffer_load_dwordx4 v171, s[16:19], s59 offen lds
	s_add_i32 s59, s58, 0x180000
	s_mov_b32 m0, s62
	s_nop 0
	buffer_load_dwordx4 v171, s[16:19], s59 offen lds
	s_mov_b32 m0, s25
	s_add_i32 s59, s53, 0x80000
	buffer_load_dwordx4 v170, s[12:15], s53 offen lds
	s_mov_b32 m0, s63
	s_nop 0
	buffer_load_dwordx4 v170, s[12:15], s59 offen lds
	s_waitcnt vmcnt(8)
	s_waitcnt lgkmcnt(0)
	s_setprio 1
	v_mfma_f32_16x16x32_bf16 v[62:65], v[130:133], v[184:187], v[62:65]
	s_barrier
	v_mfma_f32_16x16x32_bf16 v[62:65], v[134:137], v[188:191], v[62:65]
	v_mfma_f32_16x16x32_bf16 v[54:57], v[148:151], v[184:187], v[54:57]
	v_mfma_f32_16x16x32_bf16 v[54:57], v[152:155], v[188:191], v[54:57]
	v_mfma_f32_16x16x32_bf16 v[58:61], v[156:159], v[184:187], v[58:61]
	v_mfma_f32_16x16x32_bf16 v[58:61], v[160:163], v[188:191], v[58:61]
	v_mfma_f32_16x16x32_bf16 v[50:53], v[164:167], v[184:187], v[50:53]
	v_mfma_f32_16x16x32_bf16 v[50:53], v[180:183], v[188:191], v[50:53]
	v_mfma_f32_16x16x32_bf16 v[34:37], v[164:167], v[192:195], v[34:37]
	v_mfma_f32_16x16x32_bf16 v[34:37], v[180:183], v[196:199], v[34:37]
	v_mfma_f32_16x16x32_bf16 v[42:45], v[156:159], v[192:195], v[42:45]
	v_mfma_f32_16x16x32_bf16 v[42:45], v[160:163], v[196:199], v[42:45]
	v_mfma_f32_16x16x32_bf16 v[38:41], v[148:151], v[192:195], v[38:41]
	v_mfma_f32_16x16x32_bf16 v[38:41], v[152:155], v[196:199], v[38:41]
	v_mfma_f32_16x16x32_bf16 v[46:49], v[130:133], v[192:195], v[46:49]
	v_mfma_f32_16x16x32_bf16 v[46:49], v[134:137], v[196:199], v[46:49]
	v_mfma_f32_16x16x32_bf16 v[30:33], v[130:133], v[200:203], v[30:33]
	v_mfma_f32_16x16x32_bf16 v[30:33], v[134:137], v[204:207], v[30:33]
	v_mfma_f32_16x16x32_bf16 v[22:25], v[148:151], v[200:203], v[22:25]
	v_mfma_f32_16x16x32_bf16 v[22:25], v[152:155], v[204:207], v[22:25]
	v_mfma_f32_16x16x32_bf16 v[26:29], v[156:159], v[200:203], v[26:29]
	v_mfma_f32_16x16x32_bf16 v[26:29], v[160:163], v[204:207], v[26:29]
	v_mfma_f32_16x16x32_bf16 v[18:21], v[164:167], v[200:203], v[18:21]
	v_mfma_f32_16x16x32_bf16 v[18:21], v[180:183], v[204:207], v[18:21]
	v_mfma_f32_16x16x32_bf16 v[2:5], v[164:167], v[208:211], v[2:5]
	v_mfma_f32_16x16x32_bf16 v[2:5], v[180:183], v[212:215], v[2:5]
	v_mfma_f32_16x16x32_bf16 v[10:13], v[156:159], v[208:211], v[10:13]
	v_mfma_f32_16x16x32_bf16 v[10:13], v[160:163], v[212:215], v[10:13]
	v_mfma_f32_16x16x32_bf16 v[6:9], v[148:151], v[208:211], v[6:9]
	v_mfma_f32_16x16x32_bf16 v[6:9], v[152:155], v[212:215], v[6:9]
	v_mfma_f32_16x16x32_bf16 v[14:17], v[130:133], v[208:211], v[14:17]
	v_mfma_f32_16x16x32_bf16 v[14:17], v[134:137], v[212:215], v[14:17]
	s_setprio 0
	s_barrier
	s_nop 7
	s_nop 7
	s_nop 7
	ds_read_b128 v[130:133], v175
	ds_read_b128 v[134:137], v175 offset:1024
	ds_read_b128 v[148:151], v175 offset:2048
	ds_read_b128 v[152:155], v175 offset:3072
	ds_read_b128 v[156:159], v176
	ds_read_b128 v[160:163], v176 offset:1024
	ds_read_b128 v[164:167], v176 offset:2048
	ds_read_b128 v[180:183], v176 offset:3072
	s_mov_b32 m0, s64
	s_add_i32 s59, s53, 0x100000
	ds_read_b128 v[184:187], v174 offset:32768
	ds_read_b128 v[188:191], v174 offset:33792
	ds_read_b128 v[192:195], v174 offset:34816
	ds_read_b128 v[196:199], v174 offset:35840
	ds_read_b128 v[200:203], v174 offset:36864
	ds_read_b128 v[204:207], v174 offset:37888
	ds_read_b128 v[208:211], v174 offset:38912
	ds_read_b128 v[212:215], v174 offset:39936
	buffer_load_dwordx4 v170, s[12:15], s59 offen lds
	s_add_i32 s59, s53, 0x180000
	s_mov_b32 m0, s65
	s_nop 0
	buffer_load_dwordx4 v170, s[12:15], s59 offen lds
	s_waitcnt vmcnt(8)
	s_waitcnt lgkmcnt(0)
	s_setprio 1
	v_mfma_f32_16x16x32_bf16 v[126:129], v[130:133], v[184:187], v[126:129]
	s_barrier
	v_mfma_f32_16x16x32_bf16 v[126:129], v[134:137], v[188:191], v[126:129]
	v_mfma_f32_16x16x32_bf16 v[118:121], v[148:151], v[184:187], v[118:121]
	v_mfma_f32_16x16x32_bf16 v[118:121], v[152:155], v[188:191], v[118:121]
	v_mfma_f32_16x16x32_bf16 v[122:125], v[156:159], v[184:187], v[122:125]
	v_mfma_f32_16x16x32_bf16 v[122:125], v[160:163], v[188:191], v[122:125]
	v_mfma_f32_16x16x32_bf16 v[114:117], v[164:167], v[184:187], v[114:117]
	v_mfma_f32_16x16x32_bf16 v[114:117], v[180:183], v[188:191], v[114:117]
	v_mfma_f32_16x16x32_bf16 v[98:101], v[164:167], v[192:195], v[98:101]
	v_mfma_f32_16x16x32_bf16 v[98:101], v[180:183], v[196:199], v[98:101]
	v_mfma_f32_16x16x32_bf16 v[106:109], v[156:159], v[192:195], v[106:109]
	v_mfma_f32_16x16x32_bf16 v[106:109], v[160:163], v[196:199], v[106:109]
	v_mfma_f32_16x16x32_bf16 v[102:105], v[148:151], v[192:195], v[102:105]
	v_mfma_f32_16x16x32_bf16 v[102:105], v[152:155], v[196:199], v[102:105]
	v_mfma_f32_16x16x32_bf16 v[110:113], v[130:133], v[192:195], v[110:113]
	v_mfma_f32_16x16x32_bf16 v[110:113], v[134:137], v[196:199], v[110:113]
	v_mfma_f32_16x16x32_bf16 v[94:97], v[130:133], v[200:203], v[94:97]
	v_mfma_f32_16x16x32_bf16 v[94:97], v[134:137], v[204:207], v[94:97]
	v_mfma_f32_16x16x32_bf16 v[90:93], v[148:151], v[200:203], v[90:93]
	v_mfma_f32_16x16x32_bf16 v[90:93], v[152:155], v[204:207], v[90:93]
	v_mfma_f32_16x16x32_bf16 v[86:89], v[156:159], v[200:203], v[86:89]
	v_mfma_f32_16x16x32_bf16 v[86:89], v[160:163], v[204:207], v[86:89]
	v_mfma_f32_16x16x32_bf16 v[82:85], v[164:167], v[200:203], v[82:85]
	v_mfma_f32_16x16x32_bf16 v[82:85], v[180:183], v[204:207], v[82:85]
	v_mfma_f32_16x16x32_bf16 v[66:69], v[164:167], v[208:211], v[66:69]
	v_mfma_f32_16x16x32_bf16 v[66:69], v[180:183], v[212:215], v[66:69]
	v_mfma_f32_16x16x32_bf16 v[74:77], v[156:159], v[208:211], v[74:77]
	v_mfma_f32_16x16x32_bf16 v[74:77], v[160:163], v[212:215], v[74:77]
	v_mfma_f32_16x16x32_bf16 v[70:73], v[148:151], v[208:211], v[70:73]
	v_mfma_f32_16x16x32_bf16 v[70:73], v[152:155], v[212:215], v[70:73]
	v_mfma_f32_16x16x32_bf16 v[78:81], v[130:133], v[208:211], v[78:81]
	v_mfma_f32_16x16x32_bf16 v[78:81], v[134:137], v[212:215], v[78:81]
	s_setprio 0
	s_barrier
	s_mov_b32 m0, s70
	s_or_b32 s59, s58, 0x80
	ds_read_b128 v[184:187], v174 offset:49152
	ds_read_b128 v[188:191], v174 offset:50176
	ds_read_b128 v[192:195], v174 offset:51200
	ds_read_b128 v[196:199], v174 offset:52224
	ds_read_b128 v[200:203], v174 offset:53248
	ds_read_b128 v[204:207], v174 offset:54272
	ds_read_b128 v[208:211], v174 offset:55296
	ds_read_b128 v[212:215], v174 offset:56320
	buffer_load_dwordx4 v171, s[16:19], s59 offen lds
	s_add_i32 s59, s58, 0x80080
	s_mov_b32 m0, s71
	s_add_i32 s53, s53, 0x80080
	buffer_load_dwordx4 v171, s[16:19], s59 offen lds
	s_add_i32 s59, s58, 0x100080
	s_mov_b32 m0, s74
	s_add_i32 s58, s58, 0x180080
	buffer_load_dwordx4 v171, s[16:19], s59 offen lds
	s_mov_b32 m0, s75
	s_nop 0
	buffer_load_dwordx4 v171, s[16:19], s58 offen lds
	s_mov_b32 m0, s72
	s_nop 0
	buffer_load_dwordx4 v170, s[12:15], s57 offen lds
	s_mov_b32 m0, s73
	s_nop 0
	buffer_load_dwordx4 v170, s[12:15], s53 offen lds
	s_waitcnt vmcnt(8)
	s_waitcnt lgkmcnt(0)
	s_setprio 1
	v_mfma_f32_16x16x32_bf16 v[62:65], v[130:133], v[184:187], v[62:65]
	s_barrier
	v_mfma_f32_16x16x32_bf16 v[62:65], v[134:137], v[188:191], v[62:65]
	v_mfma_f32_16x16x32_bf16 v[54:57], v[148:151], v[184:187], v[54:57]
	v_mfma_f32_16x16x32_bf16 v[54:57], v[152:155], v[188:191], v[54:57]
	v_mfma_f32_16x16x32_bf16 v[58:61], v[156:159], v[184:187], v[58:61]
	v_mfma_f32_16x16x32_bf16 v[58:61], v[160:163], v[188:191], v[58:61]
	v_mfma_f32_16x16x32_bf16 v[50:53], v[164:167], v[184:187], v[50:53]
	v_mfma_f32_16x16x32_bf16 v[50:53], v[180:183], v[188:191], v[50:53]
	v_mfma_f32_16x16x32_bf16 v[34:37], v[164:167], v[192:195], v[34:37]
	v_mfma_f32_16x16x32_bf16 v[34:37], v[180:183], v[196:199], v[34:37]
	v_mfma_f32_16x16x32_bf16 v[42:45], v[156:159], v[192:195], v[42:45]
	v_mfma_f32_16x16x32_bf16 v[42:45], v[160:163], v[196:199], v[42:45]
	v_mfma_f32_16x16x32_bf16 v[38:41], v[148:151], v[192:195], v[38:41]
	v_mfma_f32_16x16x32_bf16 v[38:41], v[152:155], v[196:199], v[38:41]
	v_mfma_f32_16x16x32_bf16 v[46:49], v[130:133], v[192:195], v[46:49]
	v_mfma_f32_16x16x32_bf16 v[46:49], v[134:137], v[196:199], v[46:49]
	v_mfma_f32_16x16x32_bf16 v[30:33], v[130:133], v[200:203], v[30:33]
	v_mfma_f32_16x16x32_bf16 v[30:33], v[134:137], v[204:207], v[30:33]
	v_mfma_f32_16x16x32_bf16 v[22:25], v[148:151], v[200:203], v[22:25]
	v_mfma_f32_16x16x32_bf16 v[22:25], v[152:155], v[204:207], v[22:25]
	v_mfma_f32_16x16x32_bf16 v[26:29], v[156:159], v[200:203], v[26:29]
	v_mfma_f32_16x16x32_bf16 v[26:29], v[160:163], v[204:207], v[26:29]
	v_mfma_f32_16x16x32_bf16 v[18:21], v[164:167], v[200:203], v[18:21]
	v_mfma_f32_16x16x32_bf16 v[18:21], v[180:183], v[204:207], v[18:21]
	v_mfma_f32_16x16x32_bf16 v[2:5], v[164:167], v[208:211], v[2:5]
	v_mfma_f32_16x16x32_bf16 v[2:5], v[180:183], v[212:215], v[2:5]
	v_mfma_f32_16x16x32_bf16 v[10:13], v[156:159], v[208:211], v[10:13]
	v_mfma_f32_16x16x32_bf16 v[10:13], v[160:163], v[212:215], v[10:13]
	v_mfma_f32_16x16x32_bf16 v[6:9], v[148:151], v[208:211], v[6:9]
	v_mfma_f32_16x16x32_bf16 v[6:9], v[152:155], v[212:215], v[6:9]
	v_mfma_f32_16x16x32_bf16 v[14:17], v[130:133], v[208:211], v[14:17]
	v_mfma_f32_16x16x32_bf16 v[14:17], v[134:137], v[212:215], v[14:17]
	s_setprio 0
	s_barrier
	s_nop 7
	s_nop 7
	s_nop 7
	s_add_i32 s52, s52, 2
	s_addk_i32 s8, 0x100
	s_addk_i32 s9, 0x100
	s_cmp_ge_i32 s52, s21
	s_cbranch_scc0 .LBB0_892
	s_and_b64 vcc, exec, s[48:49]
	s_cbranch_vccz .LBB0_895

.LBB0_1020:
	v_add_u32_e32 v142, 0x10000, v162
	v_add_u32_e32 v150, 0x14000, v162
	ds_read_b128 v[130:133], v142
	ds_read_b128 v[134:137], v142 offset:1024
	ds_read_b128 v[138:141], v142 offset:2048
	ds_read_b128 v[142:145], v142 offset:3072
	ds_read_b128 v[154:157], v150
	ds_read_b128 v[164:167], v150 offset:1024
	ds_read_b128 v[168:171], v150 offset:2048
	ds_read_b128 v[172:175], v150 offset:3072
	s_add_i32 s90, s6, 0x100
	s_add_i32 s7, s88, s6
	s_cmp_eq_u32 s81, s89
	s_cselect_b32 s91, 0, s90
	s_cselect_b32 s93, s87, s7
	s_add_i32 s91, s91, s70
	s_or_b32 s92, s91, 0x80
	s_add_i32 s6, s3, s6
	s_mov_b32 m0, s82
	s_add_i32 s7, s6, 0x20080
	ds_read_b128 v[176:179], v163
	ds_read_b128 v[180:183], v163 offset:1024
	ds_read_b128 v[184:187], v163 offset:2048
	ds_read_b128 v[188:191], v163 offset:3072
	ds_read_b128 v[192:195], v163 offset:4096
	ds_read_b128 v[196:199], v163 offset:5120
	ds_read_b128 v[200:203], v163 offset:6144
	ds_read_b128 v[204:207], v163 offset:7168
	buffer_load_dwordx4 v161, s[12:15], s7 offen lds
	s_add_i32 s6, s6, 0x30080
	s_mov_b32 m0, s83
	s_nop 0
	buffer_load_dwordx4 v161, s[12:15], s6 offen lds
	s_waitcnt vmcnt(8)
	s_waitcnt lgkmcnt(0)
	s_setprio 1
	v_mfma_f32_16x16x32_bf16 v[126:129], v[130:133], v[176:179], v[126:129]
	s_barrier
	v_mfma_f32_16x16x32_bf16 v[126:129], v[134:137], v[180:183], v[126:129]
	v_mfma_f32_16x16x32_bf16 v[122:125], v[138:141], v[176:179], v[122:125]
	v_mfma_f32_16x16x32_bf16 v[122:125], v[142:145], v[180:183], v[122:125]
	v_mfma_f32_16x16x32_bf16 v[118:121], v[154:157], v[176:179], v[118:121]
	v_mfma_f32_16x16x32_bf16 v[118:121], v[164:167], v[180:183], v[118:121]
	v_mfma_f32_16x16x32_bf16 v[114:117], v[168:171], v[176:179], v[114:117]
	v_mfma_f32_16x16x32_bf16 v[114:117], v[172:175], v[180:183], v[114:117]
	v_mfma_f32_16x16x32_bf16 v[98:101], v[168:171], v[184:187], v[98:101]
	v_mfma_f32_16x16x32_bf16 v[98:101], v[172:175], v[188:191], v[98:101]
	v_mfma_f32_16x16x32_bf16 v[102:105], v[154:157], v[184:187], v[102:105]
	v_mfma_f32_16x16x32_bf16 v[102:105], v[164:167], v[188:191], v[102:105]
	v_mfma_f32_16x16x32_bf16 v[106:109], v[138:141], v[184:187], v[106:109]
	v_mfma_f32_16x16x32_bf16 v[106:109], v[142:145], v[188:191], v[106:109]
	v_mfma_f32_16x16x32_bf16 v[110:113], v[130:133], v[184:187], v[110:113]
	v_mfma_f32_16x16x32_bf16 v[110:113], v[134:137], v[188:191], v[110:113]
	v_mfma_f32_16x16x32_bf16 v[94:97], v[130:133], v[192:195], v[94:97]
	v_mfma_f32_16x16x32_bf16 v[94:97], v[134:137], v[196:199], v[94:97]
	v_mfma_f32_16x16x32_bf16 v[90:93], v[138:141], v[192:195], v[90:93]
	v_mfma_f32_16x16x32_bf16 v[90:93], v[142:145], v[196:199], v[90:93]
	v_mfma_f32_16x16x32_bf16 v[86:89], v[154:157], v[192:195], v[86:89]
	v_mfma_f32_16x16x32_bf16 v[86:89], v[164:167], v[196:199], v[86:89]
	v_mfma_f32_16x16x32_bf16 v[82:85], v[168:171], v[192:195], v[82:85]
	v_mfma_f32_16x16x32_bf16 v[82:85], v[172:175], v[196:199], v[82:85]
	v_mfma_f32_16x16x32_bf16 v[66:69], v[168:171], v[200:203], v[66:69]
	v_mfma_f32_16x16x32_bf16 v[66:69], v[172:175], v[204:207], v[66:69]
	v_mfma_f32_16x16x32_bf16 v[70:73], v[154:157], v[200:203], v[70:73]
	v_mfma_f32_16x16x32_bf16 v[70:73], v[164:167], v[204:207], v[70:73]
	v_mfma_f32_16x16x32_bf16 v[74:77], v[138:141], v[200:203], v[74:77]
	v_mfma_f32_16x16x32_bf16 v[74:77], v[142:145], v[204:207], v[74:77]
	v_mfma_f32_16x16x32_bf16 v[78:81], v[130:133], v[200:203], v[78:81]
	v_mfma_f32_16x16x32_bf16 v[78:81], v[134:137], v[204:207], v[78:81]
	s_setprio 0
	s_barrier
	s_mov_b32 m0, s66
	s_mov_b32 s6, s14
	s_mov_b32 s7, s15
	ds_read_b128 v[176:179], v163 offset:16384
	ds_read_b128 v[180:183], v163 offset:17408
	ds_read_b128 v[184:187], v163 offset:18432
	ds_read_b128 v[188:191], v163 offset:19456
	ds_read_b128 v[192:195], v163 offset:20480
	ds_read_b128 v[196:199], v163 offset:21504
	ds_read_b128 v[200:203], v163 offset:22528
	ds_read_b128 v[204:207], v163 offset:23552
	buffer_load_dwordx4 v160, s[4:7], s93 offen lds
	s_add_i32 s94, s93, 0x10000
	s_mov_b32 m0, s67
	s_nop 0
	buffer_load_dwordx4 v160, s[4:7], s94 offen lds
	s_add_i32 s94, s93, 0x20000
	s_mov_b32 m0, s68
	s_nop 0
	buffer_load_dwordx4 v160, s[4:7], s94 offen lds
	s_add_i32 s94, s93, 0x30000
	s_mov_b32 m0, s69
	s_nop 0
	buffer_load_dwordx4 v160, s[4:7], s94 offen lds
	s_mov_b32 m0, s65
	s_add_i32 s94, s91, 0x10000
	buffer_load_dwordx4 v161, s[12:15], s91 offen lds
	s_mov_b32 m0, s71
	s_nop 0
	buffer_load_dwordx4 v161, s[12:15], s94 offen lds
	s_waitcnt vmcnt(8)
	s_waitcnt lgkmcnt(0)
	s_setprio 1
	v_mfma_f32_16x16x32_bf16 v[62:65], v[130:133], v[176:179], v[62:65]
	s_barrier
	v_mfma_f32_16x16x32_bf16 v[62:65], v[134:137], v[180:183], v[62:65]
	v_mfma_f32_16x16x32_bf16 v[58:61], v[138:141], v[176:179], v[58:61]
	v_mfma_f32_16x16x32_bf16 v[58:61], v[142:145], v[180:183], v[58:61]
	v_mfma_f32_16x16x32_bf16 v[54:57], v[154:157], v[176:179], v[54:57]
	v_mfma_f32_16x16x32_bf16 v[54:57], v[164:167], v[180:183], v[54:57]
	v_mfma_f32_16x16x32_bf16 v[50:53], v[168:171], v[176:179], v[50:53]
	v_mfma_f32_16x16x32_bf16 v[50:53], v[172:175], v[180:183], v[50:53]
	v_mfma_f32_16x16x32_bf16 v[34:37], v[168:171], v[184:187], v[34:37]
	v_mfma_f32_16x16x32_bf16 v[34:37], v[172:175], v[188:191], v[34:37]
	v_mfma_f32_16x16x32_bf16 v[38:41], v[154:157], v[184:187], v[38:41]
	v_mfma_f32_16x16x32_bf16 v[38:41], v[164:167], v[188:191], v[38:41]
	v_mfma_f32_16x16x32_bf16 v[42:45], v[138:141], v[184:187], v[42:45]
	v_mfma_f32_16x16x32_bf16 v[42:45], v[142:145], v[188:191], v[42:45]
	v_mfma_f32_16x16x32_bf16 v[46:49], v[130:133], v[184:187], v[46:49]
	v_mfma_f32_16x16x32_bf16 v[46:49], v[134:137], v[188:191], v[46:49]
	v_mfma_f32_16x16x32_bf16 v[30:33], v[130:133], v[192:195], v[30:33]
	v_mfma_f32_16x16x32_bf16 v[30:33], v[134:137], v[196:199], v[30:33]
	v_mfma_f32_16x16x32_bf16 v[26:29], v[138:141], v[192:195], v[26:29]
	v_mfma_f32_16x16x32_bf16 v[26:29], v[142:145], v[196:199], v[26:29]
	v_mfma_f32_16x16x32_bf16 v[22:25], v[154:157], v[192:195], v[22:25]
	v_mfma_f32_16x16x32_bf16 v[22:25], v[164:167], v[196:199], v[22:25]
	v_mfma_f32_16x16x32_bf16 v[18:21], v[168:171], v[192:195], v[18:21]
	v_mfma_f32_16x16x32_bf16 v[18:21], v[172:175], v[196:199], v[18:21]
	v_mfma_f32_16x16x32_bf16 v[2:5], v[168:171], v[200:203], v[2:5]
	v_mfma_f32_16x16x32_bf16 v[2:5], v[172:175], v[204:207], v[2:5]
	v_mfma_f32_16x16x32_bf16 v[6:9], v[154:157], v[200:203], v[6:9]
	v_mfma_f32_16x16x32_bf16 v[6:9], v[164:167], v[204:207], v[6:9]
	v_mfma_f32_16x16x32_bf16 v[10:13], v[138:141], v[200:203], v[10:13]
	v_mfma_f32_16x16x32_bf16 v[10:13], v[142:145], v[204:207], v[10:13]
	v_mfma_f32_16x16x32_bf16 v[14:17], v[130:133], v[200:203], v[14:17]
	v_mfma_f32_16x16x32_bf16 v[14:17], v[134:137], v[204:207], v[14:17]
	s_setprio 0
	s_barrier
	s_nop 7
	s_nop 7
	s_nop 7
	v_add_u32_e32 v142, 0x18000, v162
	v_add_u32_e32 v150, 0x1c000, v162
	ds_read_b128 v[130:133], v142
	ds_read_b128 v[134:137], v142 offset:1024
	ds_read_b128 v[138:141], v142 offset:2048
	ds_read_b128 v[142:145], v142 offset:3072
	ds_read_b128 v[154:157], v150
	ds_read_b128 v[164:167], v150 offset:1024
	ds_read_b128 v[168:171], v150 offset:2048
	ds_read_b128 v[172:175], v150 offset:3072
	s_mov_b32 m0, s72
	s_add_i32 s94, s91, 0x20000
	ds_read_b128 v[176:179], v163 offset:32768
	ds_read_b128 v[180:183], v163 offset:33792
	ds_read_b128 v[184:187], v163 offset:34816
	ds_read_b128 v[188:191], v163 offset:35840
	ds_read_b128 v[192:195], v163 offset:36864
	ds_read_b128 v[196:199], v163 offset:37888
	ds_read_b128 v[200:203], v163 offset:38912
	ds_read_b128 v[204:207], v163 offset:39936
	buffer_load_dwordx4 v161, s[12:15], s94 offen lds
	s_add_i32 s94, s91, 0x30000
	s_mov_b32 m0, s73
	s_nop 0
	buffer_load_dwordx4 v161, s[12:15], s94 offen lds
	s_waitcnt vmcnt(8)
	s_waitcnt lgkmcnt(0)
	s_setprio 1
	v_mfma_f32_16x16x32_bf16 v[126:129], v[130:133], v[176:179], v[126:129]
	s_barrier
	v_mfma_f32_16x16x32_bf16 v[126:129], v[134:137], v[180:183], v[126:129]
	v_mfma_f32_16x16x32_bf16 v[122:125], v[138:141], v[176:179], v[122:125]
	v_mfma_f32_16x16x32_bf16 v[122:125], v[142:145], v[180:183], v[122:125]
	v_mfma_f32_16x16x32_bf16 v[118:121], v[154:157], v[176:179], v[118:121]
	v_mfma_f32_16x16x32_bf16 v[118:121], v[164:167], v[180:183], v[118:121]
	v_mfma_f32_16x16x32_bf16 v[114:117], v[168:171], v[176:179], v[114:117]
	v_mfma_f32_16x16x32_bf16 v[114:117], v[172:175], v[180:183], v[114:117]
	v_mfma_f32_16x16x32_bf16 v[98:101], v[168:171], v[184:187], v[98:101]
	v_mfma_f32_16x16x32_bf16 v[98:101], v[172:175], v[188:191], v[98:101]
	v_mfma_f32_16x16x32_bf16 v[102:105], v[154:157], v[184:187], v[102:105]
	v_mfma_f32_16x16x32_bf16 v[102:105], v[164:167], v[188:191], v[102:105]
	v_mfma_f32_16x16x32_bf16 v[106:109], v[138:141], v[184:187], v[106:109]
	v_mfma_f32_16x16x32_bf16 v[106:109], v[142:145], v[188:191], v[106:109]
	v_mfma_f32_16x16x32_bf16 v[110:113], v[130:133], v[184:187], v[110:113]
	v_mfma_f32_16x16x32_bf16 v[110:113], v[134:137], v[188:191], v[110:113]
	v_mfma_f32_16x16x32_bf16 v[94:97], v[130:133], v[192:195], v[94:97]
	v_mfma_f32_16x16x32_bf16 v[94:97], v[134:137], v[196:199], v[94:97]
	v_mfma_f32_16x16x32_bf16 v[90:93], v[138:141], v[192:195], v[90:93]
	v_mfma_f32_16x16x32_bf16 v[90:93], v[142:145], v[196:199], v[90:93]
	v_mfma_f32_16x16x32_bf16 v[86:89], v[154:157], v[192:195], v[86:89]
	v_mfma_f32_16x16x32_bf16 v[86:89], v[164:167], v[196:199], v[86:89]
	v_mfma_f32_16x16x32_bf16 v[82:85], v[168:171], v[192:195], v[82:85]
	v_mfma_f32_16x16x32_bf16 v[82:85], v[172:175], v[196:199], v[82:85]
	v_mfma_f32_16x16x32_bf16 v[66:69], v[168:171], v[200:203], v[66:69]
	v_mfma_f32_16x16x32_bf16 v[66:69], v[172:175], v[204:207], v[66:69]
	v_mfma_f32_16x16x32_bf16 v[70:73], v[154:157], v[200:203], v[70:73]
	v_mfma_f32_16x16x32_bf16 v[70:73], v[164:167], v[204:207], v[70:73]
	v_mfma_f32_16x16x32_bf16 v[74:77], v[138:141], v[200:203], v[74:77]
	v_mfma_f32_16x16x32_bf16 v[74:77], v[142:145], v[204:207], v[74:77]
	v_mfma_f32_16x16x32_bf16 v[78:81], v[130:133], v[200:203], v[78:81]
	v_mfma_f32_16x16x32_bf16 v[78:81], v[134:137], v[204:207], v[78:81]
	s_setprio 0
	s_barrier
	s_mov_b32 m0, s74
	s_or_b32 s94, s93, 0x80
	ds_read_b128 v[176:179], v163 offset:49152
	ds_read_b128 v[180:183], v163 offset:50176
	ds_read_b128 v[184:187], v163 offset:51200
	ds_read_b128 v[188:191], v163 offset:52224
	ds_read_b128 v[192:195], v163 offset:53248
	ds_read_b128 v[196:199], v163 offset:54272
	ds_read_b128 v[200:203], v163 offset:55296
	ds_read_b128 v[204:207], v163 offset:56320
	buffer_load_dwordx4 v160, s[4:7], s94 offen lds
	s_add_i32 s94, s93, 0x10080
	s_mov_b32 m0, s75
	s_add_i32 s91, s91, 0x10080
	buffer_load_dwordx4 v160, s[4:7], s94 offen lds
	s_add_i32 s94, s93, 0x20080
	s_mov_b32 m0, s78
	s_add_i32 s93, s93, 0x30080
	buffer_load_dwordx4 v160, s[4:7], s94 offen lds
	s_mov_b32 m0, s79
	s_nop 0
	buffer_load_dwordx4 v160, s[4:7], s93 offen lds
	s_mov_b32 m0, s76
	s_nop 0
	buffer_load_dwordx4 v161, s[12:15], s92 offen lds
	s_mov_b32 m0, s77
	s_nop 0
	buffer_load_dwordx4 v161, s[12:15], s91 offen lds
	s_waitcnt vmcnt(8)
	s_waitcnt lgkmcnt(0)
	s_setprio 1
	v_mfma_f32_16x16x32_bf16 v[62:65], v[130:133], v[176:179], v[62:65]
	s_barrier
	v_mfma_f32_16x16x32_bf16 v[62:65], v[134:137], v[180:183], v[62:65]
	v_mfma_f32_16x16x32_bf16 v[58:61], v[138:141], v[176:179], v[58:61]
	v_mfma_f32_16x16x32_bf16 v[58:61], v[142:145], v[180:183], v[58:61]
	v_mfma_f32_16x16x32_bf16 v[54:57], v[154:157], v[176:179], v[54:57]
	v_mfma_f32_16x16x32_bf16 v[54:57], v[164:167], v[180:183], v[54:57]
	v_mfma_f32_16x16x32_bf16 v[50:53], v[168:171], v[176:179], v[50:53]
	v_mfma_f32_16x16x32_bf16 v[50:53], v[172:175], v[180:183], v[50:53]
	v_mfma_f32_16x16x32_bf16 v[34:37], v[168:171], v[184:187], v[34:37]
	v_mfma_f32_16x16x32_bf16 v[34:37], v[172:175], v[188:191], v[34:37]
	v_mfma_f32_16x16x32_bf16 v[38:41], v[154:157], v[184:187], v[38:41]
	v_mfma_f32_16x16x32_bf16 v[38:41], v[164:167], v[188:191], v[38:41]
	v_mfma_f32_16x16x32_bf16 v[42:45], v[138:141], v[184:187], v[42:45]
	v_mfma_f32_16x16x32_bf16 v[42:45], v[142:145], v[188:191], v[42:45]
	v_mfma_f32_16x16x32_bf16 v[46:49], v[130:133], v[184:187], v[46:49]
	v_mfma_f32_16x16x32_bf16 v[46:49], v[134:137], v[188:191], v[46:49]
	v_mfma_f32_16x16x32_bf16 v[30:33], v[130:133], v[192:195], v[30:33]
	v_mfma_f32_16x16x32_bf16 v[30:33], v[134:137], v[196:199], v[30:33]
	v_mfma_f32_16x16x32_bf16 v[26:29], v[138:141], v[192:195], v[26:29]
	v_mfma_f32_16x16x32_bf16 v[26:29], v[142:145], v[196:199], v[26:29]
	v_mfma_f32_16x16x32_bf16 v[22:25], v[154:157], v[192:195], v[22:25]
	v_mfma_f32_16x16x32_bf16 v[22:25], v[164:167], v[196:199], v[22:25]
	v_mfma_f32_16x16x32_bf16 v[18:21], v[168:171], v[192:195], v[18:21]
	v_mfma_f32_16x16x32_bf16 v[18:21], v[172:175], v[196:199], v[18:21]
	v_mfma_f32_16x16x32_bf16 v[2:5], v[168:171], v[200:203], v[2:5]
	v_mfma_f32_16x16x32_bf16 v[2:5], v[172:175], v[204:207], v[2:5]
	v_mfma_f32_16x16x32_bf16 v[6:9], v[154:157], v[200:203], v[6:9]
	v_mfma_f32_16x16x32_bf16 v[6:9], v[164:167], v[204:207], v[6:9]
	v_mfma_f32_16x16x32_bf16 v[10:13], v[138:141], v[200:203], v[10:13]
	v_mfma_f32_16x16x32_bf16 v[10:13], v[142:145], v[204:207], v[10:13]
	v_mfma_f32_16x16x32_bf16 v[14:17], v[130:133], v[200:203], v[14:17]
	v_mfma_f32_16x16x32_bf16 v[14:17], v[134:137], v[204:207], v[14:17]
	s_setprio 0
	s_barrier
	s_nop 7
	s_nop 7
	s_nop 7
	s_add_i32 s89, s89, 2
	s_cmp_ge_i32 s89, s63
	s_mov_b32 s6, s90
	s_cbranch_scc0 .LBB0_1020
	s_and_b64 vcc, exec, s[54:55]
	s_cbranch_vccz .LBB0_1023

.LBB0_1035:
	ds_read_b128 v[140:143], v134
	ds_read_b128 v[148:151], v134 offset:1024
	ds_read_b128 v[152:155], v134 offset:2048
	ds_read_b128 v[156:159], v134 offset:3072
	ds_read_b128 v[160:163], v135
	ds_read_b128 v[164:167], v135 offset:1024
	ds_read_b128 v[168:171], v135 offset:2048
	ds_read_b128 v[172:175], v135 offset:3072
	s_add_i32 s73, s70, 0xfffb8080
	s_cmp_eq_u32 s53, s72
	s_cselect_b32 s73, s68, s73
	s_cselect_b32 s75, s69, s71
	s_add_i32 s74, s73, 0x80
	s_add_i32 s76, s70, 0xfffe8000
	s_mov_b32 m0, s54
	ds_read_b128 v[176:179], v136
	ds_read_b128 v[180:183], v136 offset:1024
	ds_read_b128 v[184:187], v136 offset:2048
	ds_read_b128 v[188:191], v136 offset:3072
	ds_read_b128 v[192:195], v136 offset:4096
	ds_read_b128 v[196:199], v136 offset:5120
	ds_read_b128 v[200:203], v136 offset:6144
	ds_read_b128 v[204:207], v136 offset:7168
	buffer_load_dwordx4 v132, s[12:15], s76 offen lds
	s_mov_b32 m0, s55
	s_nop 0
	buffer_load_dwordx4 v132, s[12:15], s70 offen lds
	s_waitcnt vmcnt(8)
	s_waitcnt lgkmcnt(0)
	s_setprio 1
	v_mfma_f32_16x16x32_bf16 v[126:129], v[140:143], v[176:179], v[126:129]
	s_barrier
	v_mfma_f32_16x16x32_bf16 v[126:129], v[148:151], v[180:183], v[126:129]
	v_mfma_f32_16x16x32_bf16 v[122:125], v[152:155], v[176:179], v[122:125]
	v_mfma_f32_16x16x32_bf16 v[122:125], v[156:159], v[180:183], v[122:125]
	v_mfma_f32_16x16x32_bf16 v[118:121], v[160:163], v[176:179], v[118:121]
	v_mfma_f32_16x16x32_bf16 v[118:121], v[164:167], v[180:183], v[118:121]
	v_mfma_f32_16x16x32_bf16 v[114:117], v[168:171], v[176:179], v[114:117]
	v_mfma_f32_16x16x32_bf16 v[114:117], v[172:175], v[180:183], v[114:117]
	v_mfma_f32_16x16x32_bf16 v[98:101], v[168:171], v[184:187], v[98:101]
	v_mfma_f32_16x16x32_bf16 v[98:101], v[172:175], v[188:191], v[98:101]
	v_mfma_f32_16x16x32_bf16 v[102:105], v[160:163], v[184:187], v[102:105]
	v_mfma_f32_16x16x32_bf16 v[102:105], v[164:167], v[188:191], v[102:105]
	v_mfma_f32_16x16x32_bf16 v[106:109], v[152:155], v[184:187], v[106:109]
	v_mfma_f32_16x16x32_bf16 v[106:109], v[156:159], v[188:191], v[106:109]
	v_mfma_f32_16x16x32_bf16 v[110:113], v[140:143], v[184:187], v[110:113]
	v_mfma_f32_16x16x32_bf16 v[110:113], v[148:151], v[188:191], v[110:113]
	v_mfma_f32_16x16x32_bf16 v[94:97], v[140:143], v[192:195], v[94:97]
	v_mfma_f32_16x16x32_bf16 v[94:97], v[148:151], v[196:199], v[94:97]
	v_mfma_f32_16x16x32_bf16 v[90:93], v[152:155], v[192:195], v[90:93]
	v_mfma_f32_16x16x32_bf16 v[90:93], v[156:159], v[196:199], v[90:93]
	v_mfma_f32_16x16x32_bf16 v[86:89], v[160:163], v[192:195], v[86:89]
	v_mfma_f32_16x16x32_bf16 v[86:89], v[164:167], v[196:199], v[86:89]
	v_mfma_f32_16x16x32_bf16 v[82:85], v[168:171], v[192:195], v[82:85]
	v_mfma_f32_16x16x32_bf16 v[82:85], v[172:175], v[196:199], v[82:85]
	v_mfma_f32_16x16x32_bf16 v[66:69], v[168:171], v[200:203], v[66:69]
	v_mfma_f32_16x16x32_bf16 v[66:69], v[172:175], v[204:207], v[66:69]
	v_mfma_f32_16x16x32_bf16 v[70:73], v[160:163], v[200:203], v[70:73]
	v_mfma_f32_16x16x32_bf16 v[70:73], v[164:167], v[204:207], v[70:73]
	v_mfma_f32_16x16x32_bf16 v[74:77], v[152:155], v[200:203], v[74:77]
	v_mfma_f32_16x16x32_bf16 v[74:77], v[156:159], v[204:207], v[74:77]
	v_mfma_f32_16x16x32_bf16 v[78:81], v[140:143], v[200:203], v[78:81]
	v_mfma_f32_16x16x32_bf16 v[78:81], v[148:151], v[204:207], v[78:81]
	s_setprio 0
	s_barrier
	s_mov_b32 m0, s30
	ds_read_b128 v[176:179], v136 offset:16384
	ds_read_b128 v[180:183], v136 offset:17408
	ds_read_b128 v[184:187], v136 offset:18432
	ds_read_b128 v[188:191], v136 offset:19456
	ds_read_b128 v[192:195], v136 offset:20480
	ds_read_b128 v[196:199], v136 offset:21504
	ds_read_b128 v[200:203], v136 offset:22528
	ds_read_b128 v[204:207], v136 offset:23552
	buffer_load_dwordx4 v133, s[16:19], s75 offen lds
	s_add_i32 s76, s75, 0x200000
	s_mov_b32 m0, s31
	s_nop 0
	buffer_load_dwordx4 v133, s[16:19], s76 offen lds
	s_add_i32 s76, s75, 0x400000
	s_mov_b32 m0, s35
	s_nop 0
	buffer_load_dwordx4 v133, s[16:19], s76 offen lds
	s_add_i32 s76, s75, 0x600000
	s_mov_b32 m0, s42
	s_nop 0
	buffer_load_dwordx4 v133, s[16:19], s76 offen lds
	s_mov_b32 m0, s27
	s_add_i32 s76, s73, 0x18000
	buffer_load_dwordx4 v132, s[12:15], s73 offen lds
	s_mov_b32 m0, s43
	s_nop 0
	buffer_load_dwordx4 v132, s[12:15], s76 offen lds
	s_waitcnt vmcnt(8)
	s_waitcnt lgkmcnt(0)
	s_setprio 1
	v_mfma_f32_16x16x32_bf16 v[62:65], v[140:143], v[176:179], v[62:65]
	s_barrier
	v_mfma_f32_16x16x32_bf16 v[62:65], v[148:151], v[180:183], v[62:65]
	v_mfma_f32_16x16x32_bf16 v[58:61], v[152:155], v[176:179], v[58:61]
	v_mfma_f32_16x16x32_bf16 v[58:61], v[156:159], v[180:183], v[58:61]
	v_mfma_f32_16x16x32_bf16 v[54:57], v[160:163], v[176:179], v[54:57]
	v_mfma_f32_16x16x32_bf16 v[54:57], v[164:167], v[180:183], v[54:57]
	v_mfma_f32_16x16x32_bf16 v[50:53], v[168:171], v[176:179], v[50:53]
	v_mfma_f32_16x16x32_bf16 v[50:53], v[172:175], v[180:183], v[50:53]
	v_mfma_f32_16x16x32_bf16 v[34:37], v[168:171], v[184:187], v[34:37]
	v_mfma_f32_16x16x32_bf16 v[34:37], v[172:175], v[188:191], v[34:37]
	v_mfma_f32_16x16x32_bf16 v[38:41], v[160:163], v[184:187], v[38:41]
	v_mfma_f32_16x16x32_bf16 v[38:41], v[164:167], v[188:191], v[38:41]
	v_mfma_f32_16x16x32_bf16 v[42:45], v[152:155], v[184:187], v[42:45]
	v_mfma_f32_16x16x32_bf16 v[42:45], v[156:159], v[188:191], v[42:45]
	v_mfma_f32_16x16x32_bf16 v[46:49], v[140:143], v[184:187], v[46:49]
	v_mfma_f32_16x16x32_bf16 v[46:49], v[148:151], v[188:191], v[46:49]
	v_mfma_f32_16x16x32_bf16 v[30:33], v[140:143], v[192:195], v[30:33]
	v_mfma_f32_16x16x32_bf16 v[30:33], v[148:151], v[196:199], v[30:33]
	v_mfma_f32_16x16x32_bf16 v[26:29], v[152:155], v[192:195], v[26:29]
	v_mfma_f32_16x16x32_bf16 v[26:29], v[156:159], v[196:199], v[26:29]
	v_mfma_f32_16x16x32_bf16 v[22:25], v[160:163], v[192:195], v[22:25]
	v_mfma_f32_16x16x32_bf16 v[22:25], v[164:167], v[196:199], v[22:25]
	v_mfma_f32_16x16x32_bf16 v[18:21], v[168:171], v[192:195], v[18:21]
	v_mfma_f32_16x16x32_bf16 v[18:21], v[172:175], v[196:199], v[18:21]
	v_mfma_f32_16x16x32_bf16 v[2:5], v[168:171], v[200:203], v[2:5]
	v_mfma_f32_16x16x32_bf16 v[2:5], v[172:175], v[204:207], v[2:5]
	v_mfma_f32_16x16x32_bf16 v[6:9], v[160:163], v[200:203], v[6:9]
	v_mfma_f32_16x16x32_bf16 v[6:9], v[164:167], v[204:207], v[6:9]
	v_mfma_f32_16x16x32_bf16 v[10:13], v[152:155], v[200:203], v[10:13]
	v_mfma_f32_16x16x32_bf16 v[10:13], v[156:159], v[204:207], v[10:13]
	v_mfma_f32_16x16x32_bf16 v[14:17], v[140:143], v[200:203], v[14:17]
	v_mfma_f32_16x16x32_bf16 v[14:17], v[148:151], v[204:207], v[14:17]
	s_setprio 0
	s_barrier
	s_nop 7
	s_nop 7
	s_nop 7
	ds_read_b128 v[140:143], v137
	ds_read_b128 v[148:151], v137 offset:1024
	ds_read_b128 v[152:155], v137 offset:2048
	ds_read_b128 v[156:159], v137 offset:3072
	ds_read_b128 v[160:163], v138
	ds_read_b128 v[164:167], v138 offset:1024
	ds_read_b128 v[168:171], v138 offset:2048
	ds_read_b128 v[172:175], v138 offset:3072
	s_mov_b32 m0, s44
	s_add_i32 s76, s73, 0x30000
	ds_read_b128 v[176:179], v136 offset:32768
	ds_read_b128 v[180:183], v136 offset:33792
	ds_read_b128 v[184:187], v136 offset:34816
	ds_read_b128 v[188:191], v136 offset:35840
	ds_read_b128 v[192:195], v136 offset:36864
	ds_read_b128 v[196:199], v136 offset:37888
	ds_read_b128 v[200:203], v136 offset:38912
	ds_read_b128 v[204:207], v136 offset:39936
	buffer_load_dwordx4 v132, s[12:15], s76 offen lds
	s_add_i32 s76, s73, 0x48000
	s_mov_b32 m0, s45
	s_nop 0
	buffer_load_dwordx4 v132, s[12:15], s76 offen lds
	s_waitcnt vmcnt(8)
	s_waitcnt lgkmcnt(0)
	s_setprio 1
	v_mfma_f32_16x16x32_bf16 v[126:129], v[140:143], v[176:179], v[126:129]
	s_barrier
	v_mfma_f32_16x16x32_bf16 v[126:129], v[148:151], v[180:183], v[126:129]
	v_mfma_f32_16x16x32_bf16 v[122:125], v[152:155], v[176:179], v[122:125]
	v_mfma_f32_16x16x32_bf16 v[122:125], v[156:159], v[180:183], v[122:125]
	v_mfma_f32_16x16x32_bf16 v[118:121], v[160:163], v[176:179], v[118:121]
	v_mfma_f32_16x16x32_bf16 v[118:121], v[164:167], v[180:183], v[118:121]
	v_mfma_f32_16x16x32_bf16 v[114:117], v[168:171], v[176:179], v[114:117]
	v_mfma_f32_16x16x32_bf16 v[114:117], v[172:175], v[180:183], v[114:117]
	v_mfma_f32_16x16x32_bf16 v[98:101], v[168:171], v[184:187], v[98:101]
	v_mfma_f32_16x16x32_bf16 v[98:101], v[172:175], v[188:191], v[98:101]
	v_mfma_f32_16x16x32_bf16 v[102:105], v[160:163], v[184:187], v[102:105]
	v_mfma_f32_16x16x32_bf16 v[102:105], v[164:167], v[188:191], v[102:105]
	v_mfma_f32_16x16x32_bf16 v[106:109], v[152:155], v[184:187], v[106:109]
	v_mfma_f32_16x16x32_bf16 v[106:109], v[156:159], v[188:191], v[106:109]
	v_mfma_f32_16x16x32_bf16 v[110:113], v[140:143], v[184:187], v[110:113]
	v_mfma_f32_16x16x32_bf16 v[110:113], v[148:151], v[188:191], v[110:113]
	v_mfma_f32_16x16x32_bf16 v[94:97], v[140:143], v[192:195], v[94:97]
	v_mfma_f32_16x16x32_bf16 v[94:97], v[148:151], v[196:199], v[94:97]
	v_mfma_f32_16x16x32_bf16 v[90:93], v[152:155], v[192:195], v[90:93]
	v_mfma_f32_16x16x32_bf16 v[90:93], v[156:159], v[196:199], v[90:93]
	v_mfma_f32_16x16x32_bf16 v[86:89], v[160:163], v[192:195], v[86:89]
	v_mfma_f32_16x16x32_bf16 v[86:89], v[164:167], v[196:199], v[86:89]
	v_mfma_f32_16x16x32_bf16 v[82:85], v[168:171], v[192:195], v[82:85]
	v_mfma_f32_16x16x32_bf16 v[82:85], v[172:175], v[196:199], v[82:85]
	v_mfma_f32_16x16x32_bf16 v[66:69], v[168:171], v[200:203], v[66:69]
	v_mfma_f32_16x16x32_bf16 v[66:69], v[172:175], v[204:207], v[66:69]
	v_mfma_f32_16x16x32_bf16 v[70:73], v[160:163], v[200:203], v[70:73]
	v_mfma_f32_16x16x32_bf16 v[70:73], v[164:167], v[204:207], v[70:73]
	v_mfma_f32_16x16x32_bf16 v[74:77], v[152:155], v[200:203], v[74:77]
	v_mfma_f32_16x16x32_bf16 v[74:77], v[156:159], v[204:207], v[74:77]
	v_mfma_f32_16x16x32_bf16 v[78:81], v[140:143], v[200:203], v[78:81]
	v_mfma_f32_16x16x32_bf16 v[78:81], v[148:151], v[204:207], v[78:81]
	s_setprio 0
	s_barrier
	s_mov_b32 m0, s46
	s_add_i32 s76, s75, 0x80
	ds_read_b128 v[176:179], v136 offset:49152
	ds_read_b128 v[180:183], v136 offset:50176
	ds_read_b128 v[184:187], v136 offset:51200
	ds_read_b128 v[188:191], v136 offset:52224
	ds_read_b128 v[192:195], v136 offset:53248
	ds_read_b128 v[196:199], v136 offset:54272
	ds_read_b128 v[200:203], v136 offset:55296
	ds_read_b128 v[204:207], v136 offset:56320
	buffer_load_dwordx4 v133, s[16:19], s76 offen lds
	s_add_i32 s76, s75, 0x200080
	s_mov_b32 m0, s47
	s_add_i32 s73, s73, 0x18080
	buffer_load_dwordx4 v133, s[16:19], s76 offen lds
	s_add_i32 s76, s75, 0x400080
	s_mov_b32 m0, s50
	s_add_i32 s75, s75, 0x600080
	buffer_load_dwordx4 v133, s[16:19], s76 offen lds
	s_mov_b32 m0, s51
	s_nop 0
	buffer_load_dwordx4 v133, s[16:19], s75 offen lds
	s_mov_b32 m0, s48
	s_nop 0
	buffer_load_dwordx4 v132, s[12:15], s74 offen lds
	s_mov_b32 m0, s49
	s_nop 0
	buffer_load_dwordx4 v132, s[12:15], s73 offen lds
	s_waitcnt vmcnt(8)
	s_waitcnt lgkmcnt(0)
	s_setprio 1
	v_mfma_f32_16x16x32_bf16 v[62:65], v[140:143], v[176:179], v[62:65]
	s_barrier
	v_mfma_f32_16x16x32_bf16 v[62:65], v[148:151], v[180:183], v[62:65]
	v_mfma_f32_16x16x32_bf16 v[58:61], v[152:155], v[176:179], v[58:61]
	v_mfma_f32_16x16x32_bf16 v[58:61], v[156:159], v[180:183], v[58:61]
	v_mfma_f32_16x16x32_bf16 v[54:57], v[160:163], v[176:179], v[54:57]
	v_mfma_f32_16x16x32_bf16 v[54:57], v[164:167], v[180:183], v[54:57]
	v_mfma_f32_16x16x32_bf16 v[50:53], v[168:171], v[176:179], v[50:53]
	v_mfma_f32_16x16x32_bf16 v[50:53], v[172:175], v[180:183], v[50:53]
	v_mfma_f32_16x16x32_bf16 v[34:37], v[168:171], v[184:187], v[34:37]
	v_mfma_f32_16x16x32_bf16 v[34:37], v[172:175], v[188:191], v[34:37]
	v_mfma_f32_16x16x32_bf16 v[38:41], v[160:163], v[184:187], v[38:41]
	v_mfma_f32_16x16x32_bf16 v[38:41], v[164:167], v[188:191], v[38:41]
	v_mfma_f32_16x16x32_bf16 v[42:45], v[152:155], v[184:187], v[42:45]
	v_mfma_f32_16x16x32_bf16 v[42:45], v[156:159], v[188:191], v[42:45]
	v_mfma_f32_16x16x32_bf16 v[46:49], v[140:143], v[184:187], v[46:49]
	v_mfma_f32_16x16x32_bf16 v[46:49], v[148:151], v[188:191], v[46:49]
	v_mfma_f32_16x16x32_bf16 v[30:33], v[140:143], v[192:195], v[30:33]
	v_mfma_f32_16x16x32_bf16 v[30:33], v[148:151], v[196:199], v[30:33]
	v_mfma_f32_16x16x32_bf16 v[26:29], v[152:155], v[192:195], v[26:29]
	v_mfma_f32_16x16x32_bf16 v[26:29], v[156:159], v[196:199], v[26:29]
	v_mfma_f32_16x16x32_bf16 v[22:25], v[160:163], v[192:195], v[22:25]
	v_mfma_f32_16x16x32_bf16 v[22:25], v[164:167], v[196:199], v[22:25]
	v_mfma_f32_16x16x32_bf16 v[18:21], v[168:171], v[192:195], v[18:21]
	v_mfma_f32_16x16x32_bf16 v[18:21], v[172:175], v[196:199], v[18:21]
	v_mfma_f32_16x16x32_bf16 v[2:5], v[168:171], v[200:203], v[2:5]
	v_mfma_f32_16x16x32_bf16 v[2:5], v[172:175], v[204:207], v[2:5]
	v_mfma_f32_16x16x32_bf16 v[6:9], v[160:163], v[200:203], v[6:9]
	v_mfma_f32_16x16x32_bf16 v[6:9], v[164:167], v[204:207], v[6:9]
	v_mfma_f32_16x16x32_bf16 v[10:13], v[152:155], v[200:203], v[10:13]
	v_mfma_f32_16x16x32_bf16 v[10:13], v[156:159], v[204:207], v[10:13]
	v_mfma_f32_16x16x32_bf16 v[14:17], v[140:143], v[200:203], v[14:17]
	v_mfma_f32_16x16x32_bf16 v[14:17], v[148:151], v[204:207], v[14:17]
	s_setprio 0
	s_barrier
	s_nop 7
	s_nop 7
	s_nop 7
	s_add_i32 s72, s72, 2
	s_addk_i32 s70, 0x100
	s_addk_i32 s71, 0x100
	s_cmp_ge_i32 s72, s21
	s_cbranch_scc0 .LBB0_1035

.LBB0_1050:
	ds_read_b128 v[132:135], v142
	ds_read_b128 v[136:139], v142 offset:1024
	ds_read_b128 v[148:151], v142 offset:2048
	ds_read_b128 v[152:155], v142 offset:3072
	ds_read_b128 v[156:159], v143
	ds_read_b128 v[160:163], v143 offset:1024
	ds_read_b128 v[164:167], v143 offset:2048
	ds_read_b128 v[168:171], v143 offset:3072
	s_add_i32 s18, s61, 0xfff40080
	s_cmp_eq_u32 s54, s62
	s_cselect_b32 s64, s35, s18
	s_add_i32 s63, s64, 0x80
	s_add_i32 s18, s61, 0xfffc0000
	s_mov_b32 m0, s55
	ds_read_b128 v[172:175], v144
	ds_read_b128 v[176:179], v144 offset:1024
	ds_read_b128 v[180:183], v144 offset:2048
	ds_read_b128 v[184:187], v144 offset:3072
	ds_read_b128 v[188:191], v144 offset:4096
	ds_read_b128 v[192:195], v144 offset:5120
	ds_read_b128 v[196:199], v144 offset:6144
	ds_read_b128 v[200:203], v144 offset:7168
	buffer_load_dwordx4 v140, s[12:15], s18 offen lds
	s_mov_b32 m0, s56
	s_nop 0
	buffer_load_dwordx4 v140, s[12:15], s61 offen lds
	s_waitcnt vmcnt(8)
	s_waitcnt lgkmcnt(0)
	s_setprio 1
	v_mfma_f32_16x16x32_bf16 v[126:129], v[132:135], v[172:175], v[126:129]
	s_barrier
	v_mfma_f32_16x16x32_bf16 v[126:129], v[136:139], v[176:179], v[126:129]
	v_mfma_f32_16x16x32_bf16 v[122:125], v[148:151], v[172:175], v[122:125]
	v_mfma_f32_16x16x32_bf16 v[122:125], v[152:155], v[176:179], v[122:125]
	v_mfma_f32_16x16x32_bf16 v[118:121], v[156:159], v[172:175], v[118:121]
	v_mfma_f32_16x16x32_bf16 v[118:121], v[160:163], v[176:179], v[118:121]
	v_mfma_f32_16x16x32_bf16 v[114:117], v[164:167], v[172:175], v[114:117]
	v_mfma_f32_16x16x32_bf16 v[114:117], v[168:171], v[176:179], v[114:117]
	v_mfma_f32_16x16x32_bf16 v[98:101], v[164:167], v[180:183], v[98:101]
	v_mfma_f32_16x16x32_bf16 v[98:101], v[168:171], v[184:187], v[98:101]
	v_mfma_f32_16x16x32_bf16 v[102:105], v[156:159], v[180:183], v[102:105]
	v_mfma_f32_16x16x32_bf16 v[102:105], v[160:163], v[184:187], v[102:105]
	v_mfma_f32_16x16x32_bf16 v[106:109], v[148:151], v[180:183], v[106:109]
	v_mfma_f32_16x16x32_bf16 v[106:109], v[152:155], v[184:187], v[106:109]
	v_mfma_f32_16x16x32_bf16 v[110:113], v[132:135], v[180:183], v[110:113]
	v_mfma_f32_16x16x32_bf16 v[110:113], v[136:139], v[184:187], v[110:113]
	v_mfma_f32_16x16x32_bf16 v[94:97], v[132:135], v[188:191], v[94:97]
	v_mfma_f32_16x16x32_bf16 v[94:97], v[136:139], v[192:195], v[94:97]
	v_mfma_f32_16x16x32_bf16 v[90:93], v[148:151], v[188:191], v[90:93]
	v_mfma_f32_16x16x32_bf16 v[90:93], v[152:155], v[192:195], v[90:93]
	v_mfma_f32_16x16x32_bf16 v[86:89], v[156:159], v[188:191], v[86:89]
	v_mfma_f32_16x16x32_bf16 v[86:89], v[160:163], v[192:195], v[86:89]
	v_mfma_f32_16x16x32_bf16 v[82:85], v[164:167], v[188:191], v[82:85]
	v_mfma_f32_16x16x32_bf16 v[82:85], v[168:171], v[192:195], v[82:85]
	v_mfma_f32_16x16x32_bf16 v[66:69], v[164:167], v[196:199], v[66:69]
	v_mfma_f32_16x16x32_bf16 v[66:69], v[168:171], v[200:203], v[66:69]
	v_mfma_f32_16x16x32_bf16 v[70:73], v[156:159], v[196:199], v[70:73]
	v_mfma_f32_16x16x32_bf16 v[70:73], v[160:163], v[200:203], v[70:73]
	v_mfma_f32_16x16x32_bf16 v[74:77], v[148:151], v[196:199], v[74:77]
	v_mfma_f32_16x16x32_bf16 v[74:77], v[152:155], v[200:203], v[74:77]
	v_mfma_f32_16x16x32_bf16 v[78:81], v[132:135], v[196:199], v[78:81]
	v_mfma_f32_16x16x32_bf16 v[78:81], v[136:139], v[200:203], v[78:81]
	s_setprio 0
	s_barrier
	s_mov_b32 m0, s25
	s_mov_b32 s18, s14
	s_mov_b32 s19, s15
	ds_read_b128 v[172:175], v144 offset:16384
	ds_read_b128 v[176:179], v144 offset:17408
	ds_read_b128 v[180:183], v144 offset:18432
	ds_read_b128 v[184:187], v144 offset:19456
	ds_read_b128 v[188:191], v144 offset:20480
	ds_read_b128 v[192:195], v144 offset:21504
	ds_read_b128 v[196:199], v144 offset:22528
	ds_read_b128 v[200:203], v144 offset:23552
	buffer_load_dwordx4 v141, s[16:19], s64 offen lds
	s_add_i32 s65, s64, 0x40000
	s_mov_b32 m0, s27
	s_add_i32 s66, s64, 0x80000
	buffer_load_dwordx4 v141, s[16:19], s65 offen lds
	s_mov_b32 m0, s30
	s_add_i32 s67, s64, 0xc0000
	buffer_load_dwordx4 v141, s[16:19], s66 offen lds
	s_mov_b32 m0, s31
	s_nop 0
	buffer_load_dwordx4 v141, s[16:19], s67 offen lds
	s_mov_b32 m0, s21
	s_nop 0
	buffer_load_dwordx4 v140, s[12:15], s64 offen lds
	s_mov_b32 m0, s38
	s_nop 0
	buffer_load_dwordx4 v140, s[12:15], s65 offen lds
	s_waitcnt vmcnt(8)
	s_waitcnt lgkmcnt(0)
	s_setprio 1
	v_mfma_f32_16x16x32_bf16 v[62:65], v[132:135], v[172:175], v[62:65]
	s_barrier
	v_mfma_f32_16x16x32_bf16 v[62:65], v[136:139], v[176:179], v[62:65]
	v_mfma_f32_16x16x32_bf16 v[58:61], v[148:151], v[172:175], v[58:61]
	v_mfma_f32_16x16x32_bf16 v[58:61], v[152:155], v[176:179], v[58:61]
	v_mfma_f32_16x16x32_bf16 v[54:57], v[156:159], v[172:175], v[54:57]
	v_mfma_f32_16x16x32_bf16 v[54:57], v[160:163], v[176:179], v[54:57]
	v_mfma_f32_16x16x32_bf16 v[50:53], v[164:167], v[172:175], v[50:53]
	v_mfma_f32_16x16x32_bf16 v[50:53], v[168:171], v[176:179], v[50:53]
	v_mfma_f32_16x16x32_bf16 v[34:37], v[164:167], v[180:183], v[34:37]
	v_mfma_f32_16x16x32_bf16 v[34:37], v[168:171], v[184:187], v[34:37]
	v_mfma_f32_16x16x32_bf16 v[38:41], v[156:159], v[180:183], v[38:41]
	v_mfma_f32_16x16x32_bf16 v[38:41], v[160:163], v[184:187], v[38:41]
	v_mfma_f32_16x16x32_bf16 v[42:45], v[148:151], v[180:183], v[42:45]
	v_mfma_f32_16x16x32_bf16 v[42:45], v[152:155], v[184:187], v[42:45]
	v_mfma_f32_16x16x32_bf16 v[46:49], v[132:135], v[180:183], v[46:49]
	v_mfma_f32_16x16x32_bf16 v[46:49], v[136:139], v[184:187], v[46:49]
	v_mfma_f32_16x16x32_bf16 v[30:33], v[132:135], v[188:191], v[30:33]
	v_mfma_f32_16x16x32_bf16 v[30:33], v[136:139], v[192:195], v[30:33]
	v_mfma_f32_16x16x32_bf16 v[26:29], v[148:151], v[188:191], v[26:29]
	v_mfma_f32_16x16x32_bf16 v[26:29], v[152:155], v[192:195], v[26:29]
	v_mfma_f32_16x16x32_bf16 v[22:25], v[156:159], v[188:191], v[22:25]
	v_mfma_f32_16x16x32_bf16 v[22:25], v[160:163], v[192:195], v[22:25]
	v_mfma_f32_16x16x32_bf16 v[18:21], v[164:167], v[188:191], v[18:21]
	v_mfma_f32_16x16x32_bf16 v[18:21], v[168:171], v[192:195], v[18:21]
	v_mfma_f32_16x16x32_bf16 v[2:5], v[164:167], v[196:199], v[2:5]
	v_mfma_f32_16x16x32_bf16 v[2:5], v[168:171], v[200:203], v[2:5]
	v_mfma_f32_16x16x32_bf16 v[6:9], v[156:159], v[196:199], v[6:9]
	v_mfma_f32_16x16x32_bf16 v[6:9], v[160:163], v[200:203], v[6:9]
	v_mfma_f32_16x16x32_bf16 v[10:13], v[148:151], v[196:199], v[10:13]
	v_mfma_f32_16x16x32_bf16 v[10:13], v[152:155], v[200:203], v[10:13]
	v_mfma_f32_16x16x32_bf16 v[14:17], v[132:135], v[196:199], v[14:17]
	v_mfma_f32_16x16x32_bf16 v[14:17], v[136:139], v[200:203], v[14:17]
	s_setprio 0
	s_barrier
	s_nop 7
	s_nop 7
	s_nop 7
	ds_read_b128 v[132:135], v145
	ds_read_b128 v[136:139], v145 offset:1024
	ds_read_b128 v[148:151], v145 offset:2048
	ds_read_b128 v[152:155], v145 offset:3072
	ds_read_b128 v[156:159], v147
	ds_read_b128 v[160:163], v147 offset:1024
	ds_read_b128 v[164:167], v147 offset:2048
	ds_read_b128 v[168:171], v147 offset:3072
	s_mov_b32 m0, s39
	ds_read_b128 v[172:175], v144 offset:32768
	ds_read_b128 v[176:179], v144 offset:33792
	ds_read_b128 v[180:183], v144 offset:34816
	ds_read_b128 v[184:187], v144 offset:35840
	ds_read_b128 v[188:191], v144 offset:36864
	ds_read_b128 v[192:195], v144 offset:37888
	ds_read_b128 v[196:199], v144 offset:38912
	ds_read_b128 v[200:203], v144 offset:39936
	buffer_load_dwordx4 v140, s[12:15], s66 offen lds
	s_mov_b32 m0, s40
	s_nop 0
	buffer_load_dwordx4 v140, s[12:15], s67 offen lds
	s_waitcnt vmcnt(8)
	s_waitcnt lgkmcnt(0)
	s_setprio 1
	v_mfma_f32_16x16x32_bf16 v[126:129], v[132:135], v[172:175], v[126:129]
	s_barrier
	v_mfma_f32_16x16x32_bf16 v[126:129], v[136:139], v[176:179], v[126:129]
	v_mfma_f32_16x16x32_bf16 v[122:125], v[148:151], v[172:175], v[122:125]
	v_mfma_f32_16x16x32_bf16 v[122:125], v[152:155], v[176:179], v[122:125]
	v_mfma_f32_16x16x32_bf16 v[118:121], v[156:159], v[172:175], v[118:121]
	v_mfma_f32_16x16x32_bf16 v[118:121], v[160:163], v[176:179], v[118:121]
	v_mfma_f32_16x16x32_bf16 v[114:117], v[164:167], v[172:175], v[114:117]
	v_mfma_f32_16x16x32_bf16 v[114:117], v[168:171], v[176:179], v[114:117]
	v_mfma_f32_16x16x32_bf16 v[98:101], v[164:167], v[180:183], v[98:101]
	v_mfma_f32_16x16x32_bf16 v[98:101], v[168:171], v[184:187], v[98:101]
	v_mfma_f32_16x16x32_bf16 v[102:105], v[156:159], v[180:183], v[102:105]
	v_mfma_f32_16x16x32_bf16 v[102:105], v[160:163], v[184:187], v[102:105]
	v_mfma_f32_16x16x32_bf16 v[106:109], v[148:151], v[180:183], v[106:109]
	v_mfma_f32_16x16x32_bf16 v[106:109], v[152:155], v[184:187], v[106:109]
	v_mfma_f32_16x16x32_bf16 v[110:113], v[132:135], v[180:183], v[110:113]
	v_mfma_f32_16x16x32_bf16 v[110:113], v[136:139], v[184:187], v[110:113]
	v_mfma_f32_16x16x32_bf16 v[94:97], v[132:135], v[188:191], v[94:97]
	v_mfma_f32_16x16x32_bf16 v[94:97], v[136:139], v[192:195], v[94:97]
	v_mfma_f32_16x16x32_bf16 v[90:93], v[148:151], v[188:191], v[90:93]
	v_mfma_f32_16x16x32_bf16 v[90:93], v[152:155], v[192:195], v[90:93]
	v_mfma_f32_16x16x32_bf16 v[86:89], v[156:159], v[188:191], v[86:89]
	v_mfma_f32_16x16x32_bf16 v[86:89], v[160:163], v[192:195], v[86:89]
	v_mfma_f32_16x16x32_bf16 v[82:85], v[164:167], v[188:191], v[82:85]
	v_mfma_f32_16x16x32_bf16 v[82:85], v[168:171], v[192:195], v[82:85]
	v_mfma_f32_16x16x32_bf16 v[66:69], v[164:167], v[196:199], v[66:69]
	v_mfma_f32_16x16x32_bf16 v[66:69], v[168:171], v[200:203], v[66:69]
	v_mfma_f32_16x16x32_bf16 v[70:73], v[156:159], v[196:199], v[70:73]
	v_mfma_f32_16x16x32_bf16 v[70:73], v[160:163], v[200:203], v[70:73]
	v_mfma_f32_16x16x32_bf16 v[74:77], v[148:151], v[196:199], v[74:77]
	v_mfma_f32_16x16x32_bf16 v[74:77], v[152:155], v[200:203], v[74:77]
	v_mfma_f32_16x16x32_bf16 v[78:81], v[132:135], v[196:199], v[78:81]
	v_mfma_f32_16x16x32_bf16 v[78:81], v[136:139], v[200:203], v[78:81]
	s_setprio 0
	s_barrier
	s_mov_b32 m0, s48
	ds_read_b128 v[172:175], v144 offset:49152
	ds_read_b128 v[176:179], v144 offset:50176
	ds_read_b128 v[180:183], v144 offset:51200
	ds_read_b128 v[184:187], v144 offset:52224
	ds_read_b128 v[188:191], v144 offset:53248
	ds_read_b128 v[192:195], v144 offset:54272
	ds_read_b128 v[196:199], v144 offset:55296
	ds_read_b128 v[200:203], v144 offset:56320
	buffer_load_dwordx4 v141, s[16:19], s63 offen lds
	s_add_i32 s65, s64, 0x40080
	s_mov_b32 m0, s49
	s_add_i32 s66, s64, 0x80080
	buffer_load_dwordx4 v141, s[16:19], s65 offen lds
	s_mov_b32 m0, s52
	s_add_i32 s64, s64, 0xc0080
	buffer_load_dwordx4 v141, s[16:19], s66 offen lds
	s_mov_b32 m0, s53
	s_nop 0
	buffer_load_dwordx4 v141, s[16:19], s64 offen lds
	s_mov_b32 m0, s50
	s_nop 0
	buffer_load_dwordx4 v140, s[12:15], s63 offen lds
	s_mov_b32 m0, s51
	s_nop 0
	buffer_load_dwordx4 v140, s[12:15], s65 offen lds
	s_waitcnt vmcnt(8)
	s_waitcnt lgkmcnt(0)
	s_setprio 1
	v_mfma_f32_16x16x32_bf16 v[62:65], v[132:135], v[172:175], v[62:65]
	s_barrier
	v_mfma_f32_16x16x32_bf16 v[62:65], v[136:139], v[176:179], v[62:65]
	v_mfma_f32_16x16x32_bf16 v[58:61], v[148:151], v[172:175], v[58:61]
	v_mfma_f32_16x16x32_bf16 v[58:61], v[152:155], v[176:179], v[58:61]
	v_mfma_f32_16x16x32_bf16 v[54:57], v[156:159], v[172:175], v[54:57]
	v_mfma_f32_16x16x32_bf16 v[54:57], v[160:163], v[176:179], v[54:57]
	v_mfma_f32_16x16x32_bf16 v[50:53], v[164:167], v[172:175], v[50:53]
	v_mfma_f32_16x16x32_bf16 v[50:53], v[168:171], v[176:179], v[50:53]
	v_mfma_f32_16x16x32_bf16 v[34:37], v[164:167], v[180:183], v[34:37]
	v_mfma_f32_16x16x32_bf16 v[34:37], v[168:171], v[184:187], v[34:37]
	v_mfma_f32_16x16x32_bf16 v[38:41], v[156:159], v[180:183], v[38:41]
	v_mfma_f32_16x16x32_bf16 v[38:41], v[160:163], v[184:187], v[38:41]
	v_mfma_f32_16x16x32_bf16 v[42:45], v[148:151], v[180:183], v[42:45]
	v_mfma_f32_16x16x32_bf16 v[42:45], v[152:155], v[184:187], v[42:45]
	v_mfma_f32_16x16x32_bf16 v[46:49], v[132:135], v[180:183], v[46:49]
	v_mfma_f32_16x16x32_bf16 v[46:49], v[136:139], v[184:187], v[46:49]
	v_mfma_f32_16x16x32_bf16 v[30:33], v[132:135], v[188:191], v[30:33]
	v_mfma_f32_16x16x32_bf16 v[30:33], v[136:139], v[192:195], v[30:33]
	v_mfma_f32_16x16x32_bf16 v[26:29], v[148:151], v[188:191], v[26:29]
	v_mfma_f32_16x16x32_bf16 v[26:29], v[152:155], v[192:195], v[26:29]
	v_mfma_f32_16x16x32_bf16 v[22:25], v[156:159], v[188:191], v[22:25]
	v_mfma_f32_16x16x32_bf16 v[22:25], v[160:163], v[192:195], v[22:25]
	v_mfma_f32_16x16x32_bf16 v[18:21], v[164:167], v[188:191], v[18:21]
	v_mfma_f32_16x16x32_bf16 v[18:21], v[168:171], v[192:195], v[18:21]
	v_mfma_f32_16x16x32_bf16 v[2:5], v[164:167], v[196:199], v[2:5]
	v_mfma_f32_16x16x32_bf16 v[2:5], v[168:171], v[200:203], v[2:5]
	v_mfma_f32_16x16x32_bf16 v[6:9], v[156:159], v[196:199], v[6:9]
	v_mfma_f32_16x16x32_bf16 v[6:9], v[160:163], v[200:203], v[6:9]
	v_mfma_f32_16x16x32_bf16 v[10:13], v[148:151], v[196:199], v[10:13]
	v_mfma_f32_16x16x32_bf16 v[10:13], v[152:155], v[200:203], v[10:13]
	v_mfma_f32_16x16x32_bf16 v[14:17], v[132:135], v[196:199], v[14:17]
	v_mfma_f32_16x16x32_bf16 v[14:17], v[136:139], v[200:203], v[14:17]
	s_setprio 0
	s_barrier
	s_nop 7
	s_nop 7
	s_nop 7
	s_add_i32 s62, s62, 2
	s_addk_i32 s61, 0x100
	s_cmp_ge_i32 s62, s3
	s_cbranch_scc0 .LBB0_1050

.LBB0_1181:
	v_add_u32_e32 v2, 0x10000, v232
	ds_read_b128 v[134:137], v2
	ds_read_b128 v[138:141], v2 offset:1024
	ds_read_b128 v[142:145], v2 offset:2048
	ds_read_b128 v[146:149], v2 offset:3072
	v_add_u32_e32 v2, 0x14000, v232
	ds_read_b128 v[150:153], v2
	ds_read_b128 v[154:157], v2 offset:1024
	ds_read_b128 v[158:161], v2 offset:2048
	ds_read_b128 v[162:165], v2 offset:3072
	s_add_i32 s50, s47, s90
	s_and_b64 s[18:19], exec, s[18:19]
	s_cselect_b32 s51, s88, s50
	s_add_i32 s50, s92, 0x80
	s_or_b32 s52, s51, 0x80
	s_add_i32 s18, s89, s93
	s_add_i32 s94, s94, 0x1bfffc80
	s_cmp_lt_u32 s91, 8
	s_cselect_b32 s18, s18, s94
	s_mov_b32 m0, s74
	s_add_i32 s19, s18, 0x80000
	ds_read_b128 v[166:169], v233
	ds_read_b128 v[170:173], v233 offset:1024
	ds_read_b128 v[174:177], v233 offset:2048
	ds_read_b128 v[178:181], v233 offset:3072
	ds_read_b128 v[182:185], v233 offset:4096
	ds_read_b128 v[186:189], v233 offset:5120
	ds_read_b128 v[190:193], v233 offset:6144
	ds_read_b128 v[194:197], v233 offset:7168
	buffer_load_dwordx4 v230, s[12:15], s19 offen lds
	s_add_i32 s18, s18, 0xc0000
	s_mov_b32 m0, s75
	s_nop 0
	buffer_load_dwordx4 v230, s[12:15], s18 offen lds
	s_waitcnt vmcnt(8)
	s_waitcnt lgkmcnt(0)
	s_setprio 1
	v_mfma_f32_16x16x32_bf16 v[130:133], v[134:137], v[166:169], v[130:133]
	s_barrier
	v_mfma_f32_16x16x32_bf16 v[130:133], v[138:141], v[170:173], v[130:133]
	v_mfma_f32_16x16x32_bf16 v[126:129], v[142:145], v[166:169], v[126:129]
	v_mfma_f32_16x16x32_bf16 v[126:129], v[146:149], v[170:173], v[126:129]
	v_mfma_f32_16x16x32_bf16 v[122:125], v[150:153], v[166:169], v[122:125]
	v_mfma_f32_16x16x32_bf16 v[122:125], v[154:157], v[170:173], v[122:125]
	v_mfma_f32_16x16x32_bf16 v[118:121], v[158:161], v[166:169], v[118:121]
	v_mfma_f32_16x16x32_bf16 v[118:121], v[162:165], v[170:173], v[118:121]
	v_mfma_f32_16x16x32_bf16 v[102:105], v[158:161], v[174:177], v[102:105]
	v_mfma_f32_16x16x32_bf16 v[102:105], v[162:165], v[178:181], v[102:105]
	v_mfma_f32_16x16x32_bf16 v[106:109], v[150:153], v[174:177], v[106:109]
	v_mfma_f32_16x16x32_bf16 v[106:109], v[154:157], v[178:181], v[106:109]
	v_mfma_f32_16x16x32_bf16 v[110:113], v[142:145], v[174:177], v[110:113]
	v_mfma_f32_16x16x32_bf16 v[110:113], v[146:149], v[178:181], v[110:113]
	v_mfma_f32_16x16x32_bf16 v[114:117], v[134:137], v[174:177], v[114:117]
	v_mfma_f32_16x16x32_bf16 v[114:117], v[138:141], v[178:181], v[114:117]
	v_mfma_f32_16x16x32_bf16 v[98:101], v[134:137], v[182:185], v[98:101]
	v_mfma_f32_16x16x32_bf16 v[98:101], v[138:141], v[186:189], v[98:101]
	v_mfma_f32_16x16x32_bf16 v[94:97], v[142:145], v[182:185], v[94:97]
	v_mfma_f32_16x16x32_bf16 v[94:97], v[146:149], v[186:189], v[94:97]
	v_mfma_f32_16x16x32_bf16 v[90:93], v[150:153], v[182:185], v[90:93]
	v_mfma_f32_16x16x32_bf16 v[90:93], v[154:157], v[186:189], v[90:93]
	v_mfma_f32_16x16x32_bf16 v[86:89], v[158:161], v[182:185], v[86:89]
	v_mfma_f32_16x16x32_bf16 v[86:89], v[162:165], v[186:189], v[86:89]
	v_mfma_f32_16x16x32_bf16 v[70:73], v[158:161], v[190:193], v[70:73]
	v_mfma_f32_16x16x32_bf16 v[70:73], v[162:165], v[194:197], v[70:73]
	v_mfma_f32_16x16x32_bf16 v[74:77], v[150:153], v[190:193], v[74:77]
	v_mfma_f32_16x16x32_bf16 v[74:77], v[154:157], v[194:197], v[74:77]
	v_mfma_f32_16x16x32_bf16 v[78:81], v[142:145], v[190:193], v[78:81]
	v_mfma_f32_16x16x32_bf16 v[78:81], v[146:149], v[194:197], v[78:81]
	v_mfma_f32_16x16x32_bf16 v[82:85], v[134:137], v[190:193], v[82:85]
	v_mfma_f32_16x16x32_bf16 v[82:85], v[138:141], v[194:197], v[82:85]
	s_setprio 0
	s_barrier
	s_mov_b32 m0, s27
	s_mov_b32 s18, s14
	s_mov_b32 s19, s15
	ds_read_b128 v[166:169], v233 offset:16384
	ds_read_b128 v[170:173], v233 offset:17408
	ds_read_b128 v[174:177], v233 offset:18432
	ds_read_b128 v[178:181], v233 offset:19456
	ds_read_b128 v[182:185], v233 offset:20480
	ds_read_b128 v[186:189], v233 offset:21504
	ds_read_b128 v[190:193], v233 offset:22528
	ds_read_b128 v[194:197], v233 offset:23552
	buffer_load_dwordx4 v231, s[16:19], s51 offen lds
	s_add_i32 s53, s51, 0x18000
	s_mov_b32 m0, s30
	s_nop 0
	buffer_load_dwordx4 v231, s[16:19], s53 offen lds
	s_add_i32 s53, s51, 0x30000
	s_mov_b32 m0, s31
	s_nop 0
	buffer_load_dwordx4 v231, s[16:19], s53 offen lds
	s_add_i32 s53, s51, 0x48000
	s_mov_b32 m0, s54
	s_nop 0
	buffer_load_dwordx4 v231, s[16:19], s53 offen lds
	s_mov_b32 m0, s25
	s_add_i32 s53, s92, 0x40000
	buffer_load_dwordx4 v230, s[12:15], s92 offen lds
	s_mov_b32 m0, s55
	s_nop 0
	buffer_load_dwordx4 v230, s[12:15], s53 offen lds
	s_waitcnt vmcnt(8)
	s_waitcnt lgkmcnt(0)
	s_setprio 1
	v_mfma_f32_16x16x32_bf16 v[66:69], v[134:137], v[166:169], v[66:69]
	s_barrier
	v_mfma_f32_16x16x32_bf16 v[62:65], v[142:145], v[166:169], v[62:65]
	v_mfma_f32_16x16x32_bf16 v[50:53], v[134:137], v[174:177], v[50:53]
	v_mfma_f32_16x16x32_bf16 v[46:49], v[142:145], v[174:177], v[46:49]
	v_mfma_f32_16x16x32_bf16 v[34:37], v[134:137], v[182:185], v[34:37]
	v_mfma_f32_16x16x32_bf16 v[30:33], v[142:145], v[182:185], v[30:33]
	v_mfma_f32_16x16x32_bf16 v[18:21], v[134:137], v[190:193], v[18:21]
	v_mfma_f32_16x16x32_bf16 v[14:17], v[142:145], v[190:193], v[14:17]
	v_mfma_f32_16x16x32_bf16 v[58:61], v[150:153], v[166:169], v[58:61]
	v_mfma_f32_16x16x32_bf16 v[54:57], v[158:161], v[166:169], v[54:57]
	v_mfma_f32_16x16x32_bf16 v[42:45], v[150:153], v[174:177], v[42:45]
	v_mfma_f32_16x16x32_bf16 v[38:41], v[158:161], v[174:177], v[38:41]
	v_mfma_f32_16x16x32_bf16 v[26:29], v[150:153], v[182:185], v[26:29]
	v_mfma_f32_16x16x32_bf16 v[22:25], v[158:161], v[182:185], v[22:25]
	v_mfma_f32_16x16x32_bf16 v[10:13], v[150:153], v[190:193], v[10:13]
	v_mfma_f32_16x16x32_bf16 v[4:7], v[158:161], v[190:193], v[6:9]
	v_mfma_f32_16x16x32_bf16 v[66:69], v[138:141], v[170:173], v[66:69]
	v_mfma_f32_16x16x32_bf16 v[62:65], v[146:149], v[170:173], v[62:65]
	v_mfma_f32_16x16x32_bf16 v[50:53], v[138:141], v[178:181], v[50:53]
	v_mfma_f32_16x16x32_bf16 v[46:49], v[146:149], v[178:181], v[46:49]
	v_mfma_f32_16x16x32_bf16 v[34:37], v[138:141], v[186:189], v[34:37]
	v_mfma_f32_16x16x32_bf16 v[30:33], v[146:149], v[186:189], v[30:33]
	v_mfma_f32_16x16x32_bf16 v[18:21], v[138:141], v[194:197], v[18:21]
	v_mfma_f32_16x16x32_bf16 v[14:17], v[146:149], v[194:197], v[14:17]
	v_mfma_f32_16x16x32_bf16 v[58:61], v[154:157], v[170:173], v[58:61]
	v_mfma_f32_16x16x32_bf16 v[54:57], v[162:165], v[170:173], v[54:57]
	v_mfma_f32_16x16x32_bf16 v[42:45], v[154:157], v[178:181], v[42:45]
	v_mfma_f32_16x16x32_bf16 v[38:41], v[162:165], v[178:181], v[38:41]
	v_mfma_f32_16x16x32_bf16 v[26:29], v[154:157], v[186:189], v[26:29]
	v_mfma_f32_16x16x32_bf16 v[22:25], v[162:165], v[186:189], v[22:25]
	v_mfma_f32_16x16x32_bf16 v[10:13], v[154:157], v[194:197], v[10:13]
	v_mfma_f32_16x16x32_bf16 v[4:7], v[162:165], v[194:197], v[4:7]
	s_setprio 0
	s_barrier
	s_nop 7
	s_nop 7
	s_nop 7
	v_add_u32_e32 v2, 0x18000, v232
	ds_read_b128 v[134:137], v2
	ds_read_b128 v[138:141], v2 offset:1024
	ds_read_b128 v[142:145], v2 offset:2048
	ds_read_b128 v[146:149], v2 offset:3072
	v_add_u32_e32 v2, 0x1c000, v232
	ds_read_b128 v[150:153], v2
	ds_read_b128 v[154:157], v2 offset:1024
	ds_read_b128 v[158:161], v2 offset:2048
	ds_read_b128 v[162:165], v2 offset:3072
	s_mov_b32 m0, s56
	s_add_i32 s53, s92, 0x80000
	ds_read_b128 v[166:169], v233 offset:32768
	ds_read_b128 v[170:173], v233 offset:33792
	ds_read_b128 v[174:177], v233 offset:34816
	ds_read_b128 v[178:181], v233 offset:35840
	ds_read_b128 v[182:185], v233 offset:36864
	ds_read_b128 v[186:189], v233 offset:37888
	ds_read_b128 v[190:193], v233 offset:38912
	ds_read_b128 v[194:197], v233 offset:39936
	buffer_load_dwordx4 v230, s[12:15], s53 offen lds
	s_add_i32 s53, s92, 0xc0000
	s_mov_b32 m0, s57
	s_nop 0
	buffer_load_dwordx4 v230, s[12:15], s53 offen lds
	s_waitcnt vmcnt(8)
	s_waitcnt lgkmcnt(0)
	s_setprio 1
	v_mfma_f32_16x16x32_bf16 v[130:133], v[134:137], v[166:169], v[130:133]
	s_barrier
	v_mfma_f32_16x16x32_bf16 v[130:133], v[138:141], v[170:173], v[130:133]
	v_mfma_f32_16x16x32_bf16 v[126:129], v[142:145], v[166:169], v[126:129]
	v_mfma_f32_16x16x32_bf16 v[126:129], v[146:149], v[170:173], v[126:129]
	v_mfma_f32_16x16x32_bf16 v[122:125], v[150:153], v[166:169], v[122:125]
	v_mfma_f32_16x16x32_bf16 v[122:125], v[154:157], v[170:173], v[122:125]
	v_mfma_f32_16x16x32_bf16 v[118:121], v[158:161], v[166:169], v[118:121]
	v_mfma_f32_16x16x32_bf16 v[118:121], v[162:165], v[170:173], v[118:121]
	v_mfma_f32_16x16x32_bf16 v[102:105], v[158:161], v[174:177], v[102:105]
	v_mfma_f32_16x16x32_bf16 v[102:105], v[162:165], v[178:181], v[102:105]
	v_mfma_f32_16x16x32_bf16 v[106:109], v[150:153], v[174:177], v[106:109]
	v_mfma_f32_16x16x32_bf16 v[106:109], v[154:157], v[178:181], v[106:109]
	v_mfma_f32_16x16x32_bf16 v[110:113], v[142:145], v[174:177], v[110:113]
	v_mfma_f32_16x16x32_bf16 v[110:113], v[146:149], v[178:181], v[110:113]
	v_mfma_f32_16x16x32_bf16 v[114:117], v[134:137], v[174:177], v[114:117]
	v_mfma_f32_16x16x32_bf16 v[114:117], v[138:141], v[178:181], v[114:117]
	v_mfma_f32_16x16x32_bf16 v[98:101], v[134:137], v[182:185], v[98:101]
	v_mfma_f32_16x16x32_bf16 v[98:101], v[138:141], v[186:189], v[98:101]
	v_mfma_f32_16x16x32_bf16 v[94:97], v[142:145], v[182:185], v[94:97]
	v_mfma_f32_16x16x32_bf16 v[94:97], v[146:149], v[186:189], v[94:97]
	v_mfma_f32_16x16x32_bf16 v[90:93], v[150:153], v[182:185], v[90:93]
	v_mfma_f32_16x16x32_bf16 v[90:93], v[154:157], v[186:189], v[90:93]
	v_mfma_f32_16x16x32_bf16 v[86:89], v[158:161], v[182:185], v[86:89]
	v_mfma_f32_16x16x32_bf16 v[86:89], v[162:165], v[186:189], v[86:89]
	v_mfma_f32_16x16x32_bf16 v[70:73], v[158:161], v[190:193], v[70:73]
	v_mfma_f32_16x16x32_bf16 v[70:73], v[162:165], v[194:197], v[70:73]
	v_mfma_f32_16x16x32_bf16 v[74:77], v[150:153], v[190:193], v[74:77]
	v_mfma_f32_16x16x32_bf16 v[74:77], v[154:157], v[194:197], v[74:77]
	v_mfma_f32_16x16x32_bf16 v[78:81], v[142:145], v[190:193], v[78:81]
	v_mfma_f32_16x16x32_bf16 v[78:81], v[146:149], v[194:197], v[78:81]
	v_mfma_f32_16x16x32_bf16 v[82:85], v[134:137], v[190:193], v[82:85]
	v_mfma_f32_16x16x32_bf16 v[82:85], v[138:141], v[194:197], v[82:85]
	s_setprio 0
	s_barrier
	s_mov_b32 m0, s64
	ds_read_b128 v[166:169], v233 offset:49152
	ds_read_b128 v[170:173], v233 offset:50176
	ds_read_b128 v[174:177], v233 offset:51200
	ds_read_b128 v[178:181], v233 offset:52224
	ds_read_b128 v[182:185], v233 offset:53248
	ds_read_b128 v[186:189], v233 offset:54272
	ds_read_b128 v[190:193], v233 offset:55296
	ds_read_b128 v[194:197], v233 offset:56320
	buffer_load_dwordx4 v231, s[16:19], s52 offen lds
	s_add_i32 s52, s51, 0x18080
	s_mov_b32 m0, s65
	s_nop 0
	buffer_load_dwordx4 v231, s[16:19], s52 offen lds
	s_add_i32 s52, s51, 0x30080
	s_mov_b32 m0, s68
	s_add_i32 s51, s51, 0x48080
	buffer_load_dwordx4 v231, s[16:19], s52 offen lds
	s_mov_b32 m0, s69
	s_nop 0
	buffer_load_dwordx4 v231, s[16:19], s51 offen lds
	s_mov_b32 m0, s66
	s_add_i32 s18, s92, 0x40080
	buffer_load_dwordx4 v230, s[12:15], s50 offen lds
	s_mov_b32 m0, s67
	s_nop 0
	buffer_load_dwordx4 v230, s[12:15], s18 offen lds
	s_waitcnt vmcnt(8)
	s_waitcnt lgkmcnt(0)
	s_setprio 1
	v_mfma_f32_16x16x32_bf16 v[66:69], v[134:137], v[166:169], v[66:69]
	s_barrier
	v_mfma_f32_16x16x32_bf16 v[62:65], v[142:145], v[166:169], v[62:65]
	v_mfma_f32_16x16x32_bf16 v[50:53], v[134:137], v[174:177], v[50:53]
	v_mfma_f32_16x16x32_bf16 v[46:49], v[142:145], v[174:177], v[46:49]
	v_mfma_f32_16x16x32_bf16 v[34:37], v[134:137], v[182:185], v[34:37]
	v_mfma_f32_16x16x32_bf16 v[30:33], v[142:145], v[182:185], v[30:33]
	v_mfma_f32_16x16x32_bf16 v[18:21], v[134:137], v[190:193], v[18:21]
	v_mfma_f32_16x16x32_bf16 v[14:17], v[142:145], v[190:193], v[14:17]
	v_mfma_f32_16x16x32_bf16 v[58:61], v[150:153], v[166:169], v[58:61]
	v_mfma_f32_16x16x32_bf16 v[54:57], v[158:161], v[166:169], v[54:57]
	v_mfma_f32_16x16x32_bf16 v[42:45], v[150:153], v[174:177], v[42:45]
	v_mfma_f32_16x16x32_bf16 v[38:41], v[158:161], v[174:177], v[38:41]
	v_mfma_f32_16x16x32_bf16 v[26:29], v[150:153], v[182:185], v[26:29]
	v_mfma_f32_16x16x32_bf16 v[22:25], v[158:161], v[182:185], v[22:25]
	v_mfma_f32_16x16x32_bf16 v[8:11], v[150:153], v[190:193], v[10:13]
	v_mfma_f32_16x16x32_bf16 v[4:7], v[158:161], v[190:193], v[4:7]
	v_mfma_f32_16x16x32_bf16 v[66:69], v[138:141], v[170:173], v[66:69]
	v_mfma_f32_16x16x32_bf16 v[62:65], v[146:149], v[170:173], v[62:65]
	v_mfma_f32_16x16x32_bf16 v[50:53], v[138:141], v[178:181], v[50:53]
	v_mfma_f32_16x16x32_bf16 v[46:49], v[146:149], v[178:181], v[46:49]
	v_mfma_f32_16x16x32_bf16 v[34:37], v[138:141], v[186:189], v[34:37]
	v_mfma_f32_16x16x32_bf16 v[30:33], v[146:149], v[186:189], v[30:33]
	v_mfma_f32_16x16x32_bf16 v[18:21], v[138:141], v[194:197], v[18:21]
	v_mfma_f32_16x16x32_bf16 v[14:17], v[146:149], v[194:197], v[14:17]
	v_mfma_f32_16x16x32_bf16 v[58:61], v[154:157], v[170:173], v[58:61]
	v_mfma_f32_16x16x32_bf16 v[54:57], v[162:165], v[170:173], v[54:57]
	v_mfma_f32_16x16x32_bf16 v[42:45], v[154:157], v[178:181], v[42:45]
	v_mfma_f32_16x16x32_bf16 v[38:41], v[162:165], v[178:181], v[38:41]
	v_mfma_f32_16x16x32_bf16 v[26:29], v[154:157], v[186:189], v[26:29]
	v_mfma_f32_16x16x32_bf16 v[22:25], v[162:165], v[186:189], v[22:25]
	v_mfma_f32_16x16x32_bf16 v[10:13], v[154:157], v[194:197], v[8:11]
	v_mfma_f32_16x16x32_bf16 v[6:9], v[162:165], v[194:197], v[4:7]
	s_setprio 0
	s_barrier
	s_nop 7
	s_nop 7
	s_nop 7
	s_add_i32 s91, s91, 2
	s_addk_i32 s90, 0x100
	s_cmp_ge_i32 s91, s3
	s_cbranch_scc1 .LBB0_1193

.LBB0_1290:
	ds_read_b128 v[106:109], v224
	ds_read_b128 v[118:121], v224 offset:1024
	ds_read_b128 v[130:133], v224 offset:2048
	ds_read_b128 v[138:141], v224 offset:3072
	ds_read_b128 v[146:149], v225
	ds_read_b128 v[150:153], v225 offset:1024
	ds_read_b128 v[154:157], v225 offset:2048
	ds_read_b128 v[158:161], v225 offset:3072
	s_add_i32 s18, s72, 0xffe80080
	s_cmp_eq_u32 s56, s74
	s_cselect_b32 s75, s6, s18
	s_cselect_b32 s77, s7, s73
	s_or_b32 s76, s75, 0x80
	s_add_i32 s18, s72, 0xfff80000
	s_mov_b32 m0, s57
	ds_read_b128 v[162:165], v226
	ds_read_b128 v[166:169], v226 offset:1024
	ds_read_b128 v[170:173], v226 offset:2048
	ds_read_b128 v[174:177], v226 offset:3072
	ds_read_b128 v[178:181], v226 offset:4096
	ds_read_b128 v[182:185], v226 offset:5120
	ds_read_b128 v[190:193], v226 offset:6144
	ds_read_b128 v[194:197], v226 offset:7168
	buffer_load_dwordx4 v222, s[12:15], s18 offen lds
	s_mov_b32 m0, s60
	s_nop 0
	buffer_load_dwordx4 v222, s[12:15], s72 offen lds
	s_waitcnt vmcnt(8)
	s_waitcnt lgkmcnt(0)
	s_setprio 1
	v_mfma_f32_16x16x32_bf16 v[142:145], v[106:109], v[162:165], v[142:145]
	s_barrier
	v_mfma_f32_16x16x32_bf16 v[142:145], v[118:121], v[166:169], v[142:145]
	v_mfma_f32_16x16x32_bf16 v[134:137], v[130:133], v[162:165], v[134:137]
	v_mfma_f32_16x16x32_bf16 v[134:137], v[138:141], v[166:169], v[134:137]
	v_mfma_f32_16x16x32_bf16 v[126:129], v[146:149], v[162:165], v[126:129]
	v_mfma_f32_16x16x32_bf16 v[126:129], v[150:153], v[166:169], v[126:129]
	v_mfma_f32_16x16x32_bf16 v[122:125], v[154:157], v[162:165], v[122:125]
	v_mfma_f32_16x16x32_bf16 v[122:125], v[158:161], v[166:169], v[122:125]
	v_mfma_f32_16x16x32_bf16 v[98:101], v[154:157], v[170:173], v[98:101]
	v_mfma_f32_16x16x32_bf16 v[98:101], v[158:161], v[174:177], v[98:101]
	v_mfma_f32_16x16x32_bf16 v[102:105], v[146:149], v[170:173], v[102:105]
	v_mfma_f32_16x16x32_bf16 v[102:105], v[150:153], v[174:177], v[102:105]
	v_mfma_f32_16x16x32_bf16 v[110:113], v[130:133], v[170:173], v[110:113]
	v_mfma_f32_16x16x32_bf16 v[110:113], v[138:141], v[174:177], v[110:113]
	v_mfma_f32_16x16x32_bf16 v[114:117], v[106:109], v[170:173], v[114:117]
	v_mfma_f32_16x16x32_bf16 v[114:117], v[118:121], v[174:177], v[114:117]
	v_mfma_f32_16x16x32_bf16 v[94:97], v[106:109], v[178:181], v[94:97]
	v_mfma_f32_16x16x32_bf16 v[94:97], v[118:121], v[182:185], v[94:97]
	v_mfma_f32_16x16x32_bf16 v[90:93], v[130:133], v[178:181], v[90:93]
	v_mfma_f32_16x16x32_bf16 v[90:93], v[138:141], v[182:185], v[90:93]
	v_mfma_f32_16x16x32_bf16 v[86:89], v[146:149], v[178:181], v[86:89]
	v_mfma_f32_16x16x32_bf16 v[86:89], v[150:153], v[182:185], v[86:89]
	v_mfma_f32_16x16x32_bf16 v[82:85], v[154:157], v[178:181], v[82:85]
	v_mfma_f32_16x16x32_bf16 v[82:85], v[158:161], v[182:185], v[82:85]
	v_mfma_f32_16x16x32_bf16 v[66:69], v[154:157], v[190:193], v[66:69]
	v_mfma_f32_16x16x32_bf16 v[66:69], v[158:161], v[194:197], v[66:69]
	v_mfma_f32_16x16x32_bf16 v[70:73], v[146:149], v[190:193], v[70:73]
	v_mfma_f32_16x16x32_bf16 v[70:73], v[150:153], v[194:197], v[70:73]
	v_mfma_f32_16x16x32_bf16 v[74:77], v[130:133], v[190:193], v[74:77]
	v_mfma_f32_16x16x32_bf16 v[74:77], v[138:141], v[194:197], v[74:77]
	v_mfma_f32_16x16x32_bf16 v[78:81], v[106:109], v[190:193], v[78:81]
	v_mfma_f32_16x16x32_bf16 v[78:81], v[118:121], v[194:197], v[78:81]
	s_setprio 0
	s_barrier
	s_mov_b32 m0, s27
	s_mov_b32 s18, s14
	s_mov_b32 s19, s15
	ds_read_b128 v[162:165], v226 offset:16384
	ds_read_b128 v[166:169], v226 offset:17408
	ds_read_b128 v[170:173], v226 offset:18432
	ds_read_b128 v[174:177], v226 offset:19456
	ds_read_b128 v[178:181], v226 offset:20480
	ds_read_b128 v[182:185], v226 offset:21504
	ds_read_b128 v[190:193], v226 offset:22528
	ds_read_b128 v[194:197], v226 offset:23552
	buffer_load_dwordx4 v223, s[16:19], s77 offen lds
	s_add_i32 s78, s77, 0x80000
	s_mov_b32 m0, s30
	s_nop 0
	buffer_load_dwordx4 v223, s[16:19], s78 offen lds
	s_add_i32 s78, s77, 0x100000
	s_mov_b32 m0, s31
	s_nop 0
	buffer_load_dwordx4 v223, s[16:19], s78 offen lds
	s_add_i32 s78, s77, 0x180000
	s_mov_b32 m0, s41
	s_nop 0
	buffer_load_dwordx4 v223, s[16:19], s78 offen lds
	s_mov_b32 m0, s25
	s_add_i32 s78, s75, 0x80000
	buffer_load_dwordx4 v222, s[12:15], s75 offen lds
	s_mov_b32 m0, s42
	s_nop 0
	buffer_load_dwordx4 v222, s[12:15], s78 offen lds
	s_waitcnt vmcnt(8)
	s_waitcnt lgkmcnt(0)
	s_setprio 1
	v_mfma_f32_16x16x32_bf16 v[62:65], v[106:109], v[162:165], v[62:65]
	s_barrier
	v_mfma_f32_16x16x32_bf16 v[62:65], v[118:121], v[166:169], v[62:65]
	v_mfma_f32_16x16x32_bf16 v[58:61], v[130:133], v[162:165], v[58:61]
	v_mfma_f32_16x16x32_bf16 v[58:61], v[138:141], v[166:169], v[58:61]
	v_mfma_f32_16x16x32_bf16 v[54:57], v[146:149], v[162:165], v[54:57]
	v_mfma_f32_16x16x32_bf16 v[54:57], v[150:153], v[166:169], v[54:57]
	v_mfma_f32_16x16x32_bf16 v[50:53], v[154:157], v[162:165], v[50:53]
	v_mfma_f32_16x16x32_bf16 v[50:53], v[158:161], v[166:169], v[50:53]
	v_mfma_f32_16x16x32_bf16 v[34:37], v[154:157], v[170:173], v[34:37]
	v_mfma_f32_16x16x32_bf16 v[34:37], v[158:161], v[174:177], v[34:37]
	v_mfma_f32_16x16x32_bf16 v[38:41], v[146:149], v[170:173], v[38:41]
	v_mfma_f32_16x16x32_bf16 v[38:41], v[150:153], v[174:177], v[38:41]
	v_mfma_f32_16x16x32_bf16 v[42:45], v[130:133], v[170:173], v[42:45]
	v_mfma_f32_16x16x32_bf16 v[42:45], v[138:141], v[174:177], v[42:45]
	v_mfma_f32_16x16x32_bf16 v[46:49], v[106:109], v[170:173], v[46:49]
	v_mfma_f32_16x16x32_bf16 v[46:49], v[118:121], v[174:177], v[46:49]
	v_mfma_f32_16x16x32_bf16 v[30:33], v[106:109], v[178:181], v[30:33]
	v_mfma_f32_16x16x32_bf16 v[30:33], v[118:121], v[182:185], v[30:33]
	v_mfma_f32_16x16x32_bf16 v[26:29], v[130:133], v[178:181], v[26:29]
	v_mfma_f32_16x16x32_bf16 v[26:29], v[138:141], v[182:185], v[26:29]
	v_mfma_f32_16x16x32_bf16 v[22:25], v[146:149], v[178:181], v[22:25]
	v_mfma_f32_16x16x32_bf16 v[22:25], v[150:153], v[182:185], v[22:25]
	v_mfma_f32_16x16x32_bf16 v[18:21], v[154:157], v[178:181], v[18:21]
	v_mfma_f32_16x16x32_bf16 v[18:21], v[158:161], v[182:185], v[18:21]
	v_mfma_f32_16x16x32_bf16 v[2:5], v[154:157], v[190:193], v[2:5]
	v_mfma_f32_16x16x32_bf16 v[2:5], v[158:161], v[194:197], v[2:5]
	v_mfma_f32_16x16x32_bf16 v[6:9], v[146:149], v[190:193], v[6:9]
	v_mfma_f32_16x16x32_bf16 v[6:9], v[150:153], v[194:197], v[6:9]
	v_mfma_f32_16x16x32_bf16 v[10:13], v[130:133], v[190:193], v[10:13]
	v_mfma_f32_16x16x32_bf16 v[10:13], v[138:141], v[194:197], v[10:13]
	v_mfma_f32_16x16x32_bf16 v[14:17], v[106:109], v[190:193], v[14:17]
	v_mfma_f32_16x16x32_bf16 v[14:17], v[118:121], v[194:197], v[14:17]
	s_setprio 0
	s_barrier
	s_nop 7
	s_nop 7
	s_nop 7
	ds_read_b128 v[106:109], v227
	ds_read_b128 v[118:121], v227 offset:1024
	ds_read_b128 v[130:133], v227 offset:2048
	ds_read_b128 v[138:141], v227 offset:3072
	ds_read_b128 v[146:149], v228
	ds_read_b128 v[150:153], v228 offset:1024
	ds_read_b128 v[154:157], v228 offset:2048
	ds_read_b128 v[158:161], v228 offset:3072
	s_mov_b32 m0, s43
	s_add_i32 s78, s75, 0x100000
	ds_read_b128 v[162:165], v226 offset:32768
	ds_read_b128 v[166:169], v226 offset:33792
	ds_read_b128 v[170:173], v226 offset:34816
	ds_read_b128 v[174:177], v226 offset:35840
	ds_read_b128 v[178:181], v226 offset:36864
	ds_read_b128 v[182:185], v226 offset:37888
	ds_read_b128 v[190:193], v226 offset:38912
	ds_read_b128 v[194:197], v226 offset:39936
	buffer_load_dwordx4 v222, s[12:15], s78 offen lds
	s_add_i32 s78, s75, 0x180000
	s_mov_b32 m0, s44
	s_nop 0
	buffer_load_dwordx4 v222, s[12:15], s78 offen lds
	s_waitcnt vmcnt(8)
	s_waitcnt lgkmcnt(0)
	s_setprio 1
	v_mfma_f32_16x16x32_bf16 v[142:145], v[106:109], v[162:165], v[142:145]
	s_barrier
	v_mfma_f32_16x16x32_bf16 v[142:145], v[118:121], v[166:169], v[142:145]
	v_mfma_f32_16x16x32_bf16 v[134:137], v[130:133], v[162:165], v[134:137]
	v_mfma_f32_16x16x32_bf16 v[134:137], v[138:141], v[166:169], v[134:137]
	v_mfma_f32_16x16x32_bf16 v[126:129], v[146:149], v[162:165], v[126:129]
	v_mfma_f32_16x16x32_bf16 v[126:129], v[150:153], v[166:169], v[126:129]
	v_mfma_f32_16x16x32_bf16 v[122:125], v[154:157], v[162:165], v[122:125]
	v_mfma_f32_16x16x32_bf16 v[122:125], v[158:161], v[166:169], v[122:125]
	v_mfma_f32_16x16x32_bf16 v[98:101], v[154:157], v[170:173], v[98:101]
	v_mfma_f32_16x16x32_bf16 v[98:101], v[158:161], v[174:177], v[98:101]
	v_mfma_f32_16x16x32_bf16 v[102:105], v[146:149], v[170:173], v[102:105]
	v_mfma_f32_16x16x32_bf16 v[102:105], v[150:153], v[174:177], v[102:105]
	v_mfma_f32_16x16x32_bf16 v[110:113], v[130:133], v[170:173], v[110:113]
	v_mfma_f32_16x16x32_bf16 v[110:113], v[138:141], v[174:177], v[110:113]
	v_mfma_f32_16x16x32_bf16 v[114:117], v[106:109], v[170:173], v[114:117]
	v_mfma_f32_16x16x32_bf16 v[114:117], v[118:121], v[174:177], v[114:117]
	v_mfma_f32_16x16x32_bf16 v[94:97], v[106:109], v[178:181], v[94:97]
	v_mfma_f32_16x16x32_bf16 v[94:97], v[118:121], v[182:185], v[94:97]
	v_mfma_f32_16x16x32_bf16 v[90:93], v[130:133], v[178:181], v[90:93]
	v_mfma_f32_16x16x32_bf16 v[90:93], v[138:141], v[182:185], v[90:93]
	v_mfma_f32_16x16x32_bf16 v[86:89], v[146:149], v[178:181], v[86:89]
	v_mfma_f32_16x16x32_bf16 v[86:89], v[150:153], v[182:185], v[86:89]
	v_mfma_f32_16x16x32_bf16 v[82:85], v[154:157], v[178:181], v[82:85]
	v_mfma_f32_16x16x32_bf16 v[82:85], v[158:161], v[182:185], v[82:85]
	v_mfma_f32_16x16x32_bf16 v[66:69], v[154:157], v[190:193], v[66:69]
	v_mfma_f32_16x16x32_bf16 v[66:69], v[158:161], v[194:197], v[66:69]
	v_mfma_f32_16x16x32_bf16 v[70:73], v[146:149], v[190:193], v[70:73]
	v_mfma_f32_16x16x32_bf16 v[70:73], v[150:153], v[194:197], v[70:73]
	v_mfma_f32_16x16x32_bf16 v[74:77], v[130:133], v[190:193], v[74:77]
	v_mfma_f32_16x16x32_bf16 v[74:77], v[138:141], v[194:197], v[74:77]
	v_mfma_f32_16x16x32_bf16 v[78:81], v[106:109], v[190:193], v[78:81]
	v_mfma_f32_16x16x32_bf16 v[78:81], v[118:121], v[194:197], v[78:81]
	s_setprio 0
	s_barrier
	s_mov_b32 m0, s48
	s_or_b32 s78, s77, 0x80
	ds_read_b128 v[162:165], v226 offset:49152
	ds_read_b128 v[166:169], v226 offset:50176
	ds_read_b128 v[170:173], v226 offset:51200
	ds_read_b128 v[174:177], v226 offset:52224
	ds_read_b128 v[178:181], v226 offset:53248
	ds_read_b128 v[182:185], v226 offset:54272
	ds_read_b128 v[190:193], v226 offset:55296
	ds_read_b128 v[194:197], v226 offset:56320
	buffer_load_dwordx4 v223, s[16:19], s78 offen lds
	s_add_i32 s78, s77, 0x80080
	s_mov_b32 m0, s49
	s_add_i32 s75, s75, 0x80080
	buffer_load_dwordx4 v223, s[16:19], s78 offen lds
	s_add_i32 s78, s77, 0x100080
	s_mov_b32 m0, s52
	s_add_i32 s77, s77, 0x180080
	buffer_load_dwordx4 v223, s[16:19], s78 offen lds
	s_mov_b32 m0, s53
	s_nop 0
	buffer_load_dwordx4 v223, s[16:19], s77 offen lds
	s_mov_b32 m0, s50
	s_nop 0
	buffer_load_dwordx4 v222, s[12:15], s76 offen lds
	s_mov_b32 m0, s51
	s_nop 0
	buffer_load_dwordx4 v222, s[12:15], s75 offen lds
	s_waitcnt vmcnt(8)
	s_waitcnt lgkmcnt(0)
	s_setprio 1
	v_mfma_f32_16x16x32_bf16 v[62:65], v[106:109], v[162:165], v[62:65]
	s_barrier
	v_mfma_f32_16x16x32_bf16 v[62:65], v[118:121], v[166:169], v[62:65]
	v_mfma_f32_16x16x32_bf16 v[58:61], v[130:133], v[162:165], v[58:61]
	v_mfma_f32_16x16x32_bf16 v[58:61], v[138:141], v[166:169], v[58:61]
	v_mfma_f32_16x16x32_bf16 v[54:57], v[146:149], v[162:165], v[54:57]
	v_mfma_f32_16x16x32_bf16 v[54:57], v[150:153], v[166:169], v[54:57]
	v_mfma_f32_16x16x32_bf16 v[50:53], v[154:157], v[162:165], v[50:53]
	v_mfma_f32_16x16x32_bf16 v[50:53], v[158:161], v[166:169], v[50:53]
	v_mfma_f32_16x16x32_bf16 v[34:37], v[154:157], v[170:173], v[34:37]
	v_mfma_f32_16x16x32_bf16 v[34:37], v[158:161], v[174:177], v[34:37]
	v_mfma_f32_16x16x32_bf16 v[38:41], v[146:149], v[170:173], v[38:41]
	v_mfma_f32_16x16x32_bf16 v[38:41], v[150:153], v[174:177], v[38:41]
	v_mfma_f32_16x16x32_bf16 v[42:45], v[130:133], v[170:173], v[42:45]
	v_mfma_f32_16x16x32_bf16 v[42:45], v[138:141], v[174:177], v[42:45]
	v_mfma_f32_16x16x32_bf16 v[46:49], v[106:109], v[170:173], v[46:49]
	v_mfma_f32_16x16x32_bf16 v[46:49], v[118:121], v[174:177], v[46:49]
	v_mfma_f32_16x16x32_bf16 v[30:33], v[106:109], v[178:181], v[30:33]
	v_mfma_f32_16x16x32_bf16 v[30:33], v[118:121], v[182:185], v[30:33]
	v_mfma_f32_16x16x32_bf16 v[26:29], v[130:133], v[178:181], v[26:29]
	v_mfma_f32_16x16x32_bf16 v[26:29], v[138:141], v[182:185], v[26:29]
	v_mfma_f32_16x16x32_bf16 v[22:25], v[146:149], v[178:181], v[22:25]
	v_mfma_f32_16x16x32_bf16 v[22:25], v[150:153], v[182:185], v[22:25]
	v_mfma_f32_16x16x32_bf16 v[18:21], v[154:157], v[178:181], v[18:21]
	v_mfma_f32_16x16x32_bf16 v[18:21], v[158:161], v[182:185], v[18:21]
	v_mfma_f32_16x16x32_bf16 v[2:5], v[154:157], v[190:193], v[2:5]
	v_mfma_f32_16x16x32_bf16 v[2:5], v[158:161], v[194:197], v[2:5]
	v_mfma_f32_16x16x32_bf16 v[6:9], v[146:149], v[190:193], v[6:9]
	v_mfma_f32_16x16x32_bf16 v[6:9], v[150:153], v[194:197], v[6:9]
	v_mfma_f32_16x16x32_bf16 v[10:13], v[130:133], v[190:193], v[10:13]
	v_mfma_f32_16x16x32_bf16 v[10:13], v[138:141], v[194:197], v[10:13]
	v_mfma_f32_16x16x32_bf16 v[14:17], v[106:109], v[190:193], v[14:17]
	v_mfma_f32_16x16x32_bf16 v[14:17], v[118:121], v[194:197], v[14:17]
	s_setprio 0
	s_barrier
	s_nop 7
	s_nop 7
	s_nop 7
	s_add_i32 s74, s74, 2
	s_addk_i32 s72, 0x100
	s_addk_i32 s73, 0x100
	s_cmp_ge_i32 s74, s3
	s_cbranch_scc0 .LBB0_1290
	s_and_b64 vcc, exec, s[38:39]
	s_cbranch_vccz .LBB0_1293

.LBB0_1382:
	ds_read_b128 v[144:147], v138
	ds_read_b128 v[148:151], v138 offset:1024
	ds_read_b128 v[152:155], v138 offset:2048
	ds_read_b128 v[156:159], v138 offset:3072
	ds_read_b128 v[160:163], v139
	ds_read_b128 v[164:167], v139 offset:1024
	ds_read_b128 v[168:171], v139 offset:2048
	ds_read_b128 v[172:175], v139 offset:3072
	s_add_i32 s14, s74, 0xffe80080
	s_cmp_eq_u32 s61, s76
	s_cselect_b32 s77, s72, s14
	s_cselect_b32 s79, s73, s75
	s_or_b32 s78, s77, 0x80
	s_add_i32 s14, s74, 0xfff80000
	s_mov_b32 m0, s62
	ds_read_b128 v[176:179], v140
	ds_read_b128 v[180:183], v140 offset:1024
	ds_read_b128 v[184:187], v140 offset:2048
	ds_read_b128 v[188:191], v140 offset:3072
	ds_read_b128 v[192:195], v140 offset:4096
	ds_read_b128 v[196:199], v140 offset:5120
	ds_read_b128 v[200:203], v140 offset:6144
	ds_read_b128 v[204:207], v140 offset:7168
	buffer_load_dwordx4 v136, s[16:19], s14 offen lds
	s_mov_b32 m0, s63
	s_nop 0
	buffer_load_dwordx4 v136, s[16:19], s74 offen lds
	s_waitcnt vmcnt(8)
	s_waitcnt lgkmcnt(0)
	s_setprio 1
	v_mfma_f32_16x16x32_bf16 v[118:121], v[144:147], v[176:179], v[118:121]
	s_barrier
	v_mfma_f32_16x16x32_bf16 v[118:121], v[148:151], v[180:183], v[118:121]
	v_mfma_f32_16x16x32_bf16 v[114:117], v[152:155], v[176:179], v[114:117]
	v_mfma_f32_16x16x32_bf16 v[114:117], v[156:159], v[180:183], v[114:117]
	v_mfma_f32_16x16x32_bf16 v[126:129], v[160:163], v[176:179], v[126:129]
	v_mfma_f32_16x16x32_bf16 v[126:129], v[164:167], v[180:183], v[126:129]
	v_mfma_f32_16x16x32_bf16 v[122:125], v[168:171], v[176:179], v[122:125]
	v_mfma_f32_16x16x32_bf16 v[122:125], v[172:175], v[180:183], v[122:125]
	v_mfma_f32_16x16x32_bf16 v[98:101], v[168:171], v[184:187], v[98:101]
	v_mfma_f32_16x16x32_bf16 v[98:101], v[172:175], v[188:191], v[98:101]
	v_mfma_f32_16x16x32_bf16 v[106:109], v[160:163], v[184:187], v[106:109]
	v_mfma_f32_16x16x32_bf16 v[106:109], v[164:167], v[188:191], v[106:109]
	v_mfma_f32_16x16x32_bf16 v[102:105], v[152:155], v[184:187], v[102:105]
	v_mfma_f32_16x16x32_bf16 v[102:105], v[156:159], v[188:191], v[102:105]
	v_mfma_f32_16x16x32_bf16 v[110:113], v[144:147], v[184:187], v[110:113]
	v_mfma_f32_16x16x32_bf16 v[110:113], v[148:151], v[188:191], v[110:113]
	v_mfma_f32_16x16x32_bf16 v[94:97], v[144:147], v[192:195], v[94:97]
	v_mfma_f32_16x16x32_bf16 v[94:97], v[148:151], v[196:199], v[94:97]
	v_mfma_f32_16x16x32_bf16 v[86:89], v[152:155], v[192:195], v[86:89]
	v_mfma_f32_16x16x32_bf16 v[86:89], v[156:159], v[196:199], v[86:89]
	v_mfma_f32_16x16x32_bf16 v[90:93], v[160:163], v[192:195], v[90:93]
	v_mfma_f32_16x16x32_bf16 v[90:93], v[164:167], v[196:199], v[90:93]
	v_mfma_f32_16x16x32_bf16 v[82:85], v[168:171], v[192:195], v[82:85]
	v_mfma_f32_16x16x32_bf16 v[82:85], v[172:175], v[196:199], v[82:85]
	v_mfma_f32_16x16x32_bf16 v[70:73], v[168:171], v[200:203], v[70:73]
	v_mfma_f32_16x16x32_bf16 v[70:73], v[172:175], v[204:207], v[70:73]
	v_mfma_f32_16x16x32_bf16 v[74:77], v[160:163], v[200:203], v[74:77]
	v_mfma_f32_16x16x32_bf16 v[74:77], v[164:167], v[204:207], v[74:77]
	v_mfma_f32_16x16x32_bf16 v[66:69], v[152:155], v[200:203], v[66:69]
	v_mfma_f32_16x16x32_bf16 v[66:69], v[156:159], v[204:207], v[66:69]
	v_mfma_f32_16x16x32_bf16 v[78:81], v[144:147], v[200:203], v[78:81]
	v_mfma_f32_16x16x32_bf16 v[78:81], v[148:151], v[204:207], v[78:81]
	s_setprio 0
	s_barrier
	s_mov_b32 m0, s45
	s_mov_b32 s14, s18
	s_mov_b32 s15, s19
	ds_read_b128 v[176:179], v140 offset:16384
	ds_read_b128 v[180:183], v140 offset:17408
	ds_read_b128 v[184:187], v140 offset:18432
	ds_read_b128 v[188:191], v140 offset:19456
	ds_read_b128 v[192:195], v140 offset:20480
	ds_read_b128 v[196:199], v140 offset:21504
	ds_read_b128 v[200:203], v140 offset:22528
	ds_read_b128 v[204:207], v140 offset:23552
	buffer_load_dwordx4 v137, s[12:15], s79 offen lds
	s_add_i32 s80, s79, 0x80000
	s_mov_b32 m0, s46
	s_nop 0
	buffer_load_dwordx4 v137, s[12:15], s80 offen lds
	s_add_i32 s80, s79, 0x100000
	s_mov_b32 m0, s47
	s_nop 0
	buffer_load_dwordx4 v137, s[12:15], s80 offen lds
	s_add_i32 s80, s79, 0x180000
	s_mov_b32 m0, s48
	s_nop 0
	buffer_load_dwordx4 v137, s[12:15], s80 offen lds
	s_mov_b32 m0, s44
	s_add_i32 s80, s77, 0x80000
	buffer_load_dwordx4 v136, s[16:19], s77 offen lds
	s_mov_b32 m0, s49
	s_nop 0
	buffer_load_dwordx4 v136, s[16:19], s80 offen lds
	s_waitcnt vmcnt(8)
	s_waitcnt lgkmcnt(0)
	s_setprio 1
	v_mfma_f32_16x16x32_bf16 v[62:65], v[144:147], v[176:179], v[62:65]
	s_barrier
	v_mfma_f32_16x16x32_bf16 v[62:65], v[148:151], v[180:183], v[62:65]
	v_mfma_f32_16x16x32_bf16 v[54:57], v[152:155], v[176:179], v[54:57]
	v_mfma_f32_16x16x32_bf16 v[54:57], v[156:159], v[180:183], v[54:57]
	v_mfma_f32_16x16x32_bf16 v[58:61], v[160:163], v[176:179], v[58:61]
	v_mfma_f32_16x16x32_bf16 v[58:61], v[164:167], v[180:183], v[58:61]
	v_mfma_f32_16x16x32_bf16 v[50:53], v[168:171], v[176:179], v[50:53]
	v_mfma_f32_16x16x32_bf16 v[50:53], v[172:175], v[180:183], v[50:53]
	v_mfma_f32_16x16x32_bf16 v[34:37], v[168:171], v[184:187], v[34:37]
	v_mfma_f32_16x16x32_bf16 v[34:37], v[172:175], v[188:191], v[34:37]
	v_mfma_f32_16x16x32_bf16 v[42:45], v[160:163], v[184:187], v[42:45]
	v_mfma_f32_16x16x32_bf16 v[42:45], v[164:167], v[188:191], v[42:45]
	v_mfma_f32_16x16x32_bf16 v[38:41], v[152:155], v[184:187], v[38:41]
	v_mfma_f32_16x16x32_bf16 v[38:41], v[156:159], v[188:191], v[38:41]
	v_mfma_f32_16x16x32_bf16 v[46:49], v[144:147], v[184:187], v[46:49]
	v_mfma_f32_16x16x32_bf16 v[46:49], v[148:151], v[188:191], v[46:49]
	v_mfma_f32_16x16x32_bf16 v[30:33], v[144:147], v[192:195], v[30:33]
	v_mfma_f32_16x16x32_bf16 v[30:33], v[148:151], v[196:199], v[30:33]
	v_mfma_f32_16x16x32_bf16 v[22:25], v[152:155], v[192:195], v[22:25]
	v_mfma_f32_16x16x32_bf16 v[22:25], v[156:159], v[196:199], v[22:25]
	v_mfma_f32_16x16x32_bf16 v[26:29], v[160:163], v[192:195], v[26:29]
	v_mfma_f32_16x16x32_bf16 v[26:29], v[164:167], v[196:199], v[26:29]
	v_mfma_f32_16x16x32_bf16 v[18:21], v[168:171], v[192:195], v[18:21]
	v_mfma_f32_16x16x32_bf16 v[18:21], v[172:175], v[196:199], v[18:21]
	v_mfma_f32_16x16x32_bf16 v[2:5], v[168:171], v[200:203], v[2:5]
	v_mfma_f32_16x16x32_bf16 v[2:5], v[172:175], v[204:207], v[2:5]
	v_mfma_f32_16x16x32_bf16 v[10:13], v[160:163], v[200:203], v[10:13]
	v_mfma_f32_16x16x32_bf16 v[10:13], v[164:167], v[204:207], v[10:13]
	v_mfma_f32_16x16x32_bf16 v[6:9], v[152:155], v[200:203], v[6:9]
	v_mfma_f32_16x16x32_bf16 v[6:9], v[156:159], v[204:207], v[6:9]
	v_mfma_f32_16x16x32_bf16 v[14:17], v[144:147], v[200:203], v[14:17]
	v_mfma_f32_16x16x32_bf16 v[14:17], v[148:151], v[204:207], v[14:17]
	s_setprio 0
	s_barrier
	s_nop 7
	s_nop 7
	s_nop 7
	ds_read_b128 v[144:147], v141
	ds_read_b128 v[148:151], v141 offset:1024
	ds_read_b128 v[152:155], v141 offset:2048
	ds_read_b128 v[156:159], v141 offset:3072
	ds_read_b128 v[160:163], v142
	ds_read_b128 v[164:167], v142 offset:1024
	ds_read_b128 v[168:171], v142 offset:2048
	ds_read_b128 v[172:175], v142 offset:3072
	s_mov_b32 m0, s50
	s_add_i32 s80, s77, 0x100000
	ds_read_b128 v[176:179], v140 offset:32768
	ds_read_b128 v[180:183], v140 offset:33792
	ds_read_b128 v[184:187], v140 offset:34816
	ds_read_b128 v[188:191], v140 offset:35840
	ds_read_b128 v[192:195], v140 offset:36864
	ds_read_b128 v[196:199], v140 offset:37888
	ds_read_b128 v[200:203], v140 offset:38912
	ds_read_b128 v[204:207], v140 offset:39936
	buffer_load_dwordx4 v136, s[16:19], s80 offen lds
	s_add_i32 s80, s77, 0x180000
	s_mov_b32 m0, s51
	s_nop 0
	buffer_load_dwordx4 v136, s[16:19], s80 offen lds
	s_waitcnt vmcnt(8)
	s_waitcnt lgkmcnt(0)
	s_setprio 1
	v_mfma_f32_16x16x32_bf16 v[118:121], v[144:147], v[176:179], v[118:121]
	s_barrier
	v_mfma_f32_16x16x32_bf16 v[118:121], v[148:151], v[180:183], v[118:121]
	v_mfma_f32_16x16x32_bf16 v[114:117], v[152:155], v[176:179], v[114:117]
	v_mfma_f32_16x16x32_bf16 v[114:117], v[156:159], v[180:183], v[114:117]
	v_mfma_f32_16x16x32_bf16 v[126:129], v[160:163], v[176:179], v[126:129]
	v_mfma_f32_16x16x32_bf16 v[126:129], v[164:167], v[180:183], v[126:129]
	v_mfma_f32_16x16x32_bf16 v[122:125], v[168:171], v[176:179], v[122:125]
	v_mfma_f32_16x16x32_bf16 v[122:125], v[172:175], v[180:183], v[122:125]
	v_mfma_f32_16x16x32_bf16 v[98:101], v[168:171], v[184:187], v[98:101]
	v_mfma_f32_16x16x32_bf16 v[98:101], v[172:175], v[188:191], v[98:101]
	v_mfma_f32_16x16x32_bf16 v[106:109], v[160:163], v[184:187], v[106:109]
	v_mfma_f32_16x16x32_bf16 v[106:109], v[164:167], v[188:191], v[106:109]
	v_mfma_f32_16x16x32_bf16 v[102:105], v[152:155], v[184:187], v[102:105]
	v_mfma_f32_16x16x32_bf16 v[102:105], v[156:159], v[188:191], v[102:105]
	v_mfma_f32_16x16x32_bf16 v[110:113], v[144:147], v[184:187], v[110:113]
	v_mfma_f32_16x16x32_bf16 v[110:113], v[148:151], v[188:191], v[110:113]
	v_mfma_f32_16x16x32_bf16 v[94:97], v[144:147], v[192:195], v[94:97]
	v_mfma_f32_16x16x32_bf16 v[94:97], v[148:151], v[196:199], v[94:97]
	v_mfma_f32_16x16x32_bf16 v[86:89], v[152:155], v[192:195], v[86:89]
	v_mfma_f32_16x16x32_bf16 v[86:89], v[156:159], v[196:199], v[86:89]
	v_mfma_f32_16x16x32_bf16 v[90:93], v[160:163], v[192:195], v[90:93]
	v_mfma_f32_16x16x32_bf16 v[90:93], v[164:167], v[196:199], v[90:93]
	v_mfma_f32_16x16x32_bf16 v[82:85], v[168:171], v[192:195], v[82:85]
	v_mfma_f32_16x16x32_bf16 v[82:85], v[172:175], v[196:199], v[82:85]
	v_mfma_f32_16x16x32_bf16 v[70:73], v[168:171], v[200:203], v[70:73]
	v_mfma_f32_16x16x32_bf16 v[70:73], v[172:175], v[204:207], v[70:73]
	v_mfma_f32_16x16x32_bf16 v[74:77], v[160:163], v[200:203], v[74:77]
	v_mfma_f32_16x16x32_bf16 v[74:77], v[164:167], v[204:207], v[74:77]
	v_mfma_f32_16x16x32_bf16 v[66:69], v[152:155], v[200:203], v[66:69]
	v_mfma_f32_16x16x32_bf16 v[66:69], v[156:159], v[204:207], v[66:69]
	v_mfma_f32_16x16x32_bf16 v[78:81], v[144:147], v[200:203], v[78:81]
	v_mfma_f32_16x16x32_bf16 v[78:81], v[148:151], v[204:207], v[78:81]
	s_setprio 0
	s_barrier
	s_mov_b32 m0, s53
	s_or_b32 s80, s79, 0x80
	ds_read_b128 v[176:179], v140 offset:49152
	ds_read_b128 v[180:183], v140 offset:50176
	ds_read_b128 v[184:187], v140 offset:51200
	ds_read_b128 v[188:191], v140 offset:52224
	ds_read_b128 v[192:195], v140 offset:53248
	ds_read_b128 v[196:199], v140 offset:54272
	ds_read_b128 v[200:203], v140 offset:55296
	ds_read_b128 v[204:207], v140 offset:56320
	buffer_load_dwordx4 v137, s[12:15], s80 offen lds
	s_add_i32 s80, s79, 0x80080
	s_mov_b32 m0, s54
	s_add_i32 s77, s77, 0x80080
	buffer_load_dwordx4 v137, s[12:15], s80 offen lds
	s_add_i32 s80, s79, 0x100080
	s_mov_b32 m0, s57
	s_add_i32 s79, s79, 0x180080
	buffer_load_dwordx4 v137, s[12:15], s80 offen lds
	s_mov_b32 m0, s58
	s_nop 0
	buffer_load_dwordx4 v137, s[12:15], s79 offen lds
	s_mov_b32 m0, s55
	s_nop 0
	buffer_load_dwordx4 v136, s[16:19], s78 offen lds
	s_mov_b32 m0, s56
	s_nop 0
	buffer_load_dwordx4 v136, s[16:19], s77 offen lds
	s_waitcnt vmcnt(8)
	s_waitcnt lgkmcnt(0)
	s_setprio 1
	v_mfma_f32_16x16x32_bf16 v[62:65], v[144:147], v[176:179], v[62:65]
	s_barrier
	v_mfma_f32_16x16x32_bf16 v[62:65], v[148:151], v[180:183], v[62:65]
	v_mfma_f32_16x16x32_bf16 v[54:57], v[152:155], v[176:179], v[54:57]
	v_mfma_f32_16x16x32_bf16 v[54:57], v[156:159], v[180:183], v[54:57]
	v_mfma_f32_16x16x32_bf16 v[58:61], v[160:163], v[176:179], v[58:61]
	v_mfma_f32_16x16x32_bf16 v[58:61], v[164:167], v[180:183], v[58:61]
	v_mfma_f32_16x16x32_bf16 v[50:53], v[168:171], v[176:179], v[50:53]
	v_mfma_f32_16x16x32_bf16 v[50:53], v[172:175], v[180:183], v[50:53]
	v_mfma_f32_16x16x32_bf16 v[34:37], v[168:171], v[184:187], v[34:37]
	v_mfma_f32_16x16x32_bf16 v[34:37], v[172:175], v[188:191], v[34:37]
	v_mfma_f32_16x16x32_bf16 v[42:45], v[160:163], v[184:187], v[42:45]
	v_mfma_f32_16x16x32_bf16 v[42:45], v[164:167], v[188:191], v[42:45]
	v_mfma_f32_16x16x32_bf16 v[38:41], v[152:155], v[184:187], v[38:41]
	v_mfma_f32_16x16x32_bf16 v[38:41], v[156:159], v[188:191], v[38:41]
	v_mfma_f32_16x16x32_bf16 v[46:49], v[144:147], v[184:187], v[46:49]
	v_mfma_f32_16x16x32_bf16 v[46:49], v[148:151], v[188:191], v[46:49]
	v_mfma_f32_16x16x32_bf16 v[30:33], v[144:147], v[192:195], v[30:33]
	v_mfma_f32_16x16x32_bf16 v[30:33], v[148:151], v[196:199], v[30:33]
	v_mfma_f32_16x16x32_bf16 v[22:25], v[152:155], v[192:195], v[22:25]
	v_mfma_f32_16x16x32_bf16 v[22:25], v[156:159], v[196:199], v[22:25]
	v_mfma_f32_16x16x32_bf16 v[26:29], v[160:163], v[192:195], v[26:29]
	v_mfma_f32_16x16x32_bf16 v[26:29], v[164:167], v[196:199], v[26:29]
	v_mfma_f32_16x16x32_bf16 v[18:21], v[168:171], v[192:195], v[18:21]
	v_mfma_f32_16x16x32_bf16 v[18:21], v[172:175], v[196:199], v[18:21]
	v_mfma_f32_16x16x32_bf16 v[2:5], v[168:171], v[200:203], v[2:5]
	v_mfma_f32_16x16x32_bf16 v[2:5], v[172:175], v[204:207], v[2:5]
	v_mfma_f32_16x16x32_bf16 v[10:13], v[160:163], v[200:203], v[10:13]
	v_mfma_f32_16x16x32_bf16 v[10:13], v[164:167], v[204:207], v[10:13]
	v_mfma_f32_16x16x32_bf16 v[6:9], v[152:155], v[200:203], v[6:9]
	v_mfma_f32_16x16x32_bf16 v[6:9], v[156:159], v[204:207], v[6:9]
	v_mfma_f32_16x16x32_bf16 v[14:17], v[144:147], v[200:203], v[14:17]
	v_mfma_f32_16x16x32_bf16 v[14:17], v[148:151], v[204:207], v[14:17]
	s_setprio 0
	s_barrier
	s_nop 7
	s_nop 7
	s_nop 7
	s_add_i32 s76, s76, 2
	s_addk_i32 s74, 0x100
	s_addk_i32 s75, 0x100
	s_cmp_ge_i32 s76, s27
	s_cbranch_scc0 .LBB0_1382
	s_and_b64 vcc, exec, s[42:43]
	s_cbranch_vccz .LBB0_1385

.LBB0_1402:
	ds_read_b128 v[146:149], v138
	ds_read_b128 v[150:153], v138 offset:1024
	ds_read_b128 v[154:157], v138 offset:2048
	ds_read_b128 v[158:161], v138 offset:3072
	ds_read_b128 v[162:165], v139
	ds_read_b128 v[166:169], v139 offset:1024
	ds_read_b128 v[170:173], v139 offset:2048
	ds_read_b128 v[174:177], v139 offset:3072
	s_add_i32 s22, s75, 0xffe80080
	s_cmp_eq_u32 s62, s77
	s_cselect_b32 s78, s73, s22
	s_cselect_b32 s80, s74, s76
	s_or_b32 s79, s78, 0x80
	s_add_i32 s22, s75, 0xfff80000
	s_mov_b32 m0, s63
	ds_read_b128 v[178:181], v140
	ds_read_b128 v[182:185], v140 offset:1024
	ds_read_b128 v[186:189], v140 offset:2048
	ds_read_b128 v[190:193], v140 offset:3072
	ds_read_b128 v[194:197], v140 offset:4096
	ds_read_b128 v[198:201], v140 offset:5120
	ds_read_b128 v[202:205], v140 offset:6144
	ds_read_b128 v[206:209], v140 offset:7168
	buffer_load_dwordx4 v136, s[16:19], s22 offen lds
	s_mov_b32 m0, s64
	s_nop 0
	buffer_load_dwordx4 v136, s[16:19], s75 offen lds
	s_waitcnt vmcnt(8)
	s_waitcnt lgkmcnt(0)
	s_setprio 1
	v_mfma_f32_16x16x32_bf16 v[118:121], v[146:149], v[178:181], v[118:121]
	s_barrier
	v_mfma_f32_16x16x32_bf16 v[118:121], v[150:153], v[182:185], v[118:121]
	v_mfma_f32_16x16x32_bf16 v[114:117], v[154:157], v[178:181], v[114:117]
	v_mfma_f32_16x16x32_bf16 v[114:117], v[158:161], v[182:185], v[114:117]
	v_mfma_f32_16x16x32_bf16 v[126:129], v[162:165], v[178:181], v[126:129]
	v_mfma_f32_16x16x32_bf16 v[126:129], v[166:169], v[182:185], v[126:129]
	v_mfma_f32_16x16x32_bf16 v[122:125], v[170:173], v[178:181], v[122:125]
	v_mfma_f32_16x16x32_bf16 v[122:125], v[174:177], v[182:185], v[122:125]
	v_mfma_f32_16x16x32_bf16 v[98:101], v[170:173], v[186:189], v[98:101]
	v_mfma_f32_16x16x32_bf16 v[98:101], v[174:177], v[190:193], v[98:101]
	v_mfma_f32_16x16x32_bf16 v[106:109], v[162:165], v[186:189], v[106:109]
	v_mfma_f32_16x16x32_bf16 v[106:109], v[166:169], v[190:193], v[106:109]
	v_mfma_f32_16x16x32_bf16 v[102:105], v[154:157], v[186:189], v[102:105]
	v_mfma_f32_16x16x32_bf16 v[102:105], v[158:161], v[190:193], v[102:105]
	v_mfma_f32_16x16x32_bf16 v[110:113], v[146:149], v[186:189], v[110:113]
	v_mfma_f32_16x16x32_bf16 v[110:113], v[150:153], v[190:193], v[110:113]
	v_mfma_f32_16x16x32_bf16 v[94:97], v[146:149], v[194:197], v[94:97]
	v_mfma_f32_16x16x32_bf16 v[94:97], v[150:153], v[198:201], v[94:97]
	v_mfma_f32_16x16x32_bf16 v[86:89], v[154:157], v[194:197], v[86:89]
	v_mfma_f32_16x16x32_bf16 v[86:89], v[158:161], v[198:201], v[86:89]
	v_mfma_f32_16x16x32_bf16 v[90:93], v[162:165], v[194:197], v[90:93]
	v_mfma_f32_16x16x32_bf16 v[90:93], v[166:169], v[198:201], v[90:93]
	v_mfma_f32_16x16x32_bf16 v[82:85], v[170:173], v[194:197], v[82:85]
	v_mfma_f32_16x16x32_bf16 v[82:85], v[174:177], v[198:201], v[82:85]
	v_mfma_f32_16x16x32_bf16 v[70:73], v[170:173], v[202:205], v[70:73]
	v_mfma_f32_16x16x32_bf16 v[70:73], v[174:177], v[206:209], v[70:73]
	v_mfma_f32_16x16x32_bf16 v[74:77], v[162:165], v[202:205], v[74:77]
	v_mfma_f32_16x16x32_bf16 v[74:77], v[166:169], v[206:209], v[74:77]
	v_mfma_f32_16x16x32_bf16 v[66:69], v[154:157], v[202:205], v[66:69]
	v_mfma_f32_16x16x32_bf16 v[66:69], v[158:161], v[206:209], v[66:69]
	v_mfma_f32_16x16x32_bf16 v[78:81], v[146:149], v[202:205], v[78:81]
	v_mfma_f32_16x16x32_bf16 v[78:81], v[150:153], v[206:209], v[78:81]
	s_setprio 0
	s_barrier
	s_mov_b32 m0, s31
	s_mov_b32 s22, s18
	s_mov_b32 s23, s19
	ds_read_b128 v[178:181], v140 offset:16384
	ds_read_b128 v[182:185], v140 offset:17408
	ds_read_b128 v[186:189], v140 offset:18432
	ds_read_b128 v[190:193], v140 offset:19456
	ds_read_b128 v[194:197], v140 offset:20480
	ds_read_b128 v[198:201], v140 offset:21504
	ds_read_b128 v[202:205], v140 offset:22528
	ds_read_b128 v[206:209], v140 offset:23552
	buffer_load_dwordx4 v137, s[20:23], s80 offen lds
	s_add_i32 s81, s80, 0x80000
	s_mov_b32 m0, s48
	s_nop 0
	buffer_load_dwordx4 v137, s[20:23], s81 offen lds
	s_add_i32 s81, s80, 0x100000
	s_mov_b32 m0, s49
	s_nop 0
	buffer_load_dwordx4 v137, s[20:23], s81 offen lds
	s_add_i32 s81, s80, 0x180000
	s_mov_b32 m0, s50
	s_nop 0
	buffer_load_dwordx4 v137, s[20:23], s81 offen lds
	s_mov_b32 m0, s30
	s_add_i32 s81, s78, 0x80000
	buffer_load_dwordx4 v136, s[16:19], s78 offen lds
	s_mov_b32 m0, s51
	s_nop 0
	buffer_load_dwordx4 v136, s[16:19], s81 offen lds
	s_waitcnt vmcnt(8)
	s_waitcnt lgkmcnt(0)
	s_setprio 1
	v_mfma_f32_16x16x32_bf16 v[62:65], v[146:149], v[178:181], v[62:65]
	s_barrier
	v_mfma_f32_16x16x32_bf16 v[62:65], v[150:153], v[182:185], v[62:65]
	v_mfma_f32_16x16x32_bf16 v[54:57], v[154:157], v[178:181], v[54:57]
	v_mfma_f32_16x16x32_bf16 v[54:57], v[158:161], v[182:185], v[54:57]
	v_mfma_f32_16x16x32_bf16 v[58:61], v[162:165], v[178:181], v[58:61]
	v_mfma_f32_16x16x32_bf16 v[58:61], v[166:169], v[182:185], v[58:61]
	v_mfma_f32_16x16x32_bf16 v[50:53], v[170:173], v[178:181], v[50:53]
	v_mfma_f32_16x16x32_bf16 v[50:53], v[174:177], v[182:185], v[50:53]
	v_mfma_f32_16x16x32_bf16 v[34:37], v[170:173], v[186:189], v[34:37]
	v_mfma_f32_16x16x32_bf16 v[34:37], v[174:177], v[190:193], v[34:37]
	v_mfma_f32_16x16x32_bf16 v[42:45], v[162:165], v[186:189], v[42:45]
	v_mfma_f32_16x16x32_bf16 v[42:45], v[166:169], v[190:193], v[42:45]
	v_mfma_f32_16x16x32_bf16 v[38:41], v[154:157], v[186:189], v[38:41]
	v_mfma_f32_16x16x32_bf16 v[38:41], v[158:161], v[190:193], v[38:41]
	v_mfma_f32_16x16x32_bf16 v[46:49], v[146:149], v[186:189], v[46:49]
	v_mfma_f32_16x16x32_bf16 v[46:49], v[150:153], v[190:193], v[46:49]
	v_mfma_f32_16x16x32_bf16 v[30:33], v[146:149], v[194:197], v[30:33]
	v_mfma_f32_16x16x32_bf16 v[30:33], v[150:153], v[198:201], v[30:33]
	v_mfma_f32_16x16x32_bf16 v[22:25], v[154:157], v[194:197], v[22:25]
	v_mfma_f32_16x16x32_bf16 v[22:25], v[158:161], v[198:201], v[22:25]
	v_mfma_f32_16x16x32_bf16 v[26:29], v[162:165], v[194:197], v[26:29]
	v_mfma_f32_16x16x32_bf16 v[26:29], v[166:169], v[198:201], v[26:29]
	v_mfma_f32_16x16x32_bf16 v[18:21], v[170:173], v[194:197], v[18:21]
	v_mfma_f32_16x16x32_bf16 v[18:21], v[174:177], v[198:201], v[18:21]
	v_mfma_f32_16x16x32_bf16 v[2:5], v[170:173], v[202:205], v[2:5]
	v_mfma_f32_16x16x32_bf16 v[2:5], v[174:177], v[206:209], v[2:5]
	v_mfma_f32_16x16x32_bf16 v[10:13], v[162:165], v[202:205], v[10:13]
	v_mfma_f32_16x16x32_bf16 v[10:13], v[166:169], v[206:209], v[10:13]
	v_mfma_f32_16x16x32_bf16 v[6:9], v[154:157], v[202:205], v[6:9]
	v_mfma_f32_16x16x32_bf16 v[6:9], v[158:161], v[206:209], v[6:9]
	v_mfma_f32_16x16x32_bf16 v[14:17], v[146:149], v[202:205], v[14:17]
	v_mfma_f32_16x16x32_bf16 v[14:17], v[150:153], v[206:209], v[14:17]
	s_setprio 0
	s_barrier
	s_nop 7
	s_nop 7
	s_nop 7
	ds_read_b128 v[146:149], v141
	ds_read_b128 v[150:153], v141 offset:1024
	ds_read_b128 v[154:157], v141 offset:2048
	ds_read_b128 v[158:161], v141 offset:3072
	ds_read_b128 v[162:165], v142
	ds_read_b128 v[166:169], v142 offset:1024
	ds_read_b128 v[170:173], v142 offset:2048
	ds_read_b128 v[174:177], v142 offset:3072
	s_mov_b32 m0, s52
	s_add_i32 s81, s78, 0x100000
	ds_read_b128 v[178:181], v140 offset:32768
	ds_read_b128 v[182:185], v140 offset:33792
	ds_read_b128 v[186:189], v140 offset:34816
	ds_read_b128 v[190:193], v140 offset:35840
	ds_read_b128 v[194:197], v140 offset:36864
	ds_read_b128 v[198:201], v140 offset:37888
	ds_read_b128 v[202:205], v140 offset:38912
	ds_read_b128 v[206:209], v140 offset:39936
	buffer_load_dwordx4 v136, s[16:19], s81 offen lds
	s_add_i32 s81, s78, 0x180000
	s_mov_b32 m0, s53
	s_nop 0
	buffer_load_dwordx4 v136, s[16:19], s81 offen lds
	s_waitcnt vmcnt(8)
	s_waitcnt lgkmcnt(0)
	s_setprio 1
	v_mfma_f32_16x16x32_bf16 v[118:121], v[146:149], v[178:181], v[118:121]
	s_barrier
	v_mfma_f32_16x16x32_bf16 v[118:121], v[150:153], v[182:185], v[118:121]
	v_mfma_f32_16x16x32_bf16 v[114:117], v[154:157], v[178:181], v[114:117]
	v_mfma_f32_16x16x32_bf16 v[114:117], v[158:161], v[182:185], v[114:117]
	v_mfma_f32_16x16x32_bf16 v[126:129], v[162:165], v[178:181], v[126:129]
	v_mfma_f32_16x16x32_bf16 v[126:129], v[166:169], v[182:185], v[126:129]
	v_mfma_f32_16x16x32_bf16 v[122:125], v[170:173], v[178:181], v[122:125]
	v_mfma_f32_16x16x32_bf16 v[122:125], v[174:177], v[182:185], v[122:125]
	v_mfma_f32_16x16x32_bf16 v[98:101], v[170:173], v[186:189], v[98:101]
	v_mfma_f32_16x16x32_bf16 v[98:101], v[174:177], v[190:193], v[98:101]
	v_mfma_f32_16x16x32_bf16 v[106:109], v[162:165], v[186:189], v[106:109]
	v_mfma_f32_16x16x32_bf16 v[106:109], v[166:169], v[190:193], v[106:109]
	v_mfma_f32_16x16x32_bf16 v[102:105], v[154:157], v[186:189], v[102:105]
	v_mfma_f32_16x16x32_bf16 v[102:105], v[158:161], v[190:193], v[102:105]
	v_mfma_f32_16x16x32_bf16 v[110:113], v[146:149], v[186:189], v[110:113]
	v_mfma_f32_16x16x32_bf16 v[110:113], v[150:153], v[190:193], v[110:113]
	v_mfma_f32_16x16x32_bf16 v[94:97], v[146:149], v[194:197], v[94:97]
	v_mfma_f32_16x16x32_bf16 v[94:97], v[150:153], v[198:201], v[94:97]
	v_mfma_f32_16x16x32_bf16 v[86:89], v[154:157], v[194:197], v[86:89]
	v_mfma_f32_16x16x32_bf16 v[86:89], v[158:161], v[198:201], v[86:89]
	v_mfma_f32_16x16x32_bf16 v[90:93], v[162:165], v[194:197], v[90:93]
	v_mfma_f32_16x16x32_bf16 v[90:93], v[166:169], v[198:201], v[90:93]
	v_mfma_f32_16x16x32_bf16 v[82:85], v[170:173], v[194:197], v[82:85]
	v_mfma_f32_16x16x32_bf16 v[82:85], v[174:177], v[198:201], v[82:85]
	v_mfma_f32_16x16x32_bf16 v[70:73], v[170:173], v[202:205], v[70:73]
	v_mfma_f32_16x16x32_bf16 v[70:73], v[174:177], v[206:209], v[70:73]
	v_mfma_f32_16x16x32_bf16 v[74:77], v[162:165], v[202:205], v[74:77]
	v_mfma_f32_16x16x32_bf16 v[74:77], v[166:169], v[206:209], v[74:77]
	v_mfma_f32_16x16x32_bf16 v[66:69], v[154:157], v[202:205], v[66:69]
	v_mfma_f32_16x16x32_bf16 v[66:69], v[158:161], v[206:209], v[66:69]
	v_mfma_f32_16x16x32_bf16 v[78:81], v[146:149], v[202:205], v[78:81]
	v_mfma_f32_16x16x32_bf16 v[78:81], v[150:153], v[206:209], v[78:81]
	s_setprio 0
	s_barrier
	s_mov_b32 m0, s54
	s_or_b32 s81, s80, 0x80
	ds_read_b128 v[178:181], v140 offset:49152
	ds_read_b128 v[182:185], v140 offset:50176
	ds_read_b128 v[186:189], v140 offset:51200
	ds_read_b128 v[190:193], v140 offset:52224
	ds_read_b128 v[194:197], v140 offset:53248
	ds_read_b128 v[198:201], v140 offset:54272
	ds_read_b128 v[202:205], v140 offset:55296
	ds_read_b128 v[206:209], v140 offset:56320
	buffer_load_dwordx4 v137, s[20:23], s81 offen lds
	s_add_i32 s81, s80, 0x80080
	s_mov_b32 m0, s55
	s_add_i32 s78, s78, 0x80080
	buffer_load_dwordx4 v137, s[20:23], s81 offen lds
	s_add_i32 s81, s80, 0x100080
	s_mov_b32 m0, s58
	s_add_i32 s80, s80, 0x180080
	buffer_load_dwordx4 v137, s[20:23], s81 offen lds
	s_mov_b32 m0, s59
	s_nop 0
	buffer_load_dwordx4 v137, s[20:23], s80 offen lds
	s_mov_b32 m0, s56
	s_nop 0
	buffer_load_dwordx4 v136, s[16:19], s79 offen lds
	s_mov_b32 m0, s57
	s_nop 0
	buffer_load_dwordx4 v136, s[16:19], s78 offen lds
	s_waitcnt vmcnt(8)
	s_waitcnt lgkmcnt(0)
	s_setprio 1
	v_mfma_f32_16x16x32_bf16 v[62:65], v[146:149], v[178:181], v[62:65]
	s_barrier
	v_mfma_f32_16x16x32_bf16 v[62:65], v[150:153], v[182:185], v[62:65]
	v_mfma_f32_16x16x32_bf16 v[54:57], v[154:157], v[178:181], v[54:57]
	v_mfma_f32_16x16x32_bf16 v[54:57], v[158:161], v[182:185], v[54:57]
	v_mfma_f32_16x16x32_bf16 v[58:61], v[162:165], v[178:181], v[58:61]
	v_mfma_f32_16x16x32_bf16 v[58:61], v[166:169], v[182:185], v[58:61]
	v_mfma_f32_16x16x32_bf16 v[50:53], v[170:173], v[178:181], v[50:53]
	v_mfma_f32_16x16x32_bf16 v[50:53], v[174:177], v[182:185], v[50:53]
	v_mfma_f32_16x16x32_bf16 v[34:37], v[170:173], v[186:189], v[34:37]
	v_mfma_f32_16x16x32_bf16 v[34:37], v[174:177], v[190:193], v[34:37]
	v_mfma_f32_16x16x32_bf16 v[42:45], v[162:165], v[186:189], v[42:45]
	v_mfma_f32_16x16x32_bf16 v[42:45], v[166:169], v[190:193], v[42:45]
	v_mfma_f32_16x16x32_bf16 v[38:41], v[154:157], v[186:189], v[38:41]
	v_mfma_f32_16x16x32_bf16 v[38:41], v[158:161], v[190:193], v[38:41]
	v_mfma_f32_16x16x32_bf16 v[46:49], v[146:149], v[186:189], v[46:49]
	v_mfma_f32_16x16x32_bf16 v[46:49], v[150:153], v[190:193], v[46:49]
	v_mfma_f32_16x16x32_bf16 v[30:33], v[146:149], v[194:197], v[30:33]
	v_mfma_f32_16x16x32_bf16 v[30:33], v[150:153], v[198:201], v[30:33]
	v_mfma_f32_16x16x32_bf16 v[22:25], v[154:157], v[194:197], v[22:25]
	v_mfma_f32_16x16x32_bf16 v[22:25], v[158:161], v[198:201], v[22:25]
	v_mfma_f32_16x16x32_bf16 v[26:29], v[162:165], v[194:197], v[26:29]
	v_mfma_f32_16x16x32_bf16 v[26:29], v[166:169], v[198:201], v[26:29]
	v_mfma_f32_16x16x32_bf16 v[18:21], v[170:173], v[194:197], v[18:21]
	v_mfma_f32_16x16x32_bf16 v[18:21], v[174:177], v[198:201], v[18:21]
	v_mfma_f32_16x16x32_bf16 v[2:5], v[170:173], v[202:205], v[2:5]
	v_mfma_f32_16x16x32_bf16 v[2:5], v[174:177], v[206:209], v[2:5]
	v_mfma_f32_16x16x32_bf16 v[10:13], v[162:165], v[202:205], v[10:13]
	v_mfma_f32_16x16x32_bf16 v[10:13], v[166:169], v[206:209], v[10:13]
	v_mfma_f32_16x16x32_bf16 v[6:9], v[154:157], v[202:205], v[6:9]
	v_mfma_f32_16x16x32_bf16 v[6:9], v[158:161], v[206:209], v[6:9]
	v_mfma_f32_16x16x32_bf16 v[14:17], v[146:149], v[202:205], v[14:17]
	v_mfma_f32_16x16x32_bf16 v[14:17], v[150:153], v[206:209], v[14:17]
	s_setprio 0
	s_barrier
	s_nop 7
	s_nop 7
	s_nop 7
	s_add_i32 s77, s77, 2
	s_addk_i32 s75, 0x100
	s_addk_i32 s76, 0x100
	s_cmp_ge_i32 s77, s13
	s_cbranch_scc0 .LBB0_1402
	s_and_b64 vcc, exec, s[46:47]
	s_cbranch_vccz .LBB0_1405

.LBB0_1519:
	ds_read_b128 v[134:137], v208
	ds_read_b128 v[138:141], v208 offset:1024
	ds_read_b128 v[142:145], v208 offset:2048
	ds_read_b128 v[146:149], v208 offset:3072
	ds_read_b128 v[150:153], v209
	ds_read_b128 v[154:157], v209 offset:1024
	ds_read_b128 v[158:161], v209 offset:2048
	ds_read_b128 v[162:165], v209 offset:3072
	s_add_i32 s18, s80, 0xffbf8080
	s_cmp_eq_u32 s65, s82
	s_cselect_b32 s83, s6, s18
	s_cselect_b32 s85, s7, s81
	s_or_b32 s84, s83, 0x80
	s_add_i32 s18, s80, 0xffea8000
	s_mov_b32 m0, s66
	ds_read_b128 v[166:169], v210
	ds_read_b128 v[170:173], v210 offset:1024
	ds_read_b128 v[174:177], v210 offset:2048
	ds_read_b128 v[178:181], v210 offset:3072
	ds_read_b128 v[182:185], v210 offset:4096
	ds_read_b128 v[186:189], v210 offset:5120
	ds_read_b128 v[190:193], v210 offset:6144
	ds_read_b128 v[194:197], v210 offset:7168
	buffer_load_dwordx4 v206, s[12:15], s18 offen lds
	s_mov_b32 m0, s69
	s_nop 0
	buffer_load_dwordx4 v206, s[12:15], s80 offen lds
	s_waitcnt vmcnt(8)
	s_waitcnt lgkmcnt(0)
	s_setprio 1
	v_mfma_f32_16x16x32_bf16 v[126:129], v[134:137], v[166:169], v[126:129]
	s_barrier
	v_mfma_f32_16x16x32_bf16 v[126:129], v[138:141], v[170:173], v[126:129]
	v_mfma_f32_16x16x32_bf16 v[122:125], v[142:145], v[166:169], v[122:125]
	v_mfma_f32_16x16x32_bf16 v[122:125], v[146:149], v[170:173], v[122:125]
	v_mfma_f32_16x16x32_bf16 v[110:113], v[150:153], v[166:169], v[110:113]
	v_mfma_f32_16x16x32_bf16 v[110:113], v[154:157], v[170:173], v[110:113]
	v_mfma_f32_16x16x32_bf16 v[102:105], v[158:161], v[166:169], v[102:105]
	v_mfma_f32_16x16x32_bf16 v[102:105], v[162:165], v[170:173], v[102:105]
	v_mfma_f32_16x16x32_bf16 v[86:89], v[158:161], v[174:177], v[86:89]
	v_mfma_f32_16x16x32_bf16 v[86:89], v[162:165], v[178:181], v[86:89]
	v_mfma_f32_16x16x32_bf16 v[94:97], v[150:153], v[174:177], v[94:97]
	v_mfma_f32_16x16x32_bf16 v[94:97], v[154:157], v[178:181], v[94:97]
	v_mfma_f32_16x16x32_bf16 v[114:117], v[142:145], v[174:177], v[114:117]
	v_mfma_f32_16x16x32_bf16 v[114:117], v[146:149], v[178:181], v[114:117]
	v_mfma_f32_16x16x32_bf16 v[118:121], v[134:137], v[174:177], v[118:121]
	v_mfma_f32_16x16x32_bf16 v[118:121], v[138:141], v[178:181], v[118:121]
	v_mfma_f32_16x16x32_bf16 v[106:109], v[134:137], v[182:185], v[106:109]
	v_mfma_f32_16x16x32_bf16 v[106:109], v[138:141], v[186:189], v[106:109]
	v_mfma_f32_16x16x32_bf16 v[98:101], v[142:145], v[182:185], v[98:101]
	v_mfma_f32_16x16x32_bf16 v[98:101], v[146:149], v[186:189], v[98:101]
	v_mfma_f32_16x16x32_bf16 v[78:81], v[150:153], v[182:185], v[78:81]
	v_mfma_f32_16x16x32_bf16 v[78:81], v[154:157], v[186:189], v[78:81]
	v_mfma_f32_16x16x32_bf16 v[74:77], v[158:161], v[182:185], v[74:77]
	v_mfma_f32_16x16x32_bf16 v[74:77], v[162:165], v[186:189], v[74:77]
	v_mfma_f32_16x16x32_bf16 v[66:69], v[158:161], v[190:193], v[66:69]
	v_mfma_f32_16x16x32_bf16 v[66:69], v[162:165], v[194:197], v[66:69]
	v_mfma_f32_16x16x32_bf16 v[70:73], v[150:153], v[190:193], v[70:73]
	v_mfma_f32_16x16x32_bf16 v[70:73], v[154:157], v[194:197], v[70:73]
	v_mfma_f32_16x16x32_bf16 v[82:85], v[142:145], v[190:193], v[82:85]
	v_mfma_f32_16x16x32_bf16 v[82:85], v[146:149], v[194:197], v[82:85]
	v_mfma_f32_16x16x32_bf16 v[90:93], v[134:137], v[190:193], v[90:93]
	v_mfma_f32_16x16x32_bf16 v[90:93], v[138:141], v[194:197], v[90:93]
	s_setprio 0
	s_barrier
	s_mov_b32 m0, s27
	s_mov_b32 s18, s14
	s_mov_b32 s19, s15
	ds_read_b128 v[166:169], v210 offset:16384
	ds_read_b128 v[170:173], v210 offset:17408
	ds_read_b128 v[174:177], v210 offset:18432
	ds_read_b128 v[178:181], v210 offset:19456
	ds_read_b128 v[182:185], v210 offset:20480
	ds_read_b128 v[186:189], v210 offset:21504
	ds_read_b128 v[190:193], v210 offset:22528
	ds_read_b128 v[194:197], v210 offset:23552
	buffer_load_dwordx4 v207, s[16:19], s85 offen lds
	s_add_i32 s86, s85, 0x158000
	s_mov_b32 m0, s30
	s_nop 0
	buffer_load_dwordx4 v207, s[16:19], s86 offen lds
	s_add_i32 s86, s85, 0x2b0000
	s_mov_b32 m0, s31
	s_nop 0
	buffer_load_dwordx4 v207, s[16:19], s86 offen lds
	s_add_i32 s86, s85, 0x408000
	s_mov_b32 m0, s50
	s_nop 0
	buffer_load_dwordx4 v207, s[16:19], s86 offen lds
	s_mov_b32 m0, s25
	s_add_i32 s86, s83, 0x158000
	buffer_load_dwordx4 v206, s[12:15], s83 offen lds
	s_mov_b32 m0, s51
	s_nop 0
	buffer_load_dwordx4 v206, s[12:15], s86 offen lds
	s_waitcnt vmcnt(8)
	s_waitcnt lgkmcnt(0)
	s_setprio 1
	v_mfma_f32_16x16x32_bf16 v[62:65], v[134:137], v[166:169], v[62:65]
	s_barrier
	v_mfma_f32_16x16x32_bf16 v[62:65], v[138:141], v[170:173], v[62:65]
	v_mfma_f32_16x16x32_bf16 v[58:61], v[142:145], v[166:169], v[58:61]
	v_mfma_f32_16x16x32_bf16 v[58:61], v[146:149], v[170:173], v[58:61]
	v_mfma_f32_16x16x32_bf16 v[46:49], v[150:153], v[166:169], v[46:49]
	v_mfma_f32_16x16x32_bf16 v[46:49], v[154:157], v[170:173], v[46:49]
	v_mfma_f32_16x16x32_bf16 v[38:41], v[158:161], v[166:169], v[38:41]
	v_mfma_f32_16x16x32_bf16 v[38:41], v[162:165], v[170:173], v[38:41]
	v_mfma_f32_16x16x32_bf16 v[22:25], v[158:161], v[174:177], v[22:25]
	v_mfma_f32_16x16x32_bf16 v[22:25], v[162:165], v[178:181], v[22:25]
	v_mfma_f32_16x16x32_bf16 v[30:33], v[150:153], v[174:177], v[30:33]
	v_mfma_f32_16x16x32_bf16 v[30:33], v[154:157], v[178:181], v[30:33]
	v_mfma_f32_16x16x32_bf16 v[50:53], v[142:145], v[174:177], v[50:53]
	v_mfma_f32_16x16x32_bf16 v[50:53], v[146:149], v[178:181], v[50:53]
	v_mfma_f32_16x16x32_bf16 v[54:57], v[134:137], v[174:177], v[54:57]
	v_mfma_f32_16x16x32_bf16 v[54:57], v[138:141], v[178:181], v[54:57]
	v_mfma_f32_16x16x32_bf16 v[42:45], v[134:137], v[182:185], v[42:45]
	v_mfma_f32_16x16x32_bf16 v[42:45], v[138:141], v[186:189], v[42:45]
	v_mfma_f32_16x16x32_bf16 v[34:37], v[142:145], v[182:185], v[34:37]
	v_mfma_f32_16x16x32_bf16 v[34:37], v[146:149], v[186:189], v[34:37]
	v_mfma_f32_16x16x32_bf16 v[14:17], v[150:153], v[182:185], v[14:17]
	v_mfma_f32_16x16x32_bf16 v[14:17], v[154:157], v[186:189], v[14:17]
	v_mfma_f32_16x16x32_bf16 v[10:13], v[158:161], v[182:185], v[10:13]
	v_mfma_f32_16x16x32_bf16 v[10:13], v[162:165], v[186:189], v[10:13]
	v_mfma_f32_16x16x32_bf16 v[2:5], v[158:161], v[190:193], v[2:5]
	v_mfma_f32_16x16x32_bf16 v[2:5], v[162:165], v[194:197], v[2:5]
	v_mfma_f32_16x16x32_bf16 v[6:9], v[150:153], v[190:193], v[6:9]
	v_mfma_f32_16x16x32_bf16 v[6:9], v[154:157], v[194:197], v[6:9]
	v_mfma_f32_16x16x32_bf16 v[18:21], v[142:145], v[190:193], v[18:21]
	v_mfma_f32_16x16x32_bf16 v[18:21], v[146:149], v[194:197], v[18:21]
	v_mfma_f32_16x16x32_bf16 v[26:29], v[134:137], v[190:193], v[26:29]
	v_mfma_f32_16x16x32_bf16 v[26:29], v[138:141], v[194:197], v[26:29]
	s_setprio 0
	s_barrier
	s_nop 7
	s_nop 7
	s_nop 7
	ds_read_b128 v[134:137], v211
	ds_read_b128 v[138:141], v211 offset:1024
	ds_read_b128 v[142:145], v211 offset:2048
	ds_read_b128 v[146:149], v211 offset:3072
	ds_read_b128 v[150:153], v212
	ds_read_b128 v[154:157], v212 offset:1024
	ds_read_b128 v[158:161], v212 offset:2048
	ds_read_b128 v[162:165], v212 offset:3072
	s_mov_b32 m0, s52
	s_add_i32 s86, s83, 0x2b0000
	ds_read_b128 v[166:169], v210 offset:32768
	ds_read_b128 v[170:173], v210 offset:33792
	ds_read_b128 v[174:177], v210 offset:34816
	ds_read_b128 v[178:181], v210 offset:35840
	ds_read_b128 v[182:185], v210 offset:36864
	ds_read_b128 v[186:189], v210 offset:37888
	ds_read_b128 v[190:193], v210 offset:38912
	ds_read_b128 v[194:197], v210 offset:39936
	buffer_load_dwordx4 v206, s[12:15], s86 offen lds
	s_add_i32 s86, s83, 0x408000
	s_mov_b32 m0, s53
	s_nop 0
	buffer_load_dwordx4 v206, s[12:15], s86 offen lds
	s_waitcnt vmcnt(8)
	s_waitcnt lgkmcnt(0)
	s_setprio 1
	v_mfma_f32_16x16x32_bf16 v[126:129], v[134:137], v[166:169], v[126:129]
	s_barrier
	v_mfma_f32_16x16x32_bf16 v[126:129], v[138:141], v[170:173], v[126:129]
	v_mfma_f32_16x16x32_bf16 v[122:125], v[142:145], v[166:169], v[122:125]
	v_mfma_f32_16x16x32_bf16 v[122:125], v[146:149], v[170:173], v[122:125]
	v_mfma_f32_16x16x32_bf16 v[110:113], v[150:153], v[166:169], v[110:113]
	v_mfma_f32_16x16x32_bf16 v[110:113], v[154:157], v[170:173], v[110:113]
	v_mfma_f32_16x16x32_bf16 v[102:105], v[158:161], v[166:169], v[102:105]
	v_mfma_f32_16x16x32_bf16 v[102:105], v[162:165], v[170:173], v[102:105]
	v_mfma_f32_16x16x32_bf16 v[86:89], v[158:161], v[174:177], v[86:89]
	v_mfma_f32_16x16x32_bf16 v[86:89], v[162:165], v[178:181], v[86:89]
	v_mfma_f32_16x16x32_bf16 v[94:97], v[150:153], v[174:177], v[94:97]
	v_mfma_f32_16x16x32_bf16 v[94:97], v[154:157], v[178:181], v[94:97]
	v_mfma_f32_16x16x32_bf16 v[114:117], v[142:145], v[174:177], v[114:117]
	v_mfma_f32_16x16x32_bf16 v[114:117], v[146:149], v[178:181], v[114:117]
	v_mfma_f32_16x16x32_bf16 v[118:121], v[134:137], v[174:177], v[118:121]
	v_mfma_f32_16x16x32_bf16 v[118:121], v[138:141], v[178:181], v[118:121]
	v_mfma_f32_16x16x32_bf16 v[106:109], v[134:137], v[182:185], v[106:109]
	v_mfma_f32_16x16x32_bf16 v[106:109], v[138:141], v[186:189], v[106:109]
	v_mfma_f32_16x16x32_bf16 v[98:101], v[142:145], v[182:185], v[98:101]
	v_mfma_f32_16x16x32_bf16 v[98:101], v[146:149], v[186:189], v[98:101]
	v_mfma_f32_16x16x32_bf16 v[78:81], v[150:153], v[182:185], v[78:81]
	v_mfma_f32_16x16x32_bf16 v[78:81], v[154:157], v[186:189], v[78:81]
	v_mfma_f32_16x16x32_bf16 v[74:77], v[158:161], v[182:185], v[74:77]
	v_mfma_f32_16x16x32_bf16 v[74:77], v[162:165], v[186:189], v[74:77]
	v_mfma_f32_16x16x32_bf16 v[66:69], v[158:161], v[190:193], v[66:69]
	v_mfma_f32_16x16x32_bf16 v[66:69], v[162:165], v[194:197], v[66:69]
	v_mfma_f32_16x16x32_bf16 v[70:73], v[150:153], v[190:193], v[70:73]
	v_mfma_f32_16x16x32_bf16 v[70:73], v[154:157], v[194:197], v[70:73]
	v_mfma_f32_16x16x32_bf16 v[82:85], v[142:145], v[190:193], v[82:85]
	v_mfma_f32_16x16x32_bf16 v[82:85], v[146:149], v[194:197], v[82:85]
	v_mfma_f32_16x16x32_bf16 v[90:93], v[134:137], v[190:193], v[90:93]
	v_mfma_f32_16x16x32_bf16 v[90:93], v[138:141], v[194:197], v[90:93]
	s_setprio 0
	s_barrier
	s_mov_b32 m0, s57
	s_or_b32 s86, s85, 0x80
	ds_read_b128 v[166:169], v210 offset:49152
	ds_read_b128 v[170:173], v210 offset:50176
	ds_read_b128 v[174:177], v210 offset:51200
	ds_read_b128 v[178:181], v210 offset:52224
	ds_read_b128 v[182:185], v210 offset:53248
	ds_read_b128 v[186:189], v210 offset:54272
	ds_read_b128 v[190:193], v210 offset:55296
	ds_read_b128 v[194:197], v210 offset:56320
	buffer_load_dwordx4 v207, s[16:19], s86 offen lds
	s_add_i32 s86, s85, 0x158080
	s_mov_b32 m0, s58
	s_add_i32 s83, s83, 0x158080
	buffer_load_dwordx4 v207, s[16:19], s86 offen lds
	s_add_i32 s86, s85, 0x2b0080
	s_mov_b32 m0, s61
	s_add_i32 s85, s85, 0x408080
	buffer_load_dwordx4 v207, s[16:19], s86 offen lds
	s_mov_b32 m0, s62
	s_nop 0
	buffer_load_dwordx4 v207, s[16:19], s85 offen lds
	s_mov_b32 m0, s59
	s_nop 0
	buffer_load_dwordx4 v206, s[12:15], s84 offen lds
	s_mov_b32 m0, s60
	s_nop 0
	buffer_load_dwordx4 v206, s[12:15], s83 offen lds
	s_waitcnt vmcnt(8)
	s_waitcnt lgkmcnt(0)
	s_setprio 1
	v_mfma_f32_16x16x32_bf16 v[62:65], v[134:137], v[166:169], v[62:65]
	s_barrier
	v_mfma_f32_16x16x32_bf16 v[62:65], v[138:141], v[170:173], v[62:65]
	v_mfma_f32_16x16x32_bf16 v[58:61], v[142:145], v[166:169], v[58:61]
	v_mfma_f32_16x16x32_bf16 v[58:61], v[146:149], v[170:173], v[58:61]
	v_mfma_f32_16x16x32_bf16 v[46:49], v[150:153], v[166:169], v[46:49]
	v_mfma_f32_16x16x32_bf16 v[46:49], v[154:157], v[170:173], v[46:49]
	v_mfma_f32_16x16x32_bf16 v[38:41], v[158:161], v[166:169], v[38:41]
	v_mfma_f32_16x16x32_bf16 v[38:41], v[162:165], v[170:173], v[38:41]
	v_mfma_f32_16x16x32_bf16 v[22:25], v[158:161], v[174:177], v[22:25]
	v_mfma_f32_16x16x32_bf16 v[22:25], v[162:165], v[178:181], v[22:25]
	v_mfma_f32_16x16x32_bf16 v[30:33], v[150:153], v[174:177], v[30:33]
	v_mfma_f32_16x16x32_bf16 v[30:33], v[154:157], v[178:181], v[30:33]
	v_mfma_f32_16x16x32_bf16 v[50:53], v[142:145], v[174:177], v[50:53]
	v_mfma_f32_16x16x32_bf16 v[50:53], v[146:149], v[178:181], v[50:53]
	v_mfma_f32_16x16x32_bf16 v[54:57], v[134:137], v[174:177], v[54:57]
	v_mfma_f32_16x16x32_bf16 v[54:57], v[138:141], v[178:181], v[54:57]
	v_mfma_f32_16x16x32_bf16 v[42:45], v[134:137], v[182:185], v[42:45]
	v_mfma_f32_16x16x32_bf16 v[42:45], v[138:141], v[186:189], v[42:45]
	v_mfma_f32_16x16x32_bf16 v[34:37], v[142:145], v[182:185], v[34:37]
	v_mfma_f32_16x16x32_bf16 v[34:37], v[146:149], v[186:189], v[34:37]
	v_mfma_f32_16x16x32_bf16 v[14:17], v[150:153], v[182:185], v[14:17]
	v_mfma_f32_16x16x32_bf16 v[14:17], v[154:157], v[186:189], v[14:17]
	v_mfma_f32_16x16x32_bf16 v[10:13], v[158:161], v[182:185], v[10:13]
	v_mfma_f32_16x16x32_bf16 v[10:13], v[162:165], v[186:189], v[10:13]
	v_mfma_f32_16x16x32_bf16 v[2:5], v[158:161], v[190:193], v[2:5]
	v_mfma_f32_16x16x32_bf16 v[2:5], v[162:165], v[194:197], v[2:5]
	v_mfma_f32_16x16x32_bf16 v[6:9], v[150:153], v[190:193], v[6:9]
	v_mfma_f32_16x16x32_bf16 v[6:9], v[154:157], v[194:197], v[6:9]
	v_mfma_f32_16x16x32_bf16 v[18:21], v[142:145], v[190:193], v[18:21]
	v_mfma_f32_16x16x32_bf16 v[18:21], v[146:149], v[194:197], v[18:21]
	v_mfma_f32_16x16x32_bf16 v[26:29], v[134:137], v[190:193], v[26:29]
	v_mfma_f32_16x16x32_bf16 v[26:29], v[138:141], v[194:197], v[26:29]
	s_setprio 0
	s_barrier
	s_nop 7
	s_nop 7
	s_nop 7
	s_add_i32 s82, s82, 2
	s_addk_i32 s80, 0x100
	s_addk_i32 s81, 0x100
	s_cmp_ge_i32 s82, s3
	s_cbranch_scc0 .LBB0_1519
	v_pk_mul_f32 v[182:183], v[128:129], 0.5 op_sel_hi:[1,0]
	v_pk_mul_f32 v[184:185], v[126:127], 0.5 op_sel_hi:[1,0]
	v_pk_mul_f32 v[186:187], v[124:125], 0.5 op_sel_hi:[1,0]
	v_pk_mul_f32 v[188:189], v[122:123], 0.5 op_sel_hi:[1,0]
	v_pk_mul_f32 v[196:197], v[112:113], 0.5 op_sel_hi:[1,0]
	v_pk_mul_f32 v[194:195], v[110:111], 0.5 op_sel_hi:[1,0]
	v_pk_mul_f32 v[192:193], v[104:105], 0.5 op_sel_hi:[1,0]
	v_pk_mul_f32 v[190:191], v[102:103], 0.5 op_sel_hi:[1,0]
	v_pk_mul_f32 v[180:181], v[120:121], 0.5 op_sel_hi:[1,0]
	v_pk_mul_f32 v[178:179], v[118:119], 0.5 op_sel_hi:[1,0]
	v_pk_mul_f32 v[176:177], v[116:117], 0.5 op_sel_hi:[1,0]
	v_pk_mul_f32 v[174:175], v[114:115], 0.5 op_sel_hi:[1,0]
	v_pk_mul_f32 v[170:171], v[96:97], 0.5 op_sel_hi:[1,0]
	v_pk_mul_f32 v[168:169], v[94:95], 0.5 op_sel_hi:[1,0]
	v_pk_mul_f32 v[166:167], v[88:89], 0.5 op_sel_hi:[1,0]
	v_pk_mul_f32 v[164:165], v[86:87], 0.5 op_sel_hi:[1,0]
	v_pk_mul_f32 v[162:163], v[108:109], 0.5 op_sel_hi:[1,0]
	v_pk_mul_f32 v[160:161], v[106:107], 0.5 op_sel_hi:[1,0]
	v_pk_mul_f32 v[158:159], v[100:101], 0.5 op_sel_hi:[1,0]
	v_pk_mul_f32 v[156:157], v[98:99], 0.5 op_sel_hi:[1,0]
	v_pk_mul_f32 v[154:155], v[80:81], 0.5 op_sel_hi:[1,0]
	v_pk_mul_f32 v[152:153], v[78:79], 0.5 op_sel_hi:[1,0]
	v_pk_mul_f32 v[150:151], v[76:77], 0.5 op_sel_hi:[1,0]
	v_pk_mul_f32 v[148:149], v[74:75], 0.5 op_sel_hi:[1,0]
	v_pk_mul_f32 v[144:145], v[92:93], 0.5 op_sel_hi:[1,0]
	v_pk_mul_f32 v[142:143], v[90:91], 0.5 op_sel_hi:[1,0]
	v_pk_mul_f32 v[140:141], v[84:85], 0.5 op_sel_hi:[1,0]
	v_pk_mul_f32 v[138:139], v[82:83], 0.5 op_sel_hi:[1,0]
	v_pk_mul_f32 v[136:137], v[72:73], 0.5 op_sel_hi:[1,0]
	v_pk_mul_f32 v[134:135], v[70:71], 0.5 op_sel_hi:[1,0]
	v_pk_mul_f32 v[128:129], v[68:69], 0.5 op_sel_hi:[1,0]
	v_pk_mul_f32 v[126:127], v[66:67], 0.5 op_sel_hi:[1,0]
	v_pk_mul_f32 v[122:123], v[64:65], 0.5 op_sel_hi:[1,0]
	v_pk_mul_f32 v[120:121], v[62:63], 0.5 op_sel_hi:[1,0]
	v_pk_mul_f32 v[118:119], v[60:61], 0.5 op_sel_hi:[1,0]
	v_pk_mul_f32 v[116:117], v[58:59], 0.5 op_sel_hi:[1,0]
	v_pk_mul_f32 v[112:113], v[48:49], 0.5 op_sel_hi:[1,0]
	v_pk_mul_f32 v[110:111], v[46:47], 0.5 op_sel_hi:[1,0]
	v_pk_mul_f32 v[108:109], v[40:41], 0.5 op_sel_hi:[1,0]
	v_pk_mul_f32 v[106:107], v[38:39], 0.5 op_sel_hi:[1,0]
	v_pk_mul_f32 v[104:105], v[56:57], 0.5 op_sel_hi:[1,0]
	v_pk_mul_f32 v[102:103], v[54:55], 0.5 op_sel_hi:[1,0]
	v_pk_mul_f32 v[100:101], v[52:53], 0.5 op_sel_hi:[1,0]
	v_pk_mul_f32 v[98:99], v[50:51], 0.5 op_sel_hi:[1,0]
	v_pk_mul_f32 v[96:97], v[32:33], 0.5 op_sel_hi:[1,0]
	v_pk_mul_f32 v[94:95], v[30:31], 0.5 op_sel_hi:[1,0]
	v_pk_mul_f32 v[92:93], v[24:25], 0.5 op_sel_hi:[1,0]
	v_pk_mul_f32 v[90:91], v[22:23], 0.5 op_sel_hi:[1,0]
	v_pk_mul_f32 v[88:89], v[44:45], 0.5 op_sel_hi:[1,0]
	v_pk_mul_f32 v[86:87], v[42:43], 0.5 op_sel_hi:[1,0]
	v_pk_mul_f32 v[84:85], v[36:37], 0.5 op_sel_hi:[1,0]
	v_pk_mul_f32 v[82:83], v[34:35], 0.5 op_sel_hi:[1,0]
	v_pk_mul_f32 v[80:81], v[16:17], 0.5 op_sel_hi:[1,0]
	v_pk_mul_f32 v[78:79], v[14:15], 0.5 op_sel_hi:[1,0]
	v_pk_mul_f32 v[76:77], v[12:13], 0.5 op_sel_hi:[1,0]
	v_pk_mul_f32 v[74:75], v[10:11], 0.5 op_sel_hi:[1,0]
	v_pk_mul_f32 v[72:73], v[28:29], 0.5 op_sel_hi:[1,0]
	v_pk_mul_f32 v[70:71], v[26:27], 0.5 op_sel_hi:[1,0]
	v_pk_mul_f32 v[68:69], v[20:21], 0.5 op_sel_hi:[1,0]
	v_pk_mul_f32 v[66:67], v[18:19], 0.5 op_sel_hi:[1,0]
	v_pk_mul_f32 v[64:65], v[8:9], 0.5 op_sel_hi:[1,0]
	v_pk_mul_f32 v[62:63], v[6:7], 0.5 op_sel_hi:[1,0]
	v_pk_mul_f32 v[60:61], v[4:5], 0.5 op_sel_hi:[1,0]
	v_pk_mul_f32 v[58:59], v[2:3], 0.5 op_sel_hi:[1,0]
	s_and_b64 vcc, exec, s[40:41]
	s_cbranch_vccz .LBB0_1522
